# GEMM main loops: the B-fragment LDS reads of the two 12-read load sections are issued one phase earlier (in the short load sections), counted vmcnt(8) two phases before publishes the staged data
# speedup vs baseline: 1.0009x; 1.0004x over previous
.LBB0_315:
	s_ashr_i32 s65, s64, 31
	s_lshl_b64 s[0:1], s[64:65], 20
	s_add_u32 s70, s20, s0
	s_addc_u32 s71, s21, s1
	s_and_b64 s[0:1], s[8:9], exec
	s_cselect_b32 s0, s71, s75
	s_cselect_b32 s1, s70, s74
	s_add_u32 s8, s76, 0x80080
	s_addc_u32 s9, s77, 0
	s_add_u32 s12, s74, 0x100
	v_mov_b32_e32 v0, 0
	s_addc_u32 s24, s75, 0
	s_mov_b32 s25, -2
	v_mov_b32_e32 v1, v0
	v_mov_b32_e32 v2, v0
	v_mov_b32_e32 v3, v0
	v_mov_b32_e32 v4, v0
	v_mov_b32_e32 v5, v0
	v_mov_b32_e32 v6, v0
	v_mov_b32_e32 v7, v0
	v_mov_b32_e32 v8, v0
	v_mov_b32_e32 v9, v0
	v_mov_b32_e32 v10, v0
	v_mov_b32_e32 v11, v0
	v_mov_b32_e32 v12, v0
	v_mov_b32_e32 v13, v0
	v_mov_b32_e32 v14, v0
	v_mov_b32_e32 v15, v0
	v_mov_b32_e32 v20, v0
	v_mov_b32_e32 v21, v0
	v_mov_b32_e32 v22, v0
	v_mov_b32_e32 v23, v0
	v_mov_b32_e32 v28, v0
	v_mov_b32_e32 v29, v0
	v_mov_b32_e32 v30, v0
	v_mov_b32_e32 v31, v0
	v_mov_b32_e32 v36, v0
	v_mov_b32_e32 v37, v0
	v_mov_b32_e32 v38, v0
	v_mov_b32_e32 v39, v0
	v_mov_b32_e32 v44, v0
	v_mov_b32_e32 v45, v0
	v_mov_b32_e32 v46, v0
	v_mov_b32_e32 v47, v0
	v_mov_b32_e32 v16, v0
	v_mov_b32_e32 v17, v0
	v_mov_b32_e32 v18, v0
	v_mov_b32_e32 v19, v0
	v_mov_b32_e32 v24, v0
	v_mov_b32_e32 v25, v0
	v_mov_b32_e32 v26, v0
	v_mov_b32_e32 v27, v0
	v_mov_b32_e32 v32, v0
	v_mov_b32_e32 v33, v0
	v_mov_b32_e32 v34, v0
	v_mov_b32_e32 v35, v0
	v_mov_b32_e32 v40, v0
	v_mov_b32_e32 v41, v0
	v_mov_b32_e32 v42, v0
	v_mov_b32_e32 v43, v0
	v_mov_b32_e32 v48, v0
	v_mov_b32_e32 v49, v0
	v_mov_b32_e32 v50, v0
	v_mov_b32_e32 v51, v0
	v_mov_b32_e32 v52, v0
	v_mov_b32_e32 v53, v0
	v_mov_b32_e32 v54, v0
	v_mov_b32_e32 v55, v0
	v_mov_b32_e32 v56, v0
	v_mov_b32_e32 v57, v0
	v_mov_b32_e32 v58, v0
	v_mov_b32_e32 v59, v0
	v_mov_b32_e32 v60, v0
	v_mov_b32_e32 v61, v0
	v_mov_b32_e32 v62, v0
	v_mov_b32_e32 v63, v0
	v_mov_b32_e32 v64, v0
	v_mov_b32_e32 v65, v0
	v_mov_b32_e32 v66, v0
	v_mov_b32_e32 v67, v0
	v_mov_b32_e32 v68, v0
	v_mov_b32_e32 v69, v0
	v_mov_b32_e32 v70, v0
	v_mov_b32_e32 v71, v0
	v_mov_b32_e32 v72, v0
	v_mov_b32_e32 v73, v0
	v_mov_b32_e32 v74, v0
	v_mov_b32_e32 v75, v0
	v_mov_b32_e32 v76, v0
	v_mov_b32_e32 v77, v0
	v_mov_b32_e32 v78, v0
	v_mov_b32_e32 v79, v0
	v_mov_b32_e32 v88, v0
	v_mov_b32_e32 v89, v0
	v_mov_b32_e32 v90, v0
	v_mov_b32_e32 v91, v0
	v_mov_b32_e32 v92, v0
	v_mov_b32_e32 v93, v0
	v_mov_b32_e32 v94, v0
	v_mov_b32_e32 v95, v0
	v_mov_b32_e32 v104, v0
	v_mov_b32_e32 v105, v0
	v_mov_b32_e32 v106, v0
	v_mov_b32_e32 v107, v0
	v_mov_b32_e32 v108, v0
	v_mov_b32_e32 v109, v0
	v_mov_b32_e32 v110, v0
	v_mov_b32_e32 v111, v0
	v_mov_b32_e32 v80, v0
	v_mov_b32_e32 v81, v0
	v_mov_b32_e32 v82, v0
	v_mov_b32_e32 v83, v0
	v_mov_b32_e32 v84, v0
	v_mov_b32_e32 v85, v0
	v_mov_b32_e32 v86, v0
	v_mov_b32_e32 v87, v0
	v_mov_b32_e32 v96, v0
	v_mov_b32_e32 v97, v0
	v_mov_b32_e32 v98, v0
	v_mov_b32_e32 v99, v0
	v_mov_b32_e32 v100, v0
	v_mov_b32_e32 v101, v0
	v_mov_b32_e32 v102, v0
	v_mov_b32_e32 v103, v0
	v_mov_b32_e32 v112, v0
	v_mov_b32_e32 v113, v0
	v_mov_b32_e32 v114, v0
	v_mov_b32_e32 v115, v0
	v_mov_b32_e32 v116, v0
	v_mov_b32_e32 v117, v0
	v_mov_b32_e32 v118, v0
	v_mov_b32_e32 v119, v0
	v_mov_b32_e32 v120, v0
	v_mov_b32_e32 v121, v0
	v_mov_b32_e32 v122, v0
	v_mov_b32_e32 v123, v0
	v_mov_b32_e32 v124, v0
	v_mov_b32_e32 v125, v0
	v_mov_b32_e32 v126, v0
	v_mov_b32_e32 v127, v0
	ds_read_b128 v[150:153], v167
	ds_read_b128 v[154:157], v167 offset:1024
	ds_read_b128 v[158:161], v167 offset:2048
	ds_read_b128 v[172:175], v167 offset:3072
.LBB0_316:
	s_add_u32 s4, s8, 0xfff80080
	s_addc_u32 s5, s9, -1
	s_cmp_eq_u32 s25, 28
	s_cselect_b32 s5, s69, s5
	s_cselect_b32 s4, s68, s4
	s_cselect_b32 s75, s0, s24
	s_cselect_b32 s74, s1, s12
	v_lshl_add_u64 v[162:163], s[8:9], 0, v[142:143]
	s_add_i32 m0, s11, 0xc000
	ds_read_b128 v[176:179], v168
	ds_read_b128 v[180:183], v168 offset:1024
	ds_read_b128 v[184:187], v168 offset:2048
	ds_read_b128 v[188:191], v168 offset:3072
	ds_read_b128 v[192:195], v168 offset:4096
	ds_read_b128 v[196:199], v168 offset:5120
	ds_read_b128 v[200:203], v168 offset:6144
	ds_read_b128 v[204:207], v168 offset:7168
	global_load_lds_dwordx4 v[162:163], off
	v_lshl_add_u64 v[162:163], s[8:9], 0, v[144:145]
	s_add_i32 m0, s11, 0xe000
	s_nop 0
	global_load_lds_dwordx4 v[162:163], off
	s_waitcnt lgkmcnt(8)
	s_barrier
	s_waitcnt lgkmcnt(0)
	s_waitcnt lgkmcnt(0)
	v_mfma_f32_16x16x32_bf16 v[124:127], v[150:153], v[176:179], v[124:127]
	v_mfma_f32_16x16x32_bf16 v[120:123], v[158:161], v[176:179], v[120:123]
	v_mfma_f32_16x16x32_bf16 v[116:119], v[150:153], v[184:187], v[116:119]
	v_mfma_f32_16x16x32_bf16 v[112:115], v[158:161], v[184:187], v[112:115]
	v_mfma_f32_16x16x32_bf16 v[100:103], v[150:153], v[192:195], v[100:103]
	v_mfma_f32_16x16x32_bf16 v[96:99], v[158:161], v[192:195], v[96:99]
	v_mfma_f32_16x16x32_bf16 v[84:87], v[150:153], v[200:203], v[84:87]
	v_mfma_f32_16x16x32_bf16 v[80:83], v[158:161], v[200:203], v[80:83]
	v_mfma_f32_16x16x32_bf16 v[124:127], v[154:157], v[180:183], v[124:127]
	v_mfma_f32_16x16x32_bf16 v[120:123], v[172:175], v[180:183], v[120:123]
	v_mfma_f32_16x16x32_bf16 v[116:119], v[154:157], v[188:191], v[116:119]
	v_mfma_f32_16x16x32_bf16 v[112:115], v[172:175], v[188:191], v[112:115]
	v_mfma_f32_16x16x32_bf16 v[100:103], v[154:157], v[196:199], v[100:103]
	v_mfma_f32_16x16x32_bf16 v[96:99], v[172:175], v[196:199], v[96:99]
	v_mfma_f32_16x16x32_bf16 v[84:87], v[154:157], v[204:207], v[84:87]
	v_mfma_f32_16x16x32_bf16 v[80:83], v[172:175], v[204:207], v[80:83]
	s_barrier
	s_add_i32 s33, s80, s28
	v_lshl_add_u64 v[162:163], s[74:75], 0, v[132:133]
	s_mov_b32 m0, s33
	ds_read_b128 v[208:211], v169
	ds_read_b128 v[212:215], v169 offset:1024
	ds_read_b128 v[218:221], v169 offset:2048
	ds_read_b128 v[222:225], v169 offset:3072
	global_load_lds_dwordx4 v[162:163], off
	v_lshl_add_u64 v[216:217], s[74:75], 0, v[136:137]
	s_add_i32 m0, s33, 0x2000
	s_nop 0
	global_load_lds_dwordx4 v[216:217], off
	s_barrier
	s_waitcnt lgkmcnt(0)
	s_waitcnt lgkmcnt(0)
	v_mfma_f32_16x16x32_bf16 v[108:111], v[208:211], v[176:179], v[108:111]
	v_mfma_f32_16x16x32_bf16 v[104:107], v[218:221], v[176:179], v[104:107]
	v_mfma_f32_16x16x32_bf16 v[92:95], v[208:211], v[184:187], v[92:95]
	v_mfma_f32_16x16x32_bf16 v[88:91], v[218:221], v[184:187], v[88:91]
	v_mfma_f32_16x16x32_bf16 v[76:79], v[208:211], v[192:195], v[76:79]
	v_mfma_f32_16x16x32_bf16 v[72:75], v[218:221], v[192:195], v[72:75]
	v_mfma_f32_16x16x32_bf16 v[68:71], v[208:211], v[200:203], v[68:71]
	v_mfma_f32_16x16x32_bf16 v[64:67], v[218:221], v[200:203], v[64:67]
	v_mfma_f32_16x16x32_bf16 v[108:111], v[212:215], v[180:183], v[108:111]
	v_mfma_f32_16x16x32_bf16 v[104:107], v[222:225], v[180:183], v[104:107]
	v_mfma_f32_16x16x32_bf16 v[92:95], v[212:215], v[188:191], v[92:95]
	v_mfma_f32_16x16x32_bf16 v[88:91], v[222:225], v[188:191], v[88:91]
	v_mfma_f32_16x16x32_bf16 v[76:79], v[212:215], v[196:199], v[76:79]
	v_mfma_f32_16x16x32_bf16 v[72:75], v[222:225], v[196:199], v[72:75]
	v_mfma_f32_16x16x32_bf16 v[68:71], v[212:215], v[204:207], v[68:71]
	v_mfma_f32_16x16x32_bf16 v[64:67], v[222:225], v[204:207], v[64:67]
	s_mov_b32 m0, s11
	v_lshl_add_u64 v[226:227], s[4:5], 0, v[130:131]
	s_barrier
	s_waitcnt vmcnt(8)
	ds_read_b128 v[176:179], v168 offset:16384
	ds_read_b128 v[180:183], v168 offset:17408
	ds_read_b128 v[184:187], v168 offset:18432
	ds_read_b128 v[188:191], v168 offset:19456
	ds_read_b128 v[192:195], v168 offset:20480
	ds_read_b128 v[196:199], v168 offset:21504
	ds_read_b128 v[200:203], v168 offset:22528
	ds_read_b128 v[204:207], v168 offset:23552
	global_load_lds_dwordx4 v[226:227], off
	v_lshl_add_u64 v[228:229], s[4:5], 0, v[134:135]
	s_mov_b32 m0, s29
	s_nop 0
	global_load_lds_dwordx4 v[228:229], off
	s_barrier
	s_waitcnt lgkmcnt(0)
	s_waitcnt lgkmcnt(0)
	v_mfma_f32_16x16x32_bf16 v[60:63], v[150:153], v[176:179], v[60:63]
	v_mfma_f32_16x16x32_bf16 v[56:59], v[158:161], v[176:179], v[56:59]
	v_mfma_f32_16x16x32_bf16 v[52:55], v[150:153], v[184:187], v[52:55]
	v_mfma_f32_16x16x32_bf16 v[48:51], v[158:161], v[184:187], v[48:51]
	v_mfma_f32_16x16x32_bf16 v[40:43], v[150:153], v[192:195], v[40:43]
	v_mfma_f32_16x16x32_bf16 v[32:35], v[158:161], v[192:195], v[32:35]
	v_mfma_f32_16x16x32_bf16 v[24:27], v[150:153], v[200:203], v[24:27]
	v_mfma_f32_16x16x32_bf16 v[16:19], v[158:161], v[200:203], v[16:19]
	v_mfma_f32_16x16x32_bf16 v[60:63], v[154:157], v[180:183], v[60:63]
	v_mfma_f32_16x16x32_bf16 v[56:59], v[172:175], v[180:183], v[56:59]
	v_mfma_f32_16x16x32_bf16 v[52:55], v[154:157], v[188:191], v[52:55]
	v_mfma_f32_16x16x32_bf16 v[48:51], v[172:175], v[188:191], v[48:51]
	v_mfma_f32_16x16x32_bf16 v[40:43], v[154:157], v[196:199], v[40:43]
	v_mfma_f32_16x16x32_bf16 v[32:35], v[172:175], v[196:199], v[32:35]
	v_mfma_f32_16x16x32_bf16 v[24:27], v[154:157], v[204:207], v[24:27]
	v_mfma_f32_16x16x32_bf16 v[16:19], v[172:175], v[204:207], v[16:19]
	s_barrier
	s_add_u32 s76, s74, 0x80000
	s_addc_u32 s77, s75, 0
	s_add_i32 s33, s81, s28
	v_lshl_add_u64 v[150:151], s[76:77], 0, v[132:133]
	s_mov_b32 m0, s33
	s_nop 0
	global_load_lds_dwordx4 v[150:151], off
	v_lshl_add_u64 v[150:151], s[76:77], 0, v[136:137]
	s_add_i32 m0, s33, 0x2000
	s_nop 0
	global_load_lds_dwordx4 v[150:151], off
	v_add_u32_e32 v138, 0x18000, v164
	ds_read_b128 v[150:153], v138
	ds_read_b128 v[154:157], v138 offset:1024
	ds_read_b128 v[158:161], v138 offset:2048
	ds_read_b128 v[172:175], v138 offset:3072
	s_waitcnt vmcnt(6)
	s_barrier
	v_mfma_f32_16x16x32_bf16 v[44:47], v[208:211], v[176:179], v[44:47]
	v_mfma_f32_16x16x32_bf16 v[36:39], v[218:221], v[176:179], v[36:39]
	v_mfma_f32_16x16x32_bf16 v[28:31], v[208:211], v[184:187], v[28:31]
	v_mfma_f32_16x16x32_bf16 v[20:23], v[218:221], v[184:187], v[20:23]
	v_mfma_f32_16x16x32_bf16 v[12:15], v[208:211], v[192:195], v[12:15]
	v_mfma_f32_16x16x32_bf16 v[8:11], v[218:221], v[192:195], v[8:11]
	v_mfma_f32_16x16x32_bf16 v[4:7], v[208:211], v[200:203], v[4:7]
	v_mfma_f32_16x16x32_bf16 v[0:3], v[218:221], v[200:203], v[0:3]
	v_mfma_f32_16x16x32_bf16 v[44:47], v[212:215], v[180:183], v[44:47]
	v_mfma_f32_16x16x32_bf16 v[36:39], v[222:225], v[180:183], v[36:39]
	v_mfma_f32_16x16x32_bf16 v[28:31], v[212:215], v[188:191], v[28:31]
	v_mfma_f32_16x16x32_bf16 v[20:23], v[222:225], v[188:191], v[20:23]
	v_mfma_f32_16x16x32_bf16 v[12:15], v[212:215], v[196:199], v[12:15]
	v_mfma_f32_16x16x32_bf16 v[8:11], v[222:225], v[196:199], v[8:11]
	v_mfma_f32_16x16x32_bf16 v[4:7], v[212:215], v[204:207], v[4:7]
	v_mfma_f32_16x16x32_bf16 v[0:3], v[222:225], v[204:207], v[0:3]
	s_add_i32 s33, 0, 0x18000
	s_barrier
	s_add_u32 s4, s4, 0x80000
	s_addc_u32 s5, s5, 0
	s_mov_b32 m0, s36
	v_lshl_add_u64 v[208:209], s[4:5], 0, v[130:131]
	ds_read_b128 v[176:179], v168 offset:32768
	ds_read_b128 v[180:183], v168 offset:33792
	ds_read_b128 v[184:187], v168 offset:34816
	ds_read_b128 v[188:191], v168 offset:35840
	ds_read_b128 v[192:195], v168 offset:36864
	ds_read_b128 v[196:199], v168 offset:37888
	ds_read_b128 v[200:203], v168 offset:38912
	ds_read_b128 v[204:207], v168 offset:39936
	global_load_lds_dwordx4 v[208:209], off
	v_lshl_add_u64 v[208:209], s[4:5], 0, v[134:135]
	s_mov_b32 m0, s37
	s_nop 0
	global_load_lds_dwordx4 v[208:209], off
	s_waitcnt lgkmcnt(8)
	s_barrier
	s_waitcnt lgkmcnt(0)
	s_waitcnt lgkmcnt(0)
	v_mfma_f32_16x16x32_bf16 v[124:127], v[150:153], v[176:179], v[124:127]
	v_mfma_f32_16x16x32_bf16 v[120:123], v[158:161], v[176:179], v[120:123]
	v_mfma_f32_16x16x32_bf16 v[116:119], v[150:153], v[184:187], v[116:119]
	v_mfma_f32_16x16x32_bf16 v[112:115], v[158:161], v[184:187], v[112:115]
	v_mfma_f32_16x16x32_bf16 v[100:103], v[150:153], v[192:195], v[100:103]
	v_mfma_f32_16x16x32_bf16 v[96:99], v[158:161], v[192:195], v[96:99]
	v_mfma_f32_16x16x32_bf16 v[84:87], v[150:153], v[200:203], v[84:87]
	v_mfma_f32_16x16x32_bf16 v[80:83], v[158:161], v[200:203], v[80:83]
	v_mfma_f32_16x16x32_bf16 v[124:127], v[154:157], v[180:183], v[124:127]
	v_mfma_f32_16x16x32_bf16 v[120:123], v[172:175], v[180:183], v[120:123]
	v_mfma_f32_16x16x32_bf16 v[116:119], v[154:157], v[188:191], v[116:119]
	v_mfma_f32_16x16x32_bf16 v[112:115], v[172:175], v[188:191], v[112:115]
	v_mfma_f32_16x16x32_bf16 v[100:103], v[154:157], v[196:199], v[100:103]
	v_mfma_f32_16x16x32_bf16 v[96:99], v[172:175], v[196:199], v[96:99]
	v_mfma_f32_16x16x32_bf16 v[84:87], v[154:157], v[204:207], v[84:87]
	v_mfma_f32_16x16x32_bf16 v[80:83], v[172:175], v[204:207], v[80:83]
	s_barrier
	s_add_i32 s65, 0, 0x1c000
	s_add_i32 s4, s33, s28
	v_add_u32_e32 v138, s65, v164
	v_lshl_add_u64 v[162:163], v[162:163], 0, s[14:15]
	s_mov_b32 m0, s4
	ds_read_b128 v[208:211], v138
	ds_read_b128 v[212:215], v138 offset:1024
	ds_read_b128 v[218:221], v138 offset:2048
	ds_read_b128 v[222:225], v138 offset:3072
	global_load_lds_dwordx4 v[162:163], off
	v_lshl_add_u64 v[162:163], v[216:217], 0, s[14:15]
	s_add_i32 m0, s4, 0x2000
	s_nop 0
	global_load_lds_dwordx4 v[162:163], off
	s_barrier
	s_waitcnt lgkmcnt(0)
	s_waitcnt lgkmcnt(0)
	v_mfma_f32_16x16x32_bf16 v[108:111], v[208:211], v[176:179], v[108:111]
	v_mfma_f32_16x16x32_bf16 v[104:107], v[218:221], v[176:179], v[104:107]
	v_mfma_f32_16x16x32_bf16 v[92:95], v[208:211], v[184:187], v[92:95]
	v_mfma_f32_16x16x32_bf16 v[88:91], v[218:221], v[184:187], v[88:91]
	v_mfma_f32_16x16x32_bf16 v[76:79], v[208:211], v[192:195], v[76:79]
	v_mfma_f32_16x16x32_bf16 v[72:75], v[218:221], v[192:195], v[72:75]
	v_mfma_f32_16x16x32_bf16 v[68:71], v[208:211], v[200:203], v[68:71]
	v_mfma_f32_16x16x32_bf16 v[64:67], v[218:221], v[200:203], v[64:67]
	v_mfma_f32_16x16x32_bf16 v[108:111], v[212:215], v[180:183], v[108:111]
	v_mfma_f32_16x16x32_bf16 v[104:107], v[222:225], v[180:183], v[104:107]
	v_mfma_f32_16x16x32_bf16 v[92:95], v[212:215], v[188:191], v[92:95]
	v_mfma_f32_16x16x32_bf16 v[88:91], v[222:225], v[188:191], v[88:91]
	v_mfma_f32_16x16x32_bf16 v[76:79], v[212:215], v[196:199], v[76:79]
	v_mfma_f32_16x16x32_bf16 v[72:75], v[222:225], v[196:199], v[72:75]
	v_mfma_f32_16x16x32_bf16 v[68:71], v[212:215], v[204:207], v[68:71]
	v_mfma_f32_16x16x32_bf16 v[64:67], v[222:225], v[204:207], v[64:67]
	s_mov_b32 m0, s73
	v_lshl_add_u64 v[162:163], v[226:227], 0, s[14:15]
	s_barrier
	s_waitcnt vmcnt(8)
	ds_read_b128 v[176:179], v168 offset:49152
	ds_read_b128 v[180:183], v168 offset:50176
	ds_read_b128 v[184:187], v168 offset:51200
	ds_read_b128 v[188:191], v168 offset:52224
	ds_read_b128 v[192:195], v168 offset:53248
	ds_read_b128 v[196:199], v168 offset:54272
	ds_read_b128 v[200:203], v168 offset:55296
	ds_read_b128 v[204:207], v168 offset:56320
	global_load_lds_dwordx4 v[162:163], off
	v_lshl_add_u64 v[162:163], v[228:229], 0, s[14:15]
	s_mov_b32 m0, s78
	s_nop 0
	global_load_lds_dwordx4 v[162:163], off
	s_barrier
	s_waitcnt lgkmcnt(0)
	s_waitcnt lgkmcnt(0)
	v_mfma_f32_16x16x32_bf16 v[60:63], v[150:153], v[176:179], v[60:63]
	v_mfma_f32_16x16x32_bf16 v[56:59], v[158:161], v[176:179], v[56:59]
	v_mfma_f32_16x16x32_bf16 v[52:55], v[150:153], v[184:187], v[52:55]
	v_mfma_f32_16x16x32_bf16 v[48:51], v[158:161], v[184:187], v[48:51]
	v_mfma_f32_16x16x32_bf16 v[40:43], v[150:153], v[192:195], v[40:43]
	v_mfma_f32_16x16x32_bf16 v[32:35], v[158:161], v[192:195], v[32:35]
	v_mfma_f32_16x16x32_bf16 v[24:27], v[150:153], v[200:203], v[24:27]
	v_mfma_f32_16x16x32_bf16 v[16:19], v[158:161], v[200:203], v[16:19]
	v_mfma_f32_16x16x32_bf16 v[60:63], v[154:157], v[180:183], v[60:63]
	v_mfma_f32_16x16x32_bf16 v[56:59], v[172:175], v[180:183], v[56:59]
	v_mfma_f32_16x16x32_bf16 v[52:55], v[154:157], v[188:191], v[52:55]
	v_mfma_f32_16x16x32_bf16 v[48:51], v[172:175], v[188:191], v[48:51]
	v_mfma_f32_16x16x32_bf16 v[40:43], v[154:157], v[196:199], v[40:43]
	v_mfma_f32_16x16x32_bf16 v[32:35], v[172:175], v[196:199], v[32:35]
	v_mfma_f32_16x16x32_bf16 v[24:27], v[154:157], v[204:207], v[24:27]
	v_mfma_f32_16x16x32_bf16 v[16:19], v[172:175], v[204:207], v[16:19]
	s_barrier
	s_add_u32 s4, s74, 0x80080
	s_addc_u32 s5, s75, 0
	s_add_i32 s33, s65, s28
	v_lshl_add_u64 v[150:151], s[4:5], 0, v[132:133]
	s_mov_b32 m0, s33
	s_nop 0
	global_load_lds_dwordx4 v[150:151], off
	v_lshl_add_u64 v[150:151], s[4:5], 0, v[136:137]
	s_add_i32 m0, s33, 0x2000
	s_nop 0
	global_load_lds_dwordx4 v[150:151], off
	ds_read_b128 v[150:153], v167
	ds_read_b128 v[154:157], v167 offset:1024
	ds_read_b128 v[158:161], v167 offset:2048
	ds_read_b128 v[172:175], v167 offset:3072
	s_waitcnt vmcnt(6)
	s_barrier
	v_mfma_f32_16x16x32_bf16 v[44:47], v[208:211], v[176:179], v[44:47]
	v_mfma_f32_16x16x32_bf16 v[36:39], v[218:221], v[176:179], v[36:39]
	v_mfma_f32_16x16x32_bf16 v[28:31], v[208:211], v[184:187], v[28:31]
	v_mfma_f32_16x16x32_bf16 v[20:23], v[218:221], v[184:187], v[20:23]
	v_mfma_f32_16x16x32_bf16 v[12:15], v[208:211], v[192:195], v[12:15]
	v_mfma_f32_16x16x32_bf16 v[8:11], v[218:221], v[192:195], v[8:11]
	v_mfma_f32_16x16x32_bf16 v[4:7], v[208:211], v[200:203], v[4:7]
	v_mfma_f32_16x16x32_bf16 v[0:3], v[218:221], v[200:203], v[0:3]
	v_mfma_f32_16x16x32_bf16 v[44:47], v[212:215], v[180:183], v[44:47]
	v_mfma_f32_16x16x32_bf16 v[36:39], v[222:225], v[180:183], v[36:39]
	v_mfma_f32_16x16x32_bf16 v[28:31], v[212:215], v[188:191], v[28:31]
	v_mfma_f32_16x16x32_bf16 v[20:23], v[222:225], v[188:191], v[20:23]
	v_mfma_f32_16x16x32_bf16 v[12:15], v[212:215], v[196:199], v[12:15]
	v_mfma_f32_16x16x32_bf16 v[8:11], v[222:225], v[196:199], v[8:11]
	v_mfma_f32_16x16x32_bf16 v[4:7], v[212:215], v[204:207], v[4:7]
	v_mfma_f32_16x16x32_bf16 v[0:3], v[222:225], v[204:207], v[0:3]
	s_add_i32 s25, s25, 2
	s_add_u32 s8, s8, 0x100
	s_addc_u32 s9, s9, 0
	s_add_u32 s12, s12, 0x100
	s_addc_u32 s24, s24, 0
	s_cmp_gt_u32 s25, 29
	s_barrier
	s_cbranch_scc0 .LBB0_316
	s_and_b32 s0, s10, -8
	v_lshl_add_u32 v150, s72, 8, v129
	s_cmp_lg_u32 s0, 8
	s_mov_b64 s[0:1], -1
	s_cbranch_scc0 .LBB0_435
	s_cmp_gt_i32 s10, 23
	s_cbranch_scc0 .LBB0_432
	s_cmp_lt_i32 s10, 26
	s_cbranch_scc1 .LBB0_323
	s_cmp_eq_u32 s10, 26
	v_mov_b32_e32 v161, v123
	v_mov_b32_e32 v160, v122
	v_mov_b32_e32 v157, v121
	v_mov_b32_e32 v156, v120
	v_mov_b32_e32 v163, v127
	v_mov_b32_e32 v162, v126
	v_mov_b32_e32 v159, v125
	v_mov_b32_e32 v158, v124
	s_cbranch_scc0 .LBB0_322
	v_mul_f32_e32 v138, 0xbfb8aa3b, v124
	v_exp_f32_e32 v138, v138
	v_mul_f32_e32 v151, 0xbfb8aa3b, v120
	v_exp_f32_e32 v151, v151
	v_mul_f32_e32 v152, 0xbfb8aa3b, v121
	v_add_f32_e32 v138, 1.0, v138
	v_rcp_f32_e32 v158, v138
	v_mul_f32_e32 v138, 0xbfb8aa3b, v125
	v_exp_f32_e32 v138, v138
	v_exp_f32_e32 v152, v152
	v_add_f32_e32 v151, 1.0, v151
	v_rcp_f32_e32 v156, v151
	v_add_f32_e32 v138, 1.0, v138
	v_mul_f32_e32 v151, 0xbfb8aa3b, v126
	v_rcp_f32_e32 v159, v138
	v_add_f32_e32 v138, 1.0, v152
	v_exp_f32_e32 v151, v151
	v_mul_f32_e32 v152, 0xbfb8aa3b, v122
	v_exp_f32_e32 v152, v152
	v_rcp_f32_e32 v157, v138
	v_add_f32_e32 v138, 1.0, v151
	v_mul_f32_e32 v151, 0xbfb8aa3b, v127
	v_rcp_f32_e32 v162, v138
	v_add_f32_e32 v138, 1.0, v152
	v_exp_f32_e32 v151, v151
	v_mul_f32_e32 v152, 0xbfb8aa3b, v123
	v_exp_f32_e32 v152, v152
	v_rcp_f32_e32 v160, v138
	v_add_f32_e32 v138, 1.0, v151
	v_rcp_f32_e32 v163, v138
	v_add_f32_e32 v138, 1.0, v152
	v_rcp_f32_e32 v161, v138

.LBB0_849:
	s_ashr_i32 s67, s66, 31
	v_cmp_lt_i64_e32 vcc, s[0:1], v[136:137]
	s_lshl_b64 s[0:1], s[66:67], 20
	s_add_u32 s68, s8, s0
	s_addc_u32 s69, s9, s1
	s_and_b64 s[0:1], vcc, exec
	s_cselect_b32 s0, s69, s75
	s_cselect_b32 s1, s68, s74
	s_ashr_i32 s61, s60, 31
	s_lshl_b64 s[4:5], s[60:61], 20
	s_add_u32 s70, s64, s4
	s_addc_u32 s71, s65, s5
	s_and_b64 s[4:5], vcc, exec
	s_cselect_b32 s46, s71, s51
	s_cselect_b32 s47, s70, s50
	s_add_u32 s61, s50, 0x100
	v_mov_b32_e32 v0, 0
	s_addc_u32 s67, s51, 0
	s_mov_b32 s73, -2
	v_mov_b32_e32 v1, v0
	v_mov_b32_e32 v2, v0
	v_mov_b32_e32 v3, v0
	v_mov_b32_e32 v20, v0
	v_mov_b32_e32 v21, v0
	v_mov_b32_e32 v22, v0
	v_mov_b32_e32 v23, v0
	v_mov_b32_e32 v4, v0
	v_mov_b32_e32 v5, v0
	v_mov_b32_e32 v6, v0
	v_mov_b32_e32 v7, v0
	v_mov_b32_e32 v28, v0
	v_mov_b32_e32 v29, v0
	v_mov_b32_e32 v30, v0
	v_mov_b32_e32 v31, v0
	v_mov_b32_e32 v8, v0
	v_mov_b32_e32 v9, v0
	v_mov_b32_e32 v10, v0
	v_mov_b32_e32 v11, v0
	v_mov_b32_e32 v36, v0
	v_mov_b32_e32 v37, v0
	v_mov_b32_e32 v38, v0
	v_mov_b32_e32 v39, v0
	v_mov_b32_e32 v12, v0
	v_mov_b32_e32 v13, v0
	v_mov_b32_e32 v14, v0
	v_mov_b32_e32 v15, v0
	v_mov_b32_e32 v44, v0
	v_mov_b32_e32 v45, v0
	v_mov_b32_e32 v46, v0
	v_mov_b32_e32 v47, v0
	v_mov_b32_e32 v56, v0
	v_mov_b32_e32 v57, v0
	v_mov_b32_e32 v58, v0
	v_mov_b32_e32 v59, v0
	v_mov_b32_e32 v84, v0
	v_mov_b32_e32 v85, v0
	v_mov_b32_e32 v86, v0
	v_mov_b32_e32 v87, v0
	v_mov_b32_e32 v64, v0
	v_mov_b32_e32 v65, v0
	v_mov_b32_e32 v66, v0
	v_mov_b32_e32 v67, v0
	v_mov_b32_e32 v92, v0
	v_mov_b32_e32 v93, v0
	v_mov_b32_e32 v94, v0
	v_mov_b32_e32 v95, v0
	v_mov_b32_e32 v72, v0
	v_mov_b32_e32 v73, v0
	v_mov_b32_e32 v74, v0
	v_mov_b32_e32 v75, v0
	v_mov_b32_e32 v104, v0
	v_mov_b32_e32 v105, v0
	v_mov_b32_e32 v106, v0
	v_mov_b32_e32 v107, v0
	v_mov_b32_e32 v76, v0
	v_mov_b32_e32 v77, v0
	v_mov_b32_e32 v78, v0
	v_mov_b32_e32 v79, v0
	v_mov_b32_e32 v108, v0
	v_mov_b32_e32 v109, v0
	v_mov_b32_e32 v110, v0
	v_mov_b32_e32 v111, v0
	v_mov_b32_e32 v16, v0
	v_mov_b32_e32 v17, v0
	v_mov_b32_e32 v18, v0
	v_mov_b32_e32 v19, v0
	v_mov_b32_e32 v48, v0
	v_mov_b32_e32 v49, v0
	v_mov_b32_e32 v50, v0
	v_mov_b32_e32 v51, v0
	v_mov_b32_e32 v24, v0
	v_mov_b32_e32 v25, v0
	v_mov_b32_e32 v26, v0
	v_mov_b32_e32 v27, v0
	v_mov_b32_e32 v52, v0
	v_mov_b32_e32 v53, v0
	v_mov_b32_e32 v54, v0
	v_mov_b32_e32 v55, v0
	v_mov_b32_e32 v32, v0
	v_mov_b32_e32 v33, v0
	v_mov_b32_e32 v34, v0
	v_mov_b32_e32 v35, v0
	v_mov_b32_e32 v60, v0
	v_mov_b32_e32 v61, v0
	v_mov_b32_e32 v62, v0
	v_mov_b32_e32 v63, v0
	v_mov_b32_e32 v40, v0
	v_mov_b32_e32 v41, v0
	v_mov_b32_e32 v42, v0
	v_mov_b32_e32 v43, v0
	v_mov_b32_e32 v68, v0
	v_mov_b32_e32 v69, v0
	v_mov_b32_e32 v70, v0
	v_mov_b32_e32 v71, v0
	v_mov_b32_e32 v80, v0
	v_mov_b32_e32 v81, v0
	v_mov_b32_e32 v82, v0
	v_mov_b32_e32 v83, v0
	v_mov_b32_e32 v112, v0
	v_mov_b32_e32 v113, v0
	v_mov_b32_e32 v114, v0
	v_mov_b32_e32 v115, v0
	v_mov_b32_e32 v88, v0
	v_mov_b32_e32 v89, v0
	v_mov_b32_e32 v90, v0
	v_mov_b32_e32 v91, v0
	v_mov_b32_e32 v116, v0
	v_mov_b32_e32 v117, v0
	v_mov_b32_e32 v118, v0
	v_mov_b32_e32 v119, v0
	v_mov_b32_e32 v96, v0
	v_mov_b32_e32 v97, v0
	v_mov_b32_e32 v98, v0
	v_mov_b32_e32 v99, v0
	v_mov_b32_e32 v120, v0
	v_mov_b32_e32 v121, v0
	v_mov_b32_e32 v122, v0
	v_mov_b32_e32 v123, v0
	v_mov_b32_e32 v100, v0
	v_mov_b32_e32 v101, v0
	v_mov_b32_e32 v102, v0
	v_mov_b32_e32 v103, v0
	v_mov_b32_e32 v124, v0
	v_mov_b32_e32 v125, v0
	v_mov_b32_e32 v126, v0
	v_mov_b32_e32 v127, v0
	ds_read_b128 v[140:143], v147
	ds_read_b128 v[150:153], v147 offset:1024
	ds_read_b128 v[154:157], v147 offset:2048
	ds_read_b128 v[158:161], v147 offset:3072
.LBB0_850:
	s_add_u32 s76, s74, 0x100
	s_addc_u32 s77, s75, 0
	s_cmp_eq_u32 s73, 28
	s_cselect_b32 s5, s0, s77
	s_cselect_b32 s4, s1, s76
	s_cselect_b32 s51, s46, s67
	s_cselect_b32 s50, s47, s61
	v_lshl_add_u64 v[194:195], s[74:75], 0, v[132:133]
	s_add_i32 m0, s23, 0xc000
	ds_read_b128 v[162:165], v148
	ds_read_b128 v[166:169], v148 offset:1024
	ds_read_b128 v[170:173], v148 offset:2048
	ds_read_b128 v[174:177], v148 offset:3072
	ds_read_b128 v[178:181], v148 offset:4096
	ds_read_b128 v[182:185], v148 offset:5120
	ds_read_b128 v[186:189], v148 offset:6144
	ds_read_b128 v[190:193], v148 offset:7168
	global_load_lds_dwordx4 v[194:195], off
	v_lshl_add_u64 v[194:195], s[74:75], 0, v[134:135]
	s_add_i32 m0, s23, 0xe000
	s_nop 0
	global_load_lds_dwordx4 v[194:195], off
	s_waitcnt lgkmcnt(8)
	s_barrier
	s_waitcnt lgkmcnt(0)
	s_waitcnt lgkmcnt(0)
	v_mfma_f32_16x16x32_bf16 v[124:127], v[140:143], v[162:165], v[124:127]
	v_mfma_f32_16x16x32_bf16 v[100:103], v[154:157], v[162:165], v[100:103]
	v_mfma_f32_16x16x32_bf16 v[120:123], v[140:143], v[170:173], v[120:123]
	v_mfma_f32_16x16x32_bf16 v[96:99], v[154:157], v[170:173], v[96:99]
	v_mfma_f32_16x16x32_bf16 v[116:119], v[140:143], v[178:181], v[116:119]
	v_mfma_f32_16x16x32_bf16 v[88:91], v[154:157], v[178:181], v[88:91]
	v_mfma_f32_16x16x32_bf16 v[112:115], v[140:143], v[186:189], v[112:115]
	v_mfma_f32_16x16x32_bf16 v[80:83], v[154:157], v[186:189], v[80:83]
	v_mfma_f32_16x16x32_bf16 v[124:127], v[150:153], v[166:169], v[124:127]
	v_mfma_f32_16x16x32_bf16 v[100:103], v[158:161], v[166:169], v[100:103]
	v_mfma_f32_16x16x32_bf16 v[120:123], v[150:153], v[174:177], v[120:123]
	v_mfma_f32_16x16x32_bf16 v[96:99], v[158:161], v[174:177], v[96:99]
	v_mfma_f32_16x16x32_bf16 v[116:119], v[150:153], v[182:185], v[116:119]
	v_mfma_f32_16x16x32_bf16 v[88:91], v[158:161], v[182:185], v[88:91]
	v_mfma_f32_16x16x32_bf16 v[112:115], v[150:153], v[190:193], v[112:115]
	v_mfma_f32_16x16x32_bf16 v[80:83], v[158:161], v[190:193], v[80:83]
	s_barrier
	s_add_i32 s42, s37, s21
	v_lshl_add_u64 v[210:211], s[50:51], 0, v[130:131]
	s_mov_b32 m0, s42
	ds_read_b128 v[194:197], v149
	ds_read_b128 v[198:201], v149 offset:1024
	ds_read_b128 v[202:205], v149 offset:2048
	ds_read_b128 v[206:209], v149 offset:3072
	global_load_lds_dwordx4 v[210:211], off
	v_lshl_add_u64 v[212:213], s[50:51], 0, v[128:129]
	s_add_i32 m0, s42, 0x2000
	s_nop 0
	global_load_lds_dwordx4 v[212:213], off
	s_barrier
	s_waitcnt lgkmcnt(0)
	s_waitcnt lgkmcnt(0)
	v_mfma_f32_16x16x32_bf16 v[68:71], v[194:197], v[162:165], v[68:71]
	v_mfma_f32_16x16x32_bf16 v[40:43], v[202:205], v[162:165], v[40:43]
	v_mfma_f32_16x16x32_bf16 v[60:63], v[194:197], v[170:173], v[60:63]
	v_mfma_f32_16x16x32_bf16 v[32:35], v[202:205], v[170:173], v[32:35]
	v_mfma_f32_16x16x32_bf16 v[52:55], v[194:197], v[178:181], v[52:55]
	v_mfma_f32_16x16x32_bf16 v[24:27], v[202:205], v[178:181], v[24:27]
	v_mfma_f32_16x16x32_bf16 v[48:51], v[194:197], v[186:189], v[48:51]
	v_mfma_f32_16x16x32_bf16 v[16:19], v[202:205], v[186:189], v[16:19]
	v_mfma_f32_16x16x32_bf16 v[68:71], v[198:201], v[166:169], v[68:71]
	v_mfma_f32_16x16x32_bf16 v[40:43], v[206:209], v[166:169], v[40:43]
	v_mfma_f32_16x16x32_bf16 v[60:63], v[198:201], v[174:177], v[60:63]
	v_mfma_f32_16x16x32_bf16 v[32:35], v[206:209], v[174:177], v[32:35]
	v_mfma_f32_16x16x32_bf16 v[52:55], v[198:201], v[182:185], v[52:55]
	v_mfma_f32_16x16x32_bf16 v[24:27], v[206:209], v[182:185], v[24:27]
	v_mfma_f32_16x16x32_bf16 v[48:51], v[198:201], v[190:193], v[48:51]
	v_mfma_f32_16x16x32_bf16 v[16:19], v[206:209], v[190:193], v[16:19]
	s_mov_b32 m0, s23
	v_lshl_add_u64 v[214:215], s[4:5], 0, v[130:131]
	s_barrier
	s_waitcnt vmcnt(8)
	ds_read_b128 v[162:165], v148 offset:16384
	ds_read_b128 v[166:169], v148 offset:17408
	ds_read_b128 v[170:173], v148 offset:18432
	ds_read_b128 v[174:177], v148 offset:19456
	ds_read_b128 v[178:181], v148 offset:20480
	ds_read_b128 v[182:185], v148 offset:21504
	ds_read_b128 v[186:189], v148 offset:22528
	ds_read_b128 v[190:193], v148 offset:23552
	global_load_lds_dwordx4 v[214:215], off
	v_lshl_add_u64 v[216:217], s[4:5], 0, v[128:129]
	s_mov_b32 m0, s24
	s_nop 0
	global_load_lds_dwordx4 v[216:217], off
	s_barrier
	s_waitcnt lgkmcnt(0)
	s_waitcnt lgkmcnt(0)
	v_mfma_f32_16x16x32_bf16 v[108:111], v[140:143], v[162:165], v[108:111]
	v_mfma_f32_16x16x32_bf16 v[76:79], v[154:157], v[162:165], v[76:79]
	v_mfma_f32_16x16x32_bf16 v[104:107], v[140:143], v[170:173], v[104:107]
	v_mfma_f32_16x16x32_bf16 v[72:75], v[154:157], v[170:173], v[72:75]
	v_mfma_f32_16x16x32_bf16 v[92:95], v[140:143], v[178:181], v[92:95]
	v_mfma_f32_16x16x32_bf16 v[64:67], v[154:157], v[178:181], v[64:67]
	v_mfma_f32_16x16x32_bf16 v[84:87], v[140:143], v[186:189], v[84:87]
	v_mfma_f32_16x16x32_bf16 v[56:59], v[154:157], v[186:189], v[56:59]
	v_mfma_f32_16x16x32_bf16 v[108:111], v[150:153], v[166:169], v[108:111]
	v_mfma_f32_16x16x32_bf16 v[76:79], v[158:161], v[166:169], v[76:79]
	v_mfma_f32_16x16x32_bf16 v[104:107], v[150:153], v[174:177], v[104:107]
	v_mfma_f32_16x16x32_bf16 v[72:75], v[158:161], v[174:177], v[72:75]
	v_mfma_f32_16x16x32_bf16 v[92:95], v[150:153], v[182:185], v[92:95]
	v_mfma_f32_16x16x32_bf16 v[64:67], v[158:161], v[182:185], v[64:67]
	v_mfma_f32_16x16x32_bf16 v[84:87], v[150:153], v[190:193], v[84:87]
	v_mfma_f32_16x16x32_bf16 v[56:59], v[158:161], v[190:193], v[56:59]
	s_barrier
	s_add_u32 s42, s50, 0x80000
	s_addc_u32 s43, s51, 0
	s_add_i32 s44, s40, s21
	v_lshl_add_u64 v[140:141], s[42:43], 0, v[130:131]
	s_mov_b32 m0, s44
	s_nop 0
	global_load_lds_dwordx4 v[140:141], off
	v_lshl_add_u64 v[140:141], s[42:43], 0, v[128:129]
	s_add_i32 m0, s44, 0x2000
	s_nop 0
	global_load_lds_dwordx4 v[140:141], off
	v_add_u32_e32 v158, 0x18000, v145
	ds_read_b128 v[140:143], v158
	ds_read_b128 v[150:153], v158 offset:1024
	ds_read_b128 v[154:157], v158 offset:2048
	ds_read_b128 v[158:161], v158 offset:3072
	s_waitcnt vmcnt(6)
	s_barrier
	v_mfma_f32_16x16x32_bf16 v[44:47], v[194:197], v[162:165], v[44:47]
	v_mfma_f32_16x16x32_bf16 v[12:15], v[202:205], v[162:165], v[12:15]
	v_mfma_f32_16x16x32_bf16 v[36:39], v[194:197], v[170:173], v[36:39]
	v_mfma_f32_16x16x32_bf16 v[8:11], v[202:205], v[170:173], v[8:11]
	v_mfma_f32_16x16x32_bf16 v[28:31], v[194:197], v[178:181], v[28:31]
	v_mfma_f32_16x16x32_bf16 v[4:7], v[202:205], v[178:181], v[4:7]
	v_mfma_f32_16x16x32_bf16 v[20:23], v[194:197], v[186:189], v[20:23]
	v_mfma_f32_16x16x32_bf16 v[0:3], v[202:205], v[186:189], v[0:3]
	v_mfma_f32_16x16x32_bf16 v[44:47], v[198:201], v[166:169], v[44:47]
	v_mfma_f32_16x16x32_bf16 v[12:15], v[206:209], v[166:169], v[12:15]
	v_mfma_f32_16x16x32_bf16 v[36:39], v[198:201], v[174:177], v[36:39]
	v_mfma_f32_16x16x32_bf16 v[8:11], v[206:209], v[174:177], v[8:11]
	v_mfma_f32_16x16x32_bf16 v[28:31], v[198:201], v[182:185], v[28:31]
	v_mfma_f32_16x16x32_bf16 v[4:7], v[206:209], v[182:185], v[4:7]
	v_mfma_f32_16x16x32_bf16 v[20:23], v[198:201], v[190:193], v[20:23]
	v_mfma_f32_16x16x32_bf16 v[0:3], v[206:209], v[190:193], v[0:3]
	s_add_i32 s42, 0, 0x18000
	s_barrier
	s_add_u32 s4, s4, 0x80000
	s_addc_u32 s5, s5, 0
	s_mov_b32 m0, s25
	v_lshl_add_u64 v[194:195], s[4:5], 0, v[130:131]
	ds_read_b128 v[162:165], v148 offset:32768
	ds_read_b128 v[166:169], v148 offset:33792
	ds_read_b128 v[170:173], v148 offset:34816
	ds_read_b128 v[174:177], v148 offset:35840
	ds_read_b128 v[178:181], v148 offset:36864
	ds_read_b128 v[182:185], v148 offset:37888
	ds_read_b128 v[186:189], v148 offset:38912
	ds_read_b128 v[190:193], v148 offset:39936
	global_load_lds_dwordx4 v[194:195], off
	v_lshl_add_u64 v[194:195], s[4:5], 0, v[128:129]
	s_mov_b32 m0, s28
	s_nop 0
	global_load_lds_dwordx4 v[194:195], off
	s_waitcnt lgkmcnt(8)
	s_barrier
	s_waitcnt lgkmcnt(0)
	s_waitcnt lgkmcnt(0)
	v_mfma_f32_16x16x32_bf16 v[124:127], v[140:143], v[162:165], v[124:127]
	v_mfma_f32_16x16x32_bf16 v[100:103], v[154:157], v[162:165], v[100:103]
	v_mfma_f32_16x16x32_bf16 v[120:123], v[140:143], v[170:173], v[120:123]
	v_mfma_f32_16x16x32_bf16 v[96:99], v[154:157], v[170:173], v[96:99]
	v_mfma_f32_16x16x32_bf16 v[116:119], v[140:143], v[178:181], v[116:119]
	v_mfma_f32_16x16x32_bf16 v[88:91], v[154:157], v[178:181], v[88:91]
	v_mfma_f32_16x16x32_bf16 v[112:115], v[140:143], v[186:189], v[112:115]
	v_mfma_f32_16x16x32_bf16 v[80:83], v[154:157], v[186:189], v[80:83]
	v_mfma_f32_16x16x32_bf16 v[124:127], v[150:153], v[166:169], v[124:127]
	v_mfma_f32_16x16x32_bf16 v[100:103], v[158:161], v[166:169], v[100:103]
	v_mfma_f32_16x16x32_bf16 v[120:123], v[150:153], v[174:177], v[120:123]
	v_mfma_f32_16x16x32_bf16 v[96:99], v[158:161], v[174:177], v[96:99]
	v_mfma_f32_16x16x32_bf16 v[116:119], v[150:153], v[182:185], v[116:119]
	v_mfma_f32_16x16x32_bf16 v[88:91], v[158:161], v[182:185], v[88:91]
	v_mfma_f32_16x16x32_bf16 v[112:115], v[150:153], v[190:193], v[112:115]
	v_mfma_f32_16x16x32_bf16 v[80:83], v[158:161], v[190:193], v[80:83]
	s_barrier
	s_add_i32 s43, 0, 0x1c000
	s_add_i32 s4, s42, s21
	v_add_u32_e32 v206, s43, v145
	v_lshl_add_u64 v[210:211], v[210:211], 0, s[16:17]
	s_mov_b32 m0, s4
	ds_read_b128 v[194:197], v206
	ds_read_b128 v[198:201], v206 offset:1024
	ds_read_b128 v[202:205], v206 offset:2048
	ds_read_b128 v[206:209], v206 offset:3072
	global_load_lds_dwordx4 v[210:211], off
	v_lshl_add_u64 v[210:211], v[212:213], 0, s[16:17]
	s_add_i32 m0, s4, 0x2000
	s_nop 0
	global_load_lds_dwordx4 v[210:211], off
	s_barrier
	s_waitcnt lgkmcnt(0)
	s_waitcnt lgkmcnt(0)
	v_mfma_f32_16x16x32_bf16 v[68:71], v[194:197], v[162:165], v[68:71]
	v_mfma_f32_16x16x32_bf16 v[40:43], v[202:205], v[162:165], v[40:43]
	v_mfma_f32_16x16x32_bf16 v[60:63], v[194:197], v[170:173], v[60:63]
	v_mfma_f32_16x16x32_bf16 v[32:35], v[202:205], v[170:173], v[32:35]
	v_mfma_f32_16x16x32_bf16 v[52:55], v[194:197], v[178:181], v[52:55]
	v_mfma_f32_16x16x32_bf16 v[24:27], v[202:205], v[178:181], v[24:27]
	v_mfma_f32_16x16x32_bf16 v[48:51], v[194:197], v[186:189], v[48:51]
	v_mfma_f32_16x16x32_bf16 v[16:19], v[202:205], v[186:189], v[16:19]
	v_mfma_f32_16x16x32_bf16 v[68:71], v[198:201], v[166:169], v[68:71]
	v_mfma_f32_16x16x32_bf16 v[40:43], v[206:209], v[166:169], v[40:43]
	v_mfma_f32_16x16x32_bf16 v[60:63], v[198:201], v[174:177], v[60:63]
	v_mfma_f32_16x16x32_bf16 v[32:35], v[206:209], v[174:177], v[32:35]
	v_mfma_f32_16x16x32_bf16 v[52:55], v[198:201], v[182:185], v[52:55]
	v_mfma_f32_16x16x32_bf16 v[24:27], v[206:209], v[182:185], v[24:27]
	v_mfma_f32_16x16x32_bf16 v[48:51], v[198:201], v[190:193], v[48:51]
	v_mfma_f32_16x16x32_bf16 v[16:19], v[206:209], v[190:193], v[16:19]
	s_mov_b32 m0, s33
	v_lshl_add_u64 v[210:211], v[214:215], 0, s[16:17]
	s_barrier
	s_waitcnt vmcnt(8)
	ds_read_b128 v[162:165], v148 offset:49152
	ds_read_b128 v[166:169], v148 offset:50176
	ds_read_b128 v[170:173], v148 offset:51200
	ds_read_b128 v[174:177], v148 offset:52224
	ds_read_b128 v[178:181], v148 offset:53248
	ds_read_b128 v[182:185], v148 offset:54272
	ds_read_b128 v[186:189], v148 offset:55296
	ds_read_b128 v[190:193], v148 offset:56320
	global_load_lds_dwordx4 v[210:211], off
	v_lshl_add_u64 v[210:211], v[216:217], 0, s[16:17]
	s_mov_b32 m0, s36
	s_nop 0
	global_load_lds_dwordx4 v[210:211], off
	s_barrier
	s_waitcnt lgkmcnt(0)
	s_waitcnt lgkmcnt(0)
	v_mfma_f32_16x16x32_bf16 v[108:111], v[140:143], v[162:165], v[108:111]
	v_mfma_f32_16x16x32_bf16 v[76:79], v[154:157], v[162:165], v[76:79]
	v_mfma_f32_16x16x32_bf16 v[104:107], v[140:143], v[170:173], v[104:107]
	v_mfma_f32_16x16x32_bf16 v[72:75], v[154:157], v[170:173], v[72:75]
	v_mfma_f32_16x16x32_bf16 v[92:95], v[140:143], v[178:181], v[92:95]
	v_mfma_f32_16x16x32_bf16 v[64:67], v[154:157], v[178:181], v[64:67]
	v_mfma_f32_16x16x32_bf16 v[84:87], v[140:143], v[186:189], v[84:87]
	v_mfma_f32_16x16x32_bf16 v[56:59], v[154:157], v[186:189], v[56:59]
	v_mfma_f32_16x16x32_bf16 v[108:111], v[150:153], v[166:169], v[108:111]
	v_mfma_f32_16x16x32_bf16 v[76:79], v[158:161], v[166:169], v[76:79]
	v_mfma_f32_16x16x32_bf16 v[104:107], v[150:153], v[174:177], v[104:107]
	v_mfma_f32_16x16x32_bf16 v[72:75], v[158:161], v[174:177], v[72:75]
	v_mfma_f32_16x16x32_bf16 v[92:95], v[150:153], v[182:185], v[92:95]
	v_mfma_f32_16x16x32_bf16 v[64:67], v[158:161], v[182:185], v[64:67]
	v_mfma_f32_16x16x32_bf16 v[84:87], v[150:153], v[190:193], v[84:87]
	v_mfma_f32_16x16x32_bf16 v[56:59], v[158:161], v[190:193], v[56:59]
	s_barrier
	s_add_u32 s4, s50, 0x80080
	s_addc_u32 s5, s51, 0
	s_add_i32 s42, s43, s21
	v_lshl_add_u64 v[140:141], s[4:5], 0, v[130:131]
	s_mov_b32 m0, s42
	s_nop 0
	global_load_lds_dwordx4 v[140:141], off
	v_lshl_add_u64 v[140:141], s[4:5], 0, v[128:129]
	s_add_i32 m0, s42, 0x2000
	s_nop 0
	global_load_lds_dwordx4 v[140:141], off
	ds_read_b128 v[140:143], v147
	ds_read_b128 v[150:153], v147 offset:1024
	ds_read_b128 v[154:157], v147 offset:2048
	ds_read_b128 v[158:161], v147 offset:3072
	s_waitcnt vmcnt(6)
	s_barrier
	v_mfma_f32_16x16x32_bf16 v[44:47], v[194:197], v[162:165], v[44:47]
	v_mfma_f32_16x16x32_bf16 v[12:15], v[202:205], v[162:165], v[12:15]
	v_mfma_f32_16x16x32_bf16 v[36:39], v[194:197], v[170:173], v[36:39]
	v_mfma_f32_16x16x32_bf16 v[8:11], v[202:205], v[170:173], v[8:11]
	v_mfma_f32_16x16x32_bf16 v[28:31], v[194:197], v[178:181], v[28:31]
	v_mfma_f32_16x16x32_bf16 v[4:7], v[202:205], v[178:181], v[4:7]
	v_mfma_f32_16x16x32_bf16 v[20:23], v[194:197], v[186:189], v[20:23]
	v_mfma_f32_16x16x32_bf16 v[0:3], v[202:205], v[186:189], v[0:3]
	v_mfma_f32_16x16x32_bf16 v[44:47], v[198:201], v[166:169], v[44:47]
	v_mfma_f32_16x16x32_bf16 v[12:15], v[206:209], v[166:169], v[12:15]
	v_mfma_f32_16x16x32_bf16 v[36:39], v[198:201], v[174:177], v[36:39]
	v_mfma_f32_16x16x32_bf16 v[8:11], v[206:209], v[174:177], v[8:11]
	v_mfma_f32_16x16x32_bf16 v[28:31], v[198:201], v[182:185], v[28:31]
	v_mfma_f32_16x16x32_bf16 v[4:7], v[206:209], v[182:185], v[4:7]
	v_mfma_f32_16x16x32_bf16 v[20:23], v[198:201], v[190:193], v[20:23]
	v_mfma_f32_16x16x32_bf16 v[0:3], v[206:209], v[190:193], v[0:3]
	s_add_i32 s73, s73, 2
	s_add_u32 s61, s61, 0x100
	s_addc_u32 s67, s67, 0
	s_cmp_gt_u32 s73, 29
	s_mov_b64 s[74:75], s[76:77]
	s_barrier
	s_cbranch_scc0 .LBB0_850
	v_lshl_or_b32 v140, s41, 8, v146
	v_lshl_add_u32 v143, s72, 8, v144
	v_lshlrev_b32_e32 v140, 2, v140
	v_lshl_add_u32 v143, v143, 13, v140
	s_mov_b32 s41, s60
	s_mov_b32 s72, s66
	s_mov_b64 s[50:51], s[70:71]
	s_mov_b64 s[74:75], s[68:69]
	v_mov_b32_e32 v141, v143
	v_mov_b32_e32 v142, v143
	global_load_dwordx4 v[166:169], v140, s[14:15] offset:0
	global_load_dwordx4 v[150:153], v141, s[10:11] offset:0
	v_add_u32_e32 v141, 0x20000, v141
	global_load_dwordx4 v[154:157], v141, s[10:11] offset:0
	v_add_u32_e32 v141, 0x20000, v141
	global_load_dwordx4 v[158:161], v141, s[10:11] offset:0
	v_add_u32_e32 v141, 0x20000, v141
	global_load_dwordx4 v[162:165], v141, s[10:11] offset:0
	v_add_u32_e32 v141, 0xa0000, v141
	s_waitcnt vmcnt(3)
	v_pk_fma_f32 v[150:151], v[124:125], v[166:167], v[150:151]
	v_pk_fma_f32 v[152:153], v[126:127], v[168:169], v[152:153]
	global_store_dwordx4 v142, v[150:153], s[12:13] offset:0
	v_add_u32_e32 v142, 0x20000, v142
	global_load_dwordx4 v[150:153], v141, s[10:11] offset:0
	v_add_u32_e32 v141, 0x20000, v141
	s_waitcnt vmcnt(4)
	v_pk_fma_f32 v[154:155], v[120:121], v[166:167], v[154:155]
	v_pk_fma_f32 v[156:157], v[122:123], v[168:169], v[156:157]
	global_store_dwordx4 v142, v[154:157], s[12:13] offset:0
	v_add_u32_e32 v142, 0x20000, v142
	global_load_dwordx4 v[154:157], v141, s[10:11] offset:0
	v_add_u32_e32 v141, 0x20000, v141
	s_waitcnt vmcnt(5)
	v_pk_fma_f32 v[158:159], v[116:117], v[166:167], v[158:159]
	v_pk_fma_f32 v[160:161], v[118:119], v[168:169], v[160:161]
	global_store_dwordx4 v142, v[158:161], s[12:13] offset:0
	v_add_u32_e32 v142, 0x20000, v142
	global_load_dwordx4 v[158:161], v141, s[10:11] offset:0
	v_add_u32_e32 v141, 0x20000, v141
	s_waitcnt vmcnt(6)
	v_pk_fma_f32 v[162:163], v[112:113], v[166:167], v[162:163]
	v_pk_fma_f32 v[164:165], v[114:115], v[168:169], v[164:165]
	global_store_dwordx4 v142, v[162:165], s[12:13] offset:0
	v_add_u32_e32 v142, 0xa0000, v142
	global_load_dwordx4 v[162:165], v141, s[10:11] offset:0
	v_add_u32_e32 v141, 0x20000, v141
	s_waitcnt vmcnt(6)
	v_pk_fma_f32 v[150:151], v[108:109], v[166:167], v[150:151]
	v_pk_fma_f32 v[152:153], v[110:111], v[168:169], v[152:153]
	global_store_dwordx4 v142, v[150:153], s[12:13] offset:0
	v_add_u32_e32 v142, 0x20000, v142
	s_waitcnt vmcnt(5)
	v_pk_fma_f32 v[154:155], v[104:105], v[166:167], v[154:155]
	v_pk_fma_f32 v[156:157], v[106:107], v[168:169], v[156:157]
	global_store_dwordx4 v142, v[154:157], s[12:13] offset:0
	v_add_u32_e32 v142, 0x20000, v142
	s_waitcnt vmcnt(4)
	v_pk_fma_f32 v[158:159], v[92:93], v[166:167], v[158:159]
	v_pk_fma_f32 v[160:161], v[94:95], v[168:169], v[160:161]
	global_store_dwordx4 v142, v[158:161], s[12:13] offset:0
	v_add_u32_e32 v142, 0x20000, v142
	s_waitcnt vmcnt(3)
	v_pk_fma_f32 v[162:163], v[84:85], v[166:167], v[162:163]
	v_pk_fma_f32 v[164:165], v[86:87], v[168:169], v[164:165]
	global_store_dwordx4 v142, v[162:165], s[12:13] offset:0
	v_add_u32_e32 v142, 0x20000, v142
	v_mov_b32_e32 v141, v143
	v_mov_b32_e32 v142, v143
	global_load_dwordx4 v[166:169], v140, s[14:15] offset:64
	global_load_dwordx4 v[150:153], v141, s[10:11] offset:64
	v_add_u32_e32 v141, 0x20000, v141
	global_load_dwordx4 v[154:157], v141, s[10:11] offset:64
	v_add_u32_e32 v141, 0x20000, v141
	global_load_dwordx4 v[158:161], v141, s[10:11] offset:64
	v_add_u32_e32 v141, 0x20000, v141
	global_load_dwordx4 v[162:165], v141, s[10:11] offset:64
	v_add_u32_e32 v141, 0xa0000, v141
	s_waitcnt vmcnt(3)
	v_pk_fma_f32 v[150:151], v[100:101], v[166:167], v[150:151]
	v_pk_fma_f32 v[152:153], v[102:103], v[168:169], v[152:153]
	global_store_dwordx4 v142, v[150:153], s[12:13] offset:64
	v_add_u32_e32 v142, 0x20000, v142
	global_load_dwordx4 v[150:153], v141, s[10:11] offset:64
	v_add_u32_e32 v141, 0x20000, v141
	s_waitcnt vmcnt(4)
	v_pk_fma_f32 v[154:155], v[96:97], v[166:167], v[154:155]
	v_pk_fma_f32 v[156:157], v[98:99], v[168:169], v[156:157]
	global_store_dwordx4 v142, v[154:157], s[12:13] offset:64
	v_add_u32_e32 v142, 0x20000, v142
	global_load_dwordx4 v[154:157], v141, s[10:11] offset:64
	v_add_u32_e32 v141, 0x20000, v141
	s_waitcnt vmcnt(5)
	v_pk_fma_f32 v[158:159], v[88:89], v[166:167], v[158:159]
	v_pk_fma_f32 v[160:161], v[90:91], v[168:169], v[160:161]
	global_store_dwordx4 v142, v[158:161], s[12:13] offset:64
	v_add_u32_e32 v142, 0x20000, v142
	global_load_dwordx4 v[158:161], v141, s[10:11] offset:64
	v_add_u32_e32 v141, 0x20000, v141
	s_waitcnt vmcnt(6)
	v_pk_fma_f32 v[162:163], v[80:81], v[166:167], v[162:163]
	v_pk_fma_f32 v[164:165], v[82:83], v[168:169], v[164:165]
	global_store_dwordx4 v142, v[162:165], s[12:13] offset:64
	v_add_u32_e32 v142, 0xa0000, v142
	global_load_dwordx4 v[162:165], v141, s[10:11] offset:64
	v_add_u32_e32 v141, 0x20000, v141
	s_waitcnt vmcnt(6)
	v_pk_fma_f32 v[150:151], v[76:77], v[166:167], v[150:151]
	v_pk_fma_f32 v[152:153], v[78:79], v[168:169], v[152:153]
	global_store_dwordx4 v142, v[150:153], s[12:13] offset:64
	v_add_u32_e32 v142, 0x20000, v142
	s_waitcnt vmcnt(5)
	v_pk_fma_f32 v[154:155], v[72:73], v[166:167], v[154:155]
	v_pk_fma_f32 v[156:157], v[74:75], v[168:169], v[156:157]
	global_store_dwordx4 v142, v[154:157], s[12:13] offset:64
	v_add_u32_e32 v142, 0x20000, v142
	s_waitcnt vmcnt(4)
	v_pk_fma_f32 v[158:159], v[64:65], v[166:167], v[158:159]
	v_pk_fma_f32 v[160:161], v[66:67], v[168:169], v[160:161]
	global_store_dwordx4 v142, v[158:161], s[12:13] offset:64
	v_add_u32_e32 v142, 0x20000, v142
	s_waitcnt vmcnt(3)
	v_pk_fma_f32 v[162:163], v[56:57], v[166:167], v[162:163]
	v_pk_fma_f32 v[164:165], v[58:59], v[168:169], v[164:165]
	global_store_dwordx4 v142, v[162:165], s[12:13] offset:64
	v_add_u32_e32 v142, 0x20000, v142
	v_mov_b32_e32 v141, v143
	v_mov_b32_e32 v142, v143
	global_load_dwordx4 v[166:169], v140, s[14:15] offset:512
	global_load_dwordx4 v[150:153], v141, s[10:11] offset:512
	v_add_u32_e32 v141, 0x20000, v141
	global_load_dwordx4 v[154:157], v141, s[10:11] offset:512
	v_add_u32_e32 v141, 0x20000, v141
	global_load_dwordx4 v[158:161], v141, s[10:11] offset:512
	v_add_u32_e32 v141, 0x20000, v141
	global_load_dwordx4 v[162:165], v141, s[10:11] offset:512
	v_add_u32_e32 v141, 0xa0000, v141
	s_waitcnt vmcnt(3)
	v_pk_fma_f32 v[150:151], v[68:69], v[166:167], v[150:151]
	v_pk_fma_f32 v[152:153], v[70:71], v[168:169], v[152:153]
	global_store_dwordx4 v142, v[150:153], s[12:13] offset:512
	v_add_u32_e32 v142, 0x20000, v142
	global_load_dwordx4 v[150:153], v141, s[10:11] offset:512
	v_add_u32_e32 v141, 0x20000, v141
	s_waitcnt vmcnt(4)
	v_pk_fma_f32 v[154:155], v[60:61], v[166:167], v[154:155]
	v_pk_fma_f32 v[156:157], v[62:63], v[168:169], v[156:157]
	global_store_dwordx4 v142, v[154:157], s[12:13] offset:512
	v_add_u32_e32 v142, 0x20000, v142
	global_load_dwordx4 v[154:157], v141, s[10:11] offset:512
	v_add_u32_e32 v141, 0x20000, v141
	s_waitcnt vmcnt(5)
	v_pk_fma_f32 v[158:159], v[52:53], v[166:167], v[158:159]
	v_pk_fma_f32 v[160:161], v[54:55], v[168:169], v[160:161]
	global_store_dwordx4 v142, v[158:161], s[12:13] offset:512
	v_add_u32_e32 v142, 0x20000, v142
	global_load_dwordx4 v[158:161], v141, s[10:11] offset:512
	v_add_u32_e32 v141, 0x20000, v141
	s_waitcnt vmcnt(6)
	v_pk_fma_f32 v[162:163], v[48:49], v[166:167], v[162:163]
	v_pk_fma_f32 v[164:165], v[50:51], v[168:169], v[164:165]
	global_store_dwordx4 v142, v[162:165], s[12:13] offset:512
	v_add_u32_e32 v142, 0xa0000, v142
	global_load_dwordx4 v[162:165], v141, s[10:11] offset:512
	v_add_u32_e32 v141, 0x20000, v141
	s_waitcnt vmcnt(6)
	v_pk_fma_f32 v[150:151], v[44:45], v[166:167], v[150:151]
	v_pk_fma_f32 v[152:153], v[46:47], v[168:169], v[152:153]
	global_store_dwordx4 v142, v[150:153], s[12:13] offset:512
	v_add_u32_e32 v142, 0x20000, v142
	s_waitcnt vmcnt(5)
	v_pk_fma_f32 v[154:155], v[36:37], v[166:167], v[154:155]
	v_pk_fma_f32 v[156:157], v[38:39], v[168:169], v[156:157]
	global_store_dwordx4 v142, v[154:157], s[12:13] offset:512
	v_add_u32_e32 v142, 0x20000, v142
	s_waitcnt vmcnt(4)
	v_pk_fma_f32 v[158:159], v[28:29], v[166:167], v[158:159]
	v_pk_fma_f32 v[160:161], v[30:31], v[168:169], v[160:161]
	global_store_dwordx4 v142, v[158:161], s[12:13] offset:512
	v_add_u32_e32 v142, 0x20000, v142
	s_waitcnt vmcnt(3)
	v_pk_fma_f32 v[162:163], v[20:21], v[166:167], v[162:163]
	v_pk_fma_f32 v[164:165], v[22:23], v[168:169], v[164:165]
	global_store_dwordx4 v142, v[162:165], s[12:13] offset:512
	v_add_u32_e32 v142, 0x20000, v142
	v_mov_b32_e32 v141, v143
	v_mov_b32_e32 v142, v143
	global_load_dwordx4 v[166:169], v140, s[14:15] offset:576
	global_load_dwordx4 v[150:153], v141, s[10:11] offset:576
	v_add_u32_e32 v141, 0x20000, v141
	global_load_dwordx4 v[154:157], v141, s[10:11] offset:576
	v_add_u32_e32 v141, 0x20000, v141
	global_load_dwordx4 v[158:161], v141, s[10:11] offset:576
	v_add_u32_e32 v141, 0x20000, v141
	global_load_dwordx4 v[162:165], v141, s[10:11] offset:576
	v_add_u32_e32 v141, 0xa0000, v141
	s_waitcnt vmcnt(3)
	v_pk_fma_f32 v[150:151], v[40:41], v[166:167], v[150:151]
	v_pk_fma_f32 v[152:153], v[42:43], v[168:169], v[152:153]
	global_store_dwordx4 v142, v[150:153], s[12:13] offset:576
	v_add_u32_e32 v142, 0x20000, v142
	global_load_dwordx4 v[150:153], v141, s[10:11] offset:576
	v_add_u32_e32 v141, 0x20000, v141
	s_waitcnt vmcnt(4)
	v_pk_fma_f32 v[154:155], v[32:33], v[166:167], v[154:155]
	v_pk_fma_f32 v[156:157], v[34:35], v[168:169], v[156:157]
	global_store_dwordx4 v142, v[154:157], s[12:13] offset:576
	v_add_u32_e32 v142, 0x20000, v142
	global_load_dwordx4 v[154:157], v141, s[10:11] offset:576
	v_add_u32_e32 v141, 0x20000, v141
	s_waitcnt vmcnt(5)
	v_pk_fma_f32 v[158:159], v[24:25], v[166:167], v[158:159]
	v_pk_fma_f32 v[160:161], v[26:27], v[168:169], v[160:161]
	global_store_dwordx4 v142, v[158:161], s[12:13] offset:576
	v_add_u32_e32 v142, 0x20000, v142
	global_load_dwordx4 v[158:161], v141, s[10:11] offset:576
	v_add_u32_e32 v141, 0x20000, v141
	s_waitcnt vmcnt(6)
	v_pk_fma_f32 v[162:163], v[16:17], v[166:167], v[162:163]
	v_pk_fma_f32 v[164:165], v[18:19], v[168:169], v[164:165]
	global_store_dwordx4 v142, v[162:165], s[12:13] offset:576
	v_add_u32_e32 v142, 0xa0000, v142
	global_load_dwordx4 v[162:165], v141, s[10:11] offset:576
	v_add_u32_e32 v141, 0x20000, v141
	s_waitcnt vmcnt(6)
	v_pk_fma_f32 v[150:151], v[12:13], v[166:167], v[150:151]
	v_pk_fma_f32 v[152:153], v[14:15], v[168:169], v[152:153]
	global_store_dwordx4 v142, v[150:153], s[12:13] offset:576
	v_add_u32_e32 v142, 0x20000, v142
	s_waitcnt vmcnt(5)
	v_pk_fma_f32 v[154:155], v[8:9], v[166:167], v[154:155]
	v_pk_fma_f32 v[156:157], v[10:11], v[168:169], v[156:157]
	global_store_dwordx4 v142, v[154:157], s[12:13] offset:576
	v_add_u32_e32 v142, 0x20000, v142
	s_waitcnt vmcnt(4)
	v_pk_fma_f32 v[158:159], v[4:5], v[166:167], v[158:159]
	v_pk_fma_f32 v[160:161], v[6:7], v[168:169], v[160:161]
	global_store_dwordx4 v142, v[158:161], s[12:13] offset:576
	v_add_u32_e32 v142, 0x20000, v142
	s_waitcnt vmcnt(3)
	v_pk_fma_f32 v[162:163], v[0:1], v[166:167], v[162:163]
	v_pk_fma_f32 v[164:165], v[2:3], v[168:169], v[164:165]
	global_store_dwordx4 v142, v[162:165], s[12:13] offset:576
	v_add_u32_e32 v142, 0x20000, v142
	s_and_b64 vcc, exec, s[6:7]
	s_cbranch_vccz .LBB0_843
	s_waitcnt vmcnt(0)
	s_cmpk_gt_u32 s20, 0xff
	s_cbranch_scc1 .LBB0_854
	s_barrier

.LBB0_985:
	s_ashr_i32 s13, s12, 31
	v_cmp_lt_i64_e32 vcc, s[0:1], v[142:143]
	s_lshl_b64 s[0:1], s[12:13], 20
	s_add_u32 s14, s38, s0
	s_addc_u32 s15, s39, s1
	s_and_b64 s[0:1], vcc, exec
	s_cselect_b32 s0, s15, s37
	s_cselect_b32 s1, s14, s36
	s_ashr_i32 s11, s10, 31
	s_lshl_b64 s[4:5], s[10:11], 20
	s_add_u32 s16, s62, s4
	s_addc_u32 s17, s63, s5
	s_and_b64 s[4:5], vcc, exec
	s_cselect_b32 s11, s17, s51
	s_cselect_b32 s13, s16, s50
	s_add_u32 s60, s36, 0x80080
	s_addc_u32 s61, s37, 0
	s_add_u32 s36, s50, 0x100
	v_mov_b32_e32 v0, 0
	s_addc_u32 s37, s51, 0
	s_mov_b32 s64, -2
	v_mov_b32_e32 v1, v0
	v_mov_b32_e32 v2, v0
	v_mov_b32_e32 v3, v0
	v_mov_b32_e32 v4, v0
	v_mov_b32_e32 v5, v0
	v_mov_b32_e32 v6, v0
	v_mov_b32_e32 v7, v0
	v_mov_b32_e32 v16, v0
	v_mov_b32_e32 v17, v0
	v_mov_b32_e32 v18, v0
	v_mov_b32_e32 v19, v0
	v_mov_b32_e32 v20, v0
	v_mov_b32_e32 v21, v0
	v_mov_b32_e32 v22, v0
	v_mov_b32_e32 v23, v0
	v_mov_b32_e32 v32, v0
	v_mov_b32_e32 v33, v0
	v_mov_b32_e32 v34, v0
	v_mov_b32_e32 v35, v0
	v_mov_b32_e32 v36, v0
	v_mov_b32_e32 v37, v0
	v_mov_b32_e32 v38, v0
	v_mov_b32_e32 v39, v0
	v_mov_b32_e32 v48, v0
	v_mov_b32_e32 v49, v0
	v_mov_b32_e32 v50, v0
	v_mov_b32_e32 v51, v0
	v_mov_b32_e32 v52, v0
	v_mov_b32_e32 v53, v0
	v_mov_b32_e32 v54, v0
	v_mov_b32_e32 v55, v0
	v_mov_b32_e32 v8, v0
	v_mov_b32_e32 v9, v0
	v_mov_b32_e32 v10, v0
	v_mov_b32_e32 v11, v0
	v_mov_b32_e32 v12, v0
	v_mov_b32_e32 v13, v0
	v_mov_b32_e32 v14, v0
	v_mov_b32_e32 v15, v0
	v_mov_b32_e32 v24, v0
	v_mov_b32_e32 v25, v0
	v_mov_b32_e32 v26, v0
	v_mov_b32_e32 v27, v0
	v_mov_b32_e32 v28, v0
	v_mov_b32_e32 v29, v0
	v_mov_b32_e32 v30, v0
	v_mov_b32_e32 v31, v0
	v_mov_b32_e32 v40, v0
	v_mov_b32_e32 v41, v0
	v_mov_b32_e32 v42, v0
	v_mov_b32_e32 v43, v0
	v_mov_b32_e32 v44, v0
	v_mov_b32_e32 v45, v0
	v_mov_b32_e32 v46, v0
	v_mov_b32_e32 v47, v0
	v_mov_b32_e32 v56, v0
	v_mov_b32_e32 v57, v0
	v_mov_b32_e32 v58, v0
	v_mov_b32_e32 v59, v0
	v_mov_b32_e32 v60, v0
	v_mov_b32_e32 v61, v0
	v_mov_b32_e32 v62, v0
	v_mov_b32_e32 v63, v0
	v_mov_b32_e32 v64, v0
	v_mov_b32_e32 v65, v0
	v_mov_b32_e32 v66, v0
	v_mov_b32_e32 v67, v0
	v_mov_b32_e32 v68, v0
	v_mov_b32_e32 v69, v0
	v_mov_b32_e32 v70, v0
	v_mov_b32_e32 v71, v0
	v_mov_b32_e32 v80, v0
	v_mov_b32_e32 v81, v0
	v_mov_b32_e32 v82, v0
	v_mov_b32_e32 v83, v0
	v_mov_b32_e32 v84, v0
	v_mov_b32_e32 v85, v0
	v_mov_b32_e32 v86, v0
	v_mov_b32_e32 v87, v0
	v_mov_b32_e32 v96, v0
	v_mov_b32_e32 v97, v0
	v_mov_b32_e32 v98, v0
	v_mov_b32_e32 v99, v0
	v_mov_b32_e32 v100, v0
	v_mov_b32_e32 v101, v0
	v_mov_b32_e32 v102, v0
	v_mov_b32_e32 v103, v0
	v_mov_b32_e32 v112, v0
	v_mov_b32_e32 v113, v0
	v_mov_b32_e32 v114, v0
	v_mov_b32_e32 v115, v0
	v_mov_b32_e32 v116, v0
	v_mov_b32_e32 v117, v0
	v_mov_b32_e32 v118, v0
	v_mov_b32_e32 v119, v0
	v_mov_b32_e32 v72, v0
	v_mov_b32_e32 v73, v0
	v_mov_b32_e32 v74, v0
	v_mov_b32_e32 v75, v0
	v_mov_b32_e32 v76, v0
	v_mov_b32_e32 v77, v0
	v_mov_b32_e32 v78, v0
	v_mov_b32_e32 v79, v0
	v_mov_b32_e32 v88, v0
	v_mov_b32_e32 v89, v0
	v_mov_b32_e32 v90, v0
	v_mov_b32_e32 v91, v0
	v_mov_b32_e32 v92, v0
	v_mov_b32_e32 v93, v0
	v_mov_b32_e32 v94, v0
	v_mov_b32_e32 v95, v0
	v_mov_b32_e32 v104, v0
	v_mov_b32_e32 v105, v0
	v_mov_b32_e32 v106, v0
	v_mov_b32_e32 v107, v0
	v_mov_b32_e32 v108, v0
	v_mov_b32_e32 v109, v0
	v_mov_b32_e32 v110, v0
	v_mov_b32_e32 v111, v0
	v_mov_b32_e32 v120, v0
	v_mov_b32_e32 v121, v0
	v_mov_b32_e32 v122, v0
	v_mov_b32_e32 v123, v0
	v_mov_b32_e32 v124, v0
	v_mov_b32_e32 v125, v0
	v_mov_b32_e32 v126, v0
	v_mov_b32_e32 v127, v0
	ds_read_b128 v[152:155], v148
	ds_read_b128 v[156:159], v148 offset:1024
	ds_read_b128 v[160:163], v148 offset:2048
	ds_read_b128 v[164:167], v148 offset:3072
.LBB0_986:
	s_add_u32 s4, s60, 0xfff80080
	s_addc_u32 s5, s61, -1
	s_cmp_eq_u32 s64, 28
	s_cselect_b32 s5, s0, s5
	s_cselect_b32 s4, s1, s4
	s_cselect_b32 s51, s11, s37
	s_cselect_b32 s50, s13, s36
	v_lshl_add_u64 v[200:201], s[60:61], 0, v[138:139]
	s_add_i32 m0, s19, 0xc000
	ds_read_b128 v[168:171], v149
	ds_read_b128 v[172:175], v149 offset:1024
	ds_read_b128 v[176:179], v149 offset:2048
	ds_read_b128 v[180:183], v149 offset:3072
	ds_read_b128 v[184:187], v149 offset:4096
	ds_read_b128 v[188:191], v149 offset:5120
	ds_read_b128 v[192:195], v149 offset:6144
	ds_read_b128 v[196:199], v149 offset:7168
	global_load_lds_dwordx4 v[200:201], off
	v_lshl_add_u64 v[200:201], s[60:61], 0, v[140:141]
	s_add_i32 m0, s19, 0xe000
	s_nop 0
	global_load_lds_dwordx4 v[200:201], off
	s_waitcnt lgkmcnt(8)
	s_barrier
	s_waitcnt lgkmcnt(0)
	s_waitcnt lgkmcnt(0)
	v_mfma_f32_16x16x32_bf16 v[124:127], v[152:155], v[168:171], v[124:127]
	v_mfma_f32_16x16x32_bf16 v[120:123], v[160:163], v[168:171], v[120:123]
	v_mfma_f32_16x16x32_bf16 v[108:111], v[152:155], v[176:179], v[108:111]
	v_mfma_f32_16x16x32_bf16 v[104:107], v[160:163], v[176:179], v[104:107]
	v_mfma_f32_16x16x32_bf16 v[92:95], v[152:155], v[184:187], v[92:95]
	v_mfma_f32_16x16x32_bf16 v[88:91], v[160:163], v[184:187], v[88:91]
	v_mfma_f32_16x16x32_bf16 v[76:79], v[152:155], v[192:195], v[76:79]
	v_mfma_f32_16x16x32_bf16 v[72:75], v[160:163], v[192:195], v[72:75]
	v_mfma_f32_16x16x32_bf16 v[124:127], v[156:159], v[172:175], v[124:127]
	v_mfma_f32_16x16x32_bf16 v[120:123], v[164:167], v[172:175], v[120:123]
	v_mfma_f32_16x16x32_bf16 v[108:111], v[156:159], v[180:183], v[108:111]
	v_mfma_f32_16x16x32_bf16 v[104:107], v[164:167], v[180:183], v[104:107]
	v_mfma_f32_16x16x32_bf16 v[92:95], v[156:159], v[188:191], v[92:95]
	v_mfma_f32_16x16x32_bf16 v[88:91], v[164:167], v[188:191], v[88:91]
	v_mfma_f32_16x16x32_bf16 v[76:79], v[156:159], v[196:199], v[76:79]
	v_mfma_f32_16x16x32_bf16 v[72:75], v[164:167], v[196:199], v[72:75]
	s_barrier
	s_add_i32 s42, s41, s21
	v_lshl_add_u64 v[216:217], s[50:51], 0, v[134:135]
	s_mov_b32 m0, s42
	ds_read_b128 v[200:203], v150
	ds_read_b128 v[204:207], v150 offset:1024
	ds_read_b128 v[208:211], v150 offset:2048
	ds_read_b128 v[212:215], v150 offset:3072
	global_load_lds_dwordx4 v[216:217], off
	v_lshl_add_u64 v[218:219], s[50:51], 0, v[130:131]
	s_add_i32 m0, s42, 0x2000
	s_nop 0
	global_load_lds_dwordx4 v[218:219], off
	s_barrier
	s_waitcnt lgkmcnt(0)
	s_waitcnt lgkmcnt(0)
	v_mfma_f32_16x16x32_bf16 v[116:119], v[200:203], v[168:171], v[116:119]
	v_mfma_f32_16x16x32_bf16 v[112:115], v[208:211], v[168:171], v[112:115]
	v_mfma_f32_16x16x32_bf16 v[100:103], v[200:203], v[176:179], v[100:103]
	v_mfma_f32_16x16x32_bf16 v[96:99], v[208:211], v[176:179], v[96:99]
	v_mfma_f32_16x16x32_bf16 v[84:87], v[200:203], v[184:187], v[84:87]
	v_mfma_f32_16x16x32_bf16 v[80:83], v[208:211], v[184:187], v[80:83]
	v_mfma_f32_16x16x32_bf16 v[68:71], v[200:203], v[192:195], v[68:71]
	v_mfma_f32_16x16x32_bf16 v[64:67], v[208:211], v[192:195], v[64:67]
	v_mfma_f32_16x16x32_bf16 v[116:119], v[204:207], v[172:175], v[116:119]
	v_mfma_f32_16x16x32_bf16 v[112:115], v[212:215], v[172:175], v[112:115]
	v_mfma_f32_16x16x32_bf16 v[100:103], v[204:207], v[180:183], v[100:103]
	v_mfma_f32_16x16x32_bf16 v[96:99], v[212:215], v[180:183], v[96:99]
	v_mfma_f32_16x16x32_bf16 v[84:87], v[204:207], v[188:191], v[84:87]
	v_mfma_f32_16x16x32_bf16 v[80:83], v[212:215], v[188:191], v[80:83]
	v_mfma_f32_16x16x32_bf16 v[68:71], v[204:207], v[196:199], v[68:71]
	v_mfma_f32_16x16x32_bf16 v[64:67], v[212:215], v[196:199], v[64:67]
	s_mov_b32 m0, s19
	v_lshl_add_u64 v[220:221], s[4:5], 0, v[136:137]
	s_barrier
	s_waitcnt vmcnt(8)
	ds_read_b128 v[168:171], v149 offset:16384
	ds_read_b128 v[172:175], v149 offset:17408
	ds_read_b128 v[176:179], v149 offset:18432
	ds_read_b128 v[180:183], v149 offset:19456
	ds_read_b128 v[184:187], v149 offset:20480
	ds_read_b128 v[188:191], v149 offset:21504
	ds_read_b128 v[192:195], v149 offset:22528
	ds_read_b128 v[196:199], v149 offset:23552
	global_load_lds_dwordx4 v[220:221], off
	v_lshl_add_u64 v[222:223], s[4:5], 0, v[132:133]
	s_mov_b32 m0, s24
	s_nop 0
	global_load_lds_dwordx4 v[222:223], off
	s_barrier
	s_waitcnt lgkmcnt(0)
	s_waitcnt lgkmcnt(0)
	v_mfma_f32_16x16x32_bf16 v[60:63], v[152:155], v[168:171], v[60:63]
	v_mfma_f32_16x16x32_bf16 v[56:59], v[160:163], v[168:171], v[56:59]
	v_mfma_f32_16x16x32_bf16 v[44:47], v[152:155], v[176:179], v[44:47]
	v_mfma_f32_16x16x32_bf16 v[40:43], v[160:163], v[176:179], v[40:43]
	v_mfma_f32_16x16x32_bf16 v[28:31], v[152:155], v[184:187], v[28:31]
	v_mfma_f32_16x16x32_bf16 v[24:27], v[160:163], v[184:187], v[24:27]
	v_mfma_f32_16x16x32_bf16 v[12:15], v[152:155], v[192:195], v[12:15]
	v_mfma_f32_16x16x32_bf16 v[8:11], v[160:163], v[192:195], v[8:11]
	v_mfma_f32_16x16x32_bf16 v[60:63], v[156:159], v[172:175], v[60:63]
	v_mfma_f32_16x16x32_bf16 v[56:59], v[164:167], v[172:175], v[56:59]
	v_mfma_f32_16x16x32_bf16 v[44:47], v[156:159], v[180:183], v[44:47]
	v_mfma_f32_16x16x32_bf16 v[40:43], v[164:167], v[180:183], v[40:43]
	v_mfma_f32_16x16x32_bf16 v[28:31], v[156:159], v[188:191], v[28:31]
	v_mfma_f32_16x16x32_bf16 v[24:27], v[164:167], v[188:191], v[24:27]
	v_mfma_f32_16x16x32_bf16 v[12:15], v[156:159], v[196:199], v[12:15]
	v_mfma_f32_16x16x32_bf16 v[8:11], v[164:167], v[196:199], v[8:11]
	s_barrier
	s_add_u32 s42, s50, 0x80000
	s_addc_u32 s43, s51, 0
	s_add_i32 s44, s46, s21
	v_lshl_add_u64 v[152:153], s[42:43], 0, v[134:135]
	s_mov_b32 m0, s44
	s_nop 0
	global_load_lds_dwordx4 v[152:153], off
	v_lshl_add_u64 v[152:153], s[42:43], 0, v[130:131]
	s_add_i32 m0, s44, 0x2000
	s_nop 0
	global_load_lds_dwordx4 v[152:153], off
	v_add_u32_e32 v151, 0x18000, v146
	ds_read_b128 v[152:155], v151
	ds_read_b128 v[156:159], v151 offset:1024
	ds_read_b128 v[160:163], v151 offset:2048
	ds_read_b128 v[164:167], v151 offset:3072
	s_waitcnt vmcnt(6)
	s_barrier
	v_mfma_f32_16x16x32_bf16 v[52:55], v[200:203], v[168:171], v[52:55]
	v_mfma_f32_16x16x32_bf16 v[48:51], v[208:211], v[168:171], v[48:51]
	v_mfma_f32_16x16x32_bf16 v[36:39], v[200:203], v[176:179], v[36:39]
	v_mfma_f32_16x16x32_bf16 v[32:35], v[208:211], v[176:179], v[32:35]
	v_mfma_f32_16x16x32_bf16 v[20:23], v[200:203], v[184:187], v[20:23]
	v_mfma_f32_16x16x32_bf16 v[16:19], v[208:211], v[184:187], v[16:19]
	v_mfma_f32_16x16x32_bf16 v[4:7], v[200:203], v[192:195], v[4:7]
	v_mfma_f32_16x16x32_bf16 v[0:3], v[208:211], v[192:195], v[0:3]
	v_mfma_f32_16x16x32_bf16 v[52:55], v[204:207], v[172:175], v[52:55]
	v_mfma_f32_16x16x32_bf16 v[48:51], v[212:215], v[172:175], v[48:51]
	v_mfma_f32_16x16x32_bf16 v[36:39], v[204:207], v[180:183], v[36:39]
	v_mfma_f32_16x16x32_bf16 v[32:35], v[212:215], v[180:183], v[32:35]
	v_mfma_f32_16x16x32_bf16 v[20:23], v[204:207], v[188:191], v[20:23]
	v_mfma_f32_16x16x32_bf16 v[16:19], v[212:215], v[188:191], v[16:19]
	v_mfma_f32_16x16x32_bf16 v[4:7], v[204:207], v[196:199], v[4:7]
	v_mfma_f32_16x16x32_bf16 v[0:3], v[212:215], v[196:199], v[0:3]
	s_add_i32 s42, 0, 0x18000
	s_barrier
	s_add_u32 s4, s4, 0x80000
	s_addc_u32 s5, s5, 0
	s_mov_b32 m0, s25
	v_lshl_add_u64 v[200:201], s[4:5], 0, v[136:137]
	ds_read_b128 v[168:171], v149 offset:32768
	ds_read_b128 v[172:175], v149 offset:33792
	ds_read_b128 v[176:179], v149 offset:34816
	ds_read_b128 v[180:183], v149 offset:35840
	ds_read_b128 v[184:187], v149 offset:36864
	ds_read_b128 v[188:191], v149 offset:37888
	ds_read_b128 v[192:195], v149 offset:38912
	ds_read_b128 v[196:199], v149 offset:39936
	global_load_lds_dwordx4 v[200:201], off
	v_lshl_add_u64 v[200:201], s[4:5], 0, v[132:133]
	s_mov_b32 m0, s28
	s_nop 0
	global_load_lds_dwordx4 v[200:201], off
	s_waitcnt lgkmcnt(8)
	s_barrier
	s_waitcnt lgkmcnt(0)
	s_waitcnt lgkmcnt(0)
	v_mfma_f32_16x16x32_bf16 v[124:127], v[152:155], v[168:171], v[124:127]
	v_mfma_f32_16x16x32_bf16 v[120:123], v[160:163], v[168:171], v[120:123]
	v_mfma_f32_16x16x32_bf16 v[108:111], v[152:155], v[176:179], v[108:111]
	v_mfma_f32_16x16x32_bf16 v[104:107], v[160:163], v[176:179], v[104:107]
	v_mfma_f32_16x16x32_bf16 v[92:95], v[152:155], v[184:187], v[92:95]
	v_mfma_f32_16x16x32_bf16 v[88:91], v[160:163], v[184:187], v[88:91]
	v_mfma_f32_16x16x32_bf16 v[76:79], v[152:155], v[192:195], v[76:79]
	v_mfma_f32_16x16x32_bf16 v[72:75], v[160:163], v[192:195], v[72:75]
	v_mfma_f32_16x16x32_bf16 v[124:127], v[156:159], v[172:175], v[124:127]
	v_mfma_f32_16x16x32_bf16 v[120:123], v[164:167], v[172:175], v[120:123]
	v_mfma_f32_16x16x32_bf16 v[108:111], v[156:159], v[180:183], v[108:111]
	v_mfma_f32_16x16x32_bf16 v[104:107], v[164:167], v[180:183], v[104:107]
	v_mfma_f32_16x16x32_bf16 v[92:95], v[156:159], v[188:191], v[92:95]
	v_mfma_f32_16x16x32_bf16 v[88:91], v[164:167], v[188:191], v[88:91]
	v_mfma_f32_16x16x32_bf16 v[76:79], v[156:159], v[196:199], v[76:79]
	v_mfma_f32_16x16x32_bf16 v[72:75], v[164:167], v[196:199], v[72:75]
	s_barrier
	s_add_i32 s43, 0, 0x1c000
	s_add_i32 s4, s42, s21
	v_add_u32_e32 v151, s43, v146
	v_lshl_add_u64 v[216:217], v[216:217], 0, s[8:9]
	s_mov_b32 m0, s4
	ds_read_b128 v[200:203], v151
	ds_read_b128 v[204:207], v151 offset:1024
	ds_read_b128 v[208:211], v151 offset:2048
	ds_read_b128 v[212:215], v151 offset:3072
	global_load_lds_dwordx4 v[216:217], off
	v_lshl_add_u64 v[216:217], v[218:219], 0, s[8:9]
	s_add_i32 m0, s4, 0x2000
	s_nop 0
	global_load_lds_dwordx4 v[216:217], off
	s_barrier
	s_waitcnt lgkmcnt(0)
	s_waitcnt lgkmcnt(0)
	v_mfma_f32_16x16x32_bf16 v[116:119], v[200:203], v[168:171], v[116:119]
	v_mfma_f32_16x16x32_bf16 v[112:115], v[208:211], v[168:171], v[112:115]
	v_mfma_f32_16x16x32_bf16 v[100:103], v[200:203], v[176:179], v[100:103]
	v_mfma_f32_16x16x32_bf16 v[96:99], v[208:211], v[176:179], v[96:99]
	v_mfma_f32_16x16x32_bf16 v[84:87], v[200:203], v[184:187], v[84:87]
	v_mfma_f32_16x16x32_bf16 v[80:83], v[208:211], v[184:187], v[80:83]
	v_mfma_f32_16x16x32_bf16 v[68:71], v[200:203], v[192:195], v[68:71]
	v_mfma_f32_16x16x32_bf16 v[64:67], v[208:211], v[192:195], v[64:67]
	v_mfma_f32_16x16x32_bf16 v[116:119], v[204:207], v[172:175], v[116:119]
	v_mfma_f32_16x16x32_bf16 v[112:115], v[212:215], v[172:175], v[112:115]
	v_mfma_f32_16x16x32_bf16 v[100:103], v[204:207], v[180:183], v[100:103]
	v_mfma_f32_16x16x32_bf16 v[96:99], v[212:215], v[180:183], v[96:99]
	v_mfma_f32_16x16x32_bf16 v[84:87], v[204:207], v[188:191], v[84:87]
	v_mfma_f32_16x16x32_bf16 v[80:83], v[212:215], v[188:191], v[80:83]
	v_mfma_f32_16x16x32_bf16 v[68:71], v[204:207], v[196:199], v[68:71]
	v_mfma_f32_16x16x32_bf16 v[64:67], v[212:215], v[196:199], v[64:67]
	s_mov_b32 m0, s33
	v_lshl_add_u64 v[216:217], v[220:221], 0, s[8:9]
	s_barrier
	s_waitcnt vmcnt(8)
	ds_read_b128 v[168:171], v149 offset:49152
	ds_read_b128 v[172:175], v149 offset:50176
	ds_read_b128 v[176:179], v149 offset:51200
	ds_read_b128 v[180:183], v149 offset:52224
	ds_read_b128 v[184:187], v149 offset:53248
	ds_read_b128 v[188:191], v149 offset:54272
	ds_read_b128 v[192:195], v149 offset:55296
	ds_read_b128 v[196:199], v149 offset:56320
	global_load_lds_dwordx4 v[216:217], off
	v_lshl_add_u64 v[216:217], v[222:223], 0, s[8:9]
	s_mov_b32 m0, s40
	s_nop 0
	global_load_lds_dwordx4 v[216:217], off
	s_barrier
	s_waitcnt lgkmcnt(0)
	s_waitcnt lgkmcnt(0)
	v_mfma_f32_16x16x32_bf16 v[60:63], v[152:155], v[168:171], v[60:63]
	v_mfma_f32_16x16x32_bf16 v[56:59], v[160:163], v[168:171], v[56:59]
	v_mfma_f32_16x16x32_bf16 v[44:47], v[152:155], v[176:179], v[44:47]
	v_mfma_f32_16x16x32_bf16 v[40:43], v[160:163], v[176:179], v[40:43]
	v_mfma_f32_16x16x32_bf16 v[28:31], v[152:155], v[184:187], v[28:31]
	v_mfma_f32_16x16x32_bf16 v[24:27], v[160:163], v[184:187], v[24:27]
	v_mfma_f32_16x16x32_bf16 v[12:15], v[152:155], v[192:195], v[12:15]
	v_mfma_f32_16x16x32_bf16 v[8:11], v[160:163], v[192:195], v[8:11]
	v_mfma_f32_16x16x32_bf16 v[60:63], v[156:159], v[172:175], v[60:63]
	v_mfma_f32_16x16x32_bf16 v[56:59], v[164:167], v[172:175], v[56:59]
	v_mfma_f32_16x16x32_bf16 v[44:47], v[156:159], v[180:183], v[44:47]
	v_mfma_f32_16x16x32_bf16 v[40:43], v[164:167], v[180:183], v[40:43]
	v_mfma_f32_16x16x32_bf16 v[28:31], v[156:159], v[188:191], v[28:31]
	v_mfma_f32_16x16x32_bf16 v[24:27], v[164:167], v[188:191], v[24:27]
	v_mfma_f32_16x16x32_bf16 v[12:15], v[156:159], v[196:199], v[12:15]
	v_mfma_f32_16x16x32_bf16 v[8:11], v[164:167], v[196:199], v[8:11]
	s_barrier
	s_add_u32 s4, s50, 0x80080
	s_addc_u32 s5, s51, 0
	s_add_i32 s42, s43, s21
	v_lshl_add_u64 v[152:153], s[4:5], 0, v[134:135]
	s_mov_b32 m0, s42
	s_nop 0
	global_load_lds_dwordx4 v[152:153], off
	v_lshl_add_u64 v[152:153], s[4:5], 0, v[130:131]
	s_add_i32 m0, s42, 0x2000
	s_nop 0
	global_load_lds_dwordx4 v[152:153], off
	ds_read_b128 v[152:155], v148
	ds_read_b128 v[156:159], v148 offset:1024
	ds_read_b128 v[160:163], v148 offset:2048
	ds_read_b128 v[164:167], v148 offset:3072
	s_waitcnt vmcnt(6)
	s_barrier
	v_mfma_f32_16x16x32_bf16 v[52:55], v[200:203], v[168:171], v[52:55]
	v_mfma_f32_16x16x32_bf16 v[48:51], v[208:211], v[168:171], v[48:51]
	v_mfma_f32_16x16x32_bf16 v[36:39], v[200:203], v[176:179], v[36:39]
	v_mfma_f32_16x16x32_bf16 v[32:35], v[208:211], v[176:179], v[32:35]
	v_mfma_f32_16x16x32_bf16 v[20:23], v[200:203], v[184:187], v[20:23]
	v_mfma_f32_16x16x32_bf16 v[16:19], v[208:211], v[184:187], v[16:19]
	v_mfma_f32_16x16x32_bf16 v[4:7], v[200:203], v[192:195], v[4:7]
	v_mfma_f32_16x16x32_bf16 v[0:3], v[208:211], v[192:195], v[0:3]
	v_mfma_f32_16x16x32_bf16 v[52:55], v[204:207], v[172:175], v[52:55]
	v_mfma_f32_16x16x32_bf16 v[48:51], v[212:215], v[172:175], v[48:51]
	v_mfma_f32_16x16x32_bf16 v[36:39], v[204:207], v[180:183], v[36:39]
	v_mfma_f32_16x16x32_bf16 v[32:35], v[212:215], v[180:183], v[32:35]
	v_mfma_f32_16x16x32_bf16 v[20:23], v[204:207], v[188:191], v[20:23]
	v_mfma_f32_16x16x32_bf16 v[16:19], v[212:215], v[188:191], v[16:19]
	v_mfma_f32_16x16x32_bf16 v[4:7], v[204:207], v[196:199], v[4:7]
	v_mfma_f32_16x16x32_bf16 v[0:3], v[212:215], v[196:199], v[0:3]
	s_add_i32 s64, s64, 2
	s_add_u32 s60, s60, 0x100
	s_addc_u32 s61, s61, 0
	s_add_u32 s36, s36, 0x100
	s_addc_u32 s37, s37, 0
	s_cmp_gt_u32 s64, 29
	s_barrier
	s_cbranch_scc0 .LBB0_986
	v_mul_f32_e32 v152, 0xbfb8aa3b, v124
	v_exp_f32_e32 v153, v152
	v_mul_f32_e32 v152, 0xbfb8aa3b, v120
	v_exp_f32_e32 v154, v152
	v_lshl_or_b32 v152, s53, 7, v147
	v_add_f32_e32 v153, 1.0, v153
	v_rcp_f32_e32 v155, v153
	v_add_f32_e32 v153, 1.0, v154
	v_rcp_f32_e32 v154, v153
	v_lshl_add_u32 v151, s18, 8, v129
	v_mul_f32_e32 v124, v124, v155
	v_mul_f32_e32 v116, v124, v116
	v_mul_f32_e32 v124, 0xbfb8aa3b, v125
	v_mul_f32_e32 v120, v120, v154
	v_exp_f32_e32 v124, v124
	v_mul_f32_e32 v154, 0xbfb8aa3b, v121
	v_exp_f32_e32 v154, v154
	v_mul_f32_e32 v112, v120, v112
	v_add_f32_e32 v120, 1.0, v124
	v_rcp_f32_e32 v120, v120
	v_add_f32_e32 v124, 1.0, v154
	v_mul_f32_e32 v154, 0xbfb8aa3b, v126
	v_rcp_f32_e32 v124, v124
	v_exp_f32_e32 v154, v154
	v_mul_f32_e32 v120, v125, v120
	v_mul_f32_e32 v117, v120, v117
	v_mul_f32_e32 v120, v121, v124
	v_add_f32_e32 v121, 1.0, v154
	v_rcp_f32_e32 v121, v121
	v_mul_f32_e32 v124, 0xbfb8aa3b, v122
	v_exp_f32_e32 v124, v124
	v_mul_f32_e32 v113, v120, v113
	v_mul_f32_e32 v120, v126, v121
	v_mul_f32_e32 v121, 0xbfb8aa3b, v127
	v_mul_f32_e32 v118, v120, v118
	v_add_f32_e32 v120, 1.0, v124
	v_exp_f32_e32 v121, v121
	v_mul_f32_e32 v124, 0xbfb8aa3b, v123
	v_rcp_f32_e32 v120, v120
	v_exp_f32_e32 v124, v124
	v_add_f32_e32 v121, 1.0, v121
	v_rcp_f32_e32 v121, v121
	v_mul_f32_e32 v120, v122, v120
	v_add_f32_e32 v122, 1.0, v124
	v_rcp_f32_e32 v122, v122
	v_mul_f32_e32 v114, v120, v114
	v_mul_f32_e32 v120, v127, v121
	v_mul_f32_e32 v119, v120, v119
	v_mul_f32_e32 v120, v123, v122
	v_mul_f32_e32 v122, 0xbfb8aa3b, v108
	v_exp_f32_e32 v122, v122
	v_mul_f32_e32 v123, 0xbfb8aa3b, v104
	v_exp_f32_e32 v123, v123
	v_ashrrev_i32_e32 v153, 31, v152
	v_add_f32_e32 v122, 1.0, v122
	v_rcp_f32_e32 v122, v122
	v_mul_f32_e32 v115, v120, v115
	s_nop 1
	v_cvt_pk_bf16_f32 v116, v116, v117
	s_nop 1
	v_cvt_pk_bf16_f32 v117, v118, v119
	s_nop 1
	v_cvt_pk_bf16_f32 v118, v112, v113
	v_mov_b64_e32 v[112:113], s[48:49]
	s_nop 1
	v_cvt_pk_bf16_f32 v119, v114, v115
	v_mad_i64_i32 v[120:121], s[0:1], v151, s47, v[112:113]
	v_lshlrev_b64 v[114:115], 1, v[152:153]
	v_add_f32_e32 v123, 1.0, v123
	v_mul_f32_e32 v108, v108, v122
	v_lshl_add_u64 v[120:121], v[120:121], 0, v[114:115]
	v_rcp_f32_e32 v123, v123
	v_mul_f32_e32 v100, v108, v100
	v_mul_f32_e32 v108, 0xbfb8aa3b, v109
	global_store_dwordx4 v[120:121], v[116:119], off
	v_exp_f32_e32 v108, v108
	v_mul_f32_e32 v104, v104, v123
	v_mul_f32_e32 v116, 0xbfb8aa3b, v105
	v_exp_f32_e32 v116, v116
	v_mul_f32_e32 v104, v104, v96
	v_add_f32_e32 v96, 1.0, v108
	v_rcp_f32_e32 v96, v96
	v_add_f32_e32 v108, 1.0, v116
	v_mul_f32_e32 v116, 0xbfb8aa3b, v110
	v_rcp_f32_e32 v108, v108
	v_exp_f32_e32 v116, v116
	v_mul_f32_e32 v96, v109, v96
	v_mul_f32_e32 v96, v96, v101
	v_mul_f32_e32 v101, v105, v108
	v_add_f32_e32 v105, 1.0, v116
	v_rcp_f32_e32 v105, v105
	v_mul_f32_e32 v108, 0xbfb8aa3b, v106
	v_exp_f32_e32 v108, v108
	v_mul_f32_e32 v101, v101, v97
	v_mul_f32_e32 v97, v110, v105
	v_mul_f32_e32 v105, 0xbfb8aa3b, v111
	v_mul_f32_e32 v97, v97, v102
	v_add_f32_e32 v102, 1.0, v108
	v_exp_f32_e32 v105, v105
	v_mul_f32_e32 v108, 0xbfb8aa3b, v107
	v_rcp_f32_e32 v102, v102
	v_exp_f32_e32 v108, v108
	v_add_f32_e32 v105, 1.0, v105
	v_rcp_f32_e32 v105, v105
	v_mul_f32_e32 v102, v106, v102
	v_add_f32_e32 v106, 1.0, v108
	v_rcp_f32_e32 v106, v106
	v_mul_f32_e32 v102, v102, v98
	v_mul_f32_e32 v98, v111, v105
	v_mul_f32_e32 v98, v98, v103
	v_mul_f32_e32 v103, v107, v106
	v_mul_f32_e32 v99, v103, v99
	s_nop 1
	v_cvt_pk_bf16_f32 v96, v100, v96
	s_nop 1
	v_cvt_pk_bf16_f32 v97, v97, v98
	s_nop 1
	v_cvt_pk_bf16_f32 v98, v104, v101
	s_nop 1
	v_cvt_pk_bf16_f32 v99, v102, v99
	v_mul_f32_e32 v102, 0xbfb8aa3b, v92
	v_exp_f32_e32 v102, v102
	v_mul_f32_e32 v103, 0xbfb8aa3b, v88
	v_exp_f32_e32 v103, v103
	v_or_b32_e32 v100, 16, v151
	v_add_f32_e32 v102, 1.0, v102
	v_rcp_f32_e32 v102, v102
	v_mad_i64_i32 v[100:101], s[0:1], v100, s47, v[112:113]
	v_add_f32_e32 v103, 1.0, v103
	v_mul_f32_e32 v92, v92, v102
	v_lshl_add_u64 v[100:101], v[100:101], 0, v[114:115]
	v_rcp_f32_e32 v103, v103
	v_mul_f32_e32 v84, v92, v84
	v_mul_f32_e32 v92, 0xbfb8aa3b, v93
	global_store_dwordx4 v[100:101], v[96:99], off
	v_exp_f32_e32 v92, v92
	v_mul_f32_e32 v88, v88, v103
	v_mul_f32_e32 v96, 0xbfb8aa3b, v89
	v_exp_f32_e32 v96, v96
	v_mul_f32_e32 v88, v88, v80
	v_add_f32_e32 v80, 1.0, v92
	v_rcp_f32_e32 v80, v80
	v_add_f32_e32 v92, 1.0, v96
	v_mul_f32_e32 v96, 0xbfb8aa3b, v94
	v_rcp_f32_e32 v92, v92
	v_exp_f32_e32 v96, v96
	v_mul_f32_e32 v80, v93, v80
	v_mul_f32_e32 v80, v80, v85
	v_mul_f32_e32 v85, v89, v92
	v_add_f32_e32 v89, 1.0, v96
	v_rcp_f32_e32 v89, v89
	v_mul_f32_e32 v92, 0xbfb8aa3b, v90
	v_exp_f32_e32 v92, v92
	v_mul_f32_e32 v85, v85, v81
	v_mul_f32_e32 v81, v94, v89
	v_mul_f32_e32 v89, 0xbfb8aa3b, v95
	v_mul_f32_e32 v81, v81, v86
	v_add_f32_e32 v86, 1.0, v92
	v_exp_f32_e32 v89, v89
	v_mul_f32_e32 v92, 0xbfb8aa3b, v91
	v_rcp_f32_e32 v86, v86
	v_exp_f32_e32 v92, v92
	v_add_f32_e32 v89, 1.0, v89
	v_rcp_f32_e32 v89, v89
	v_mul_f32_e32 v86, v90, v86
	v_add_f32_e32 v90, 1.0, v92
	v_rcp_f32_e32 v90, v90
	v_mul_f32_e32 v86, v86, v82
	v_mul_f32_e32 v82, v95, v89
	v_mul_f32_e32 v82, v82, v87
	v_mul_f32_e32 v87, v91, v90
	v_mul_f32_e32 v83, v87, v83
	s_nop 1
	v_cvt_pk_bf16_f32 v80, v84, v80
	s_nop 1
	v_cvt_pk_bf16_f32 v81, v81, v82
	s_nop 1
	v_cvt_pk_bf16_f32 v82, v88, v85
	s_nop 1
	v_cvt_pk_bf16_f32 v83, v86, v83
	v_mul_f32_e32 v86, 0xbfb8aa3b, v76
	v_exp_f32_e32 v86, v86
	v_mul_f32_e32 v87, 0xbfb8aa3b, v72
	v_exp_f32_e32 v87, v87
	v_or_b32_e32 v84, 32, v151
	v_add_f32_e32 v86, 1.0, v86
	v_rcp_f32_e32 v86, v86
	v_mad_i64_i32 v[84:85], s[0:1], v84, s47, v[112:113]
	v_add_f32_e32 v87, 1.0, v87
	v_mul_f32_e32 v76, v76, v86
	v_lshl_add_u64 v[84:85], v[84:85], 0, v[114:115]
	v_rcp_f32_e32 v87, v87
	v_mul_f32_e32 v68, v76, v68
	v_mul_f32_e32 v76, 0xbfb8aa3b, v77
	global_store_dwordx4 v[84:85], v[80:83], off
	v_exp_f32_e32 v76, v76
	v_mul_f32_e32 v72, v72, v87
	v_mul_f32_e32 v80, 0xbfb8aa3b, v73
	v_exp_f32_e32 v80, v80
	v_mul_f32_e32 v72, v72, v64
	v_add_f32_e32 v64, 1.0, v76
	v_rcp_f32_e32 v64, v64
	v_add_f32_e32 v76, 1.0, v80
	v_mul_f32_e32 v80, 0xbfb8aa3b, v78
	v_rcp_f32_e32 v76, v76
	v_exp_f32_e32 v80, v80
	v_mul_f32_e32 v64, v77, v64
	v_mul_f32_e32 v64, v64, v69
	v_mul_f32_e32 v69, v73, v76
	v_add_f32_e32 v73, 1.0, v80
	v_rcp_f32_e32 v73, v73
	v_mul_f32_e32 v76, 0xbfb8aa3b, v74
	v_exp_f32_e32 v76, v76
	v_mul_f32_e32 v69, v69, v65
	v_mul_f32_e32 v65, v78, v73
	v_mul_f32_e32 v73, 0xbfb8aa3b, v79
	v_mul_f32_e32 v65, v65, v70
	v_add_f32_e32 v70, 1.0, v76
	v_exp_f32_e32 v73, v73
	v_mul_f32_e32 v76, 0xbfb8aa3b, v75
	v_rcp_f32_e32 v70, v70
	v_exp_f32_e32 v76, v76
	v_add_f32_e32 v73, 1.0, v73
	v_rcp_f32_e32 v73, v73
	v_mul_f32_e32 v70, v74, v70
	v_add_f32_e32 v74, 1.0, v76
	v_rcp_f32_e32 v74, v74
	v_mul_f32_e32 v70, v70, v66
	v_mul_f32_e32 v66, v79, v73
	v_mul_f32_e32 v66, v66, v71
	v_mul_f32_e32 v71, v75, v74
	v_mul_f32_e32 v67, v71, v67
	s_nop 1
	v_cvt_pk_bf16_f32 v64, v68, v64
	s_nop 1
	v_cvt_pk_bf16_f32 v65, v65, v66
	s_nop 1
	v_cvt_pk_bf16_f32 v66, v72, v69
	s_nop 1
	v_cvt_pk_bf16_f32 v67, v70, v67
	v_mul_f32_e32 v70, 0xbfb8aa3b, v60
	v_exp_f32_e32 v70, v70
	v_or_b32_e32 v68, 48, v151
	v_mad_i64_i32 v[68:69], s[0:1], v68, s47, v[112:113]
	v_lshl_add_u64 v[68:69], v[68:69], 0, v[114:115]
	v_mul_f32_e32 v71, 0xbfb8aa3b, v56
	global_store_dwordx4 v[68:69], v[64:67], off
	v_exp_f32_e32 v71, v71
	s_and_b64 vcc, exec, s[6:7]
	v_add_f32_e32 v64, 1.0, v70
	v_rcp_f32_e32 v64, v64
	v_add_f32_e32 v65, 1.0, v71
	v_rcp_f32_e32 v65, v65
	v_add_u32_e32 v66, 0x80, v151
	v_mul_f32_e32 v60, v60, v64
	v_mul_f32_e32 v52, v60, v52
	v_mul_f32_e32 v60, 0xbfb8aa3b, v61
	v_exp_f32_e32 v60, v60
	v_mul_f32_e32 v64, 0xbfb8aa3b, v57
	v_exp_f32_e32 v64, v64
	v_mul_f32_e32 v56, v56, v65
	v_mul_f32_e32 v56, v56, v48
	v_add_f32_e32 v48, 1.0, v60
	v_rcp_f32_e32 v48, v48
	v_add_f32_e32 v60, 1.0, v64
	v_mul_f32_e32 v64, 0xbfb8aa3b, v62
	v_rcp_f32_e32 v60, v60
	v_exp_f32_e32 v64, v64
	v_mul_f32_e32 v48, v61, v48
	v_mul_f32_e32 v48, v48, v53
	v_mul_f32_e32 v53, v57, v60
	v_add_f32_e32 v57, 1.0, v64
	v_rcp_f32_e32 v57, v57
	v_mul_f32_e32 v60, 0xbfb8aa3b, v58
	v_exp_f32_e32 v60, v60
	v_mul_f32_e32 v53, v53, v49
	v_mul_f32_e32 v49, v62, v57
	v_mul_f32_e32 v57, 0xbfb8aa3b, v63
	v_mul_f32_e32 v49, v49, v54
	v_add_f32_e32 v54, 1.0, v60
	v_exp_f32_e32 v57, v57
	v_mul_f32_e32 v60, 0xbfb8aa3b, v59
	v_rcp_f32_e32 v54, v54
	v_exp_f32_e32 v60, v60
	v_add_f32_e32 v57, 1.0, v57
	v_rcp_f32_e32 v57, v57
	v_mul_f32_e32 v54, v58, v54
	v_add_f32_e32 v58, 1.0, v60
	v_rcp_f32_e32 v58, v58
	v_mul_f32_e32 v54, v54, v50
	v_mul_f32_e32 v50, v63, v57
	v_mul_f32_e32 v50, v50, v55
	v_mul_f32_e32 v55, v59, v58
	v_mul_f32_e32 v51, v55, v51
	s_nop 1
	v_cvt_pk_bf16_f32 v48, v52, v48
	s_nop 1
	v_cvt_pk_bf16_f32 v49, v49, v50
	s_nop 1
	v_cvt_pk_bf16_f32 v50, v56, v53
	s_nop 1
	v_cvt_pk_bf16_f32 v51, v54, v51
	v_mul_f32_e32 v54, 0xbfb8aa3b, v44
	v_exp_f32_e32 v54, v54
	v_mul_f32_e32 v55, 0xbfb8aa3b, v40
	v_exp_f32_e32 v55, v55
	v_mad_i64_i32 v[52:53], s[0:1], v66, s47, v[112:113]
	v_add_f32_e32 v54, 1.0, v54
	v_rcp_f32_e32 v54, v54
	v_add_f32_e32 v55, 1.0, v55
	v_lshl_add_u64 v[52:53], v[52:53], 0, v[114:115]
	v_rcp_f32_e32 v55, v55
	v_mul_f32_e32 v44, v44, v54
	v_mul_f32_e32 v36, v44, v36
	v_mul_f32_e32 v44, 0xbfb8aa3b, v45
	global_store_dwordx4 v[52:53], v[48:51], off
	v_exp_f32_e32 v44, v44
	v_mul_f32_e32 v40, v40, v55
	v_mul_f32_e32 v48, 0xbfb8aa3b, v41
	v_exp_f32_e32 v48, v48
	v_mul_f32_e32 v40, v40, v32
	v_add_f32_e32 v32, 1.0, v44
	v_rcp_f32_e32 v32, v32
	v_add_f32_e32 v44, 1.0, v48
	v_mul_f32_e32 v48, 0xbfb8aa3b, v46
	v_rcp_f32_e32 v44, v44
	v_exp_f32_e32 v48, v48
	v_mul_f32_e32 v32, v45, v32
	v_mul_f32_e32 v32, v32, v37
	v_mul_f32_e32 v37, v41, v44
	v_add_f32_e32 v41, 1.0, v48
	v_rcp_f32_e32 v41, v41
	v_mul_f32_e32 v44, 0xbfb8aa3b, v42
	v_exp_f32_e32 v44, v44
	v_mul_f32_e32 v37, v37, v33
	v_mul_f32_e32 v33, v46, v41
	v_mul_f32_e32 v41, 0xbfb8aa3b, v47
	v_mul_f32_e32 v33, v33, v38
	v_add_f32_e32 v38, 1.0, v44
	v_exp_f32_e32 v41, v41
	v_mul_f32_e32 v44, 0xbfb8aa3b, v43
	v_rcp_f32_e32 v38, v38
	v_exp_f32_e32 v44, v44
	v_add_f32_e32 v41, 1.0, v41
	v_rcp_f32_e32 v41, v41
	v_mul_f32_e32 v38, v42, v38
	v_add_f32_e32 v42, 1.0, v44
	v_rcp_f32_e32 v42, v42
	v_mul_f32_e32 v38, v38, v34
	v_mul_f32_e32 v34, v47, v41
	v_mul_f32_e32 v34, v34, v39
	v_mul_f32_e32 v39, v43, v42
	v_mul_f32_e32 v35, v39, v35
	s_nop 1
	v_cvt_pk_bf16_f32 v32, v36, v32
	s_nop 1
	v_cvt_pk_bf16_f32 v33, v33, v34
	s_nop 1
	v_cvt_pk_bf16_f32 v34, v40, v37
	s_nop 1
	v_cvt_pk_bf16_f32 v35, v38, v35
	v_mul_f32_e32 v38, 0xbfb8aa3b, v28
	v_exp_f32_e32 v38, v38
	v_mul_f32_e32 v39, 0xbfb8aa3b, v24
	v_exp_f32_e32 v39, v39
	v_add_u32_e32 v36, 0x90, v151
	v_add_f32_e32 v38, 1.0, v38
	v_rcp_f32_e32 v38, v38
	v_mad_i64_i32 v[36:37], s[0:1], v36, s47, v[112:113]
	v_add_f32_e32 v39, 1.0, v39
	v_mul_f32_e32 v28, v28, v38
	v_lshl_add_u64 v[36:37], v[36:37], 0, v[114:115]
	v_rcp_f32_e32 v39, v39
	v_mul_f32_e32 v20, v28, v20
	v_mul_f32_e32 v28, 0xbfb8aa3b, v29
	global_store_dwordx4 v[36:37], v[32:35], off
	v_exp_f32_e32 v28, v28
	v_mul_f32_e32 v24, v24, v39
	v_mul_f32_e32 v32, 0xbfb8aa3b, v25
	v_exp_f32_e32 v32, v32
	v_mul_f32_e32 v24, v24, v16
	v_add_f32_e32 v16, 1.0, v28
	v_rcp_f32_e32 v16, v16
	v_add_f32_e32 v28, 1.0, v32
	v_mul_f32_e32 v32, 0xbfb8aa3b, v30
	v_rcp_f32_e32 v28, v28
	v_exp_f32_e32 v32, v32
	v_mul_f32_e32 v16, v29, v16
	v_mul_f32_e32 v16, v16, v21
	v_mul_f32_e32 v21, v25, v28
	v_add_f32_e32 v25, 1.0, v32
	v_rcp_f32_e32 v25, v25
	v_mul_f32_e32 v28, 0xbfb8aa3b, v26
	v_exp_f32_e32 v28, v28
	v_mul_f32_e32 v21, v21, v17
	v_mul_f32_e32 v17, v30, v25
	v_mul_f32_e32 v25, 0xbfb8aa3b, v31
	v_mul_f32_e32 v17, v17, v22
	v_add_f32_e32 v22, 1.0, v28
	v_exp_f32_e32 v25, v25
	v_mul_f32_e32 v28, 0xbfb8aa3b, v27
	v_rcp_f32_e32 v22, v22
	v_exp_f32_e32 v28, v28
	v_add_f32_e32 v25, 1.0, v25
	v_rcp_f32_e32 v25, v25
	v_mul_f32_e32 v22, v26, v22
	v_add_f32_e32 v26, 1.0, v28
	v_rcp_f32_e32 v26, v26
	v_mul_f32_e32 v22, v22, v18
	v_mul_f32_e32 v18, v31, v25
	v_mul_f32_e32 v18, v18, v23
	v_mul_f32_e32 v23, v27, v26
	v_mul_f32_e32 v19, v23, v19
	s_nop 1
	v_cvt_pk_bf16_f32 v16, v20, v16
	s_nop 1
	v_cvt_pk_bf16_f32 v17, v17, v18
	s_nop 1
	v_cvt_pk_bf16_f32 v18, v24, v21
	s_nop 1
	v_cvt_pk_bf16_f32 v19, v22, v19
	v_mul_f32_e32 v22, 0xbfb8aa3b, v12
	v_exp_f32_e32 v22, v22
	v_mul_f32_e32 v23, 0xbfb8aa3b, v8
	v_exp_f32_e32 v23, v23
	v_add_u32_e32 v20, 0xa0, v151
	v_add_f32_e32 v22, 1.0, v22
	v_rcp_f32_e32 v22, v22
	v_mad_i64_i32 v[20:21], s[0:1], v20, s47, v[112:113]
	v_add_f32_e32 v23, 1.0, v23
	v_mul_f32_e32 v12, v12, v22
	v_lshl_add_u64 v[20:21], v[20:21], 0, v[114:115]
	v_rcp_f32_e32 v23, v23
	v_mul_f32_e32 v4, v12, v4
	v_mul_f32_e32 v12, 0xbfb8aa3b, v13
	global_store_dwordx4 v[20:21], v[16:19], off
	v_exp_f32_e32 v12, v12
	v_mul_f32_e32 v8, v8, v23
	v_mul_f32_e32 v16, 0xbfb8aa3b, v9
	v_exp_f32_e32 v16, v16
	v_mul_f32_e32 v8, v8, v0
	v_add_f32_e32 v0, 1.0, v12
	v_rcp_f32_e32 v0, v0
	v_add_f32_e32 v12, 1.0, v16
	v_mul_f32_e32 v16, 0xbfb8aa3b, v14
	v_rcp_f32_e32 v12, v12
	v_exp_f32_e32 v16, v16
	v_mul_f32_e32 v0, v13, v0
	v_mul_f32_e32 v0, v0, v5
	v_mul_f32_e32 v5, v9, v12
	v_add_f32_e32 v9, 1.0, v16
	v_rcp_f32_e32 v9, v9
	v_mul_f32_e32 v12, 0xbfb8aa3b, v10
	v_exp_f32_e32 v12, v12
	v_mul_f32_e32 v5, v5, v1
	v_mul_f32_e32 v1, v14, v9
	v_mul_f32_e32 v9, 0xbfb8aa3b, v15
	v_exp_f32_e32 v9, v9
	v_mul_f32_e32 v1, v1, v6
	v_add_f32_e32 v6, 1.0, v12
	v_mul_f32_e32 v12, 0xbfb8aa3b, v11
	v_rcp_f32_e32 v6, v6
	v_exp_f32_e32 v12, v12
	v_add_f32_e32 v9, 1.0, v9
	v_rcp_f32_e32 v9, v9
	v_mul_f32_e32 v6, v10, v6
	v_add_f32_e32 v10, 1.0, v12
	v_rcp_f32_e32 v10, v10
	v_mul_f32_e32 v6, v6, v2
	v_mul_f32_e32 v2, v15, v9
	v_mul_f32_e32 v2, v2, v7
	s_nop 1
	v_cvt_pk_bf16_f32 v0, v4, v0
	v_add_u32_e32 v4, 0xb0, v151
	v_mul_f32_e32 v7, v11, v10
	s_nop 1
	v_cvt_pk_bf16_f32 v1, v1, v2
	s_nop 1
	v_cvt_pk_bf16_f32 v2, v8, v5
	v_mad_i64_i32 v[4:5], s[0:1], v4, s47, v[112:113]
	v_mul_f32_e32 v3, v7, v3
	v_lshl_add_u64 v[4:5], v[4:5], 0, v[114:115]
	s_mov_b32 s53, s10
	s_mov_b32 s18, s12
	s_mov_b64 s[50:51], s[16:17]
	s_mov_b64 s[36:37], s[14:15]
	s_nop 1
	v_cvt_pk_bf16_f32 v3, v6, v3
	global_store_dwordx4 v[4:5], v[0:3], off
	s_cbranch_vccz .LBB0_983
	s_waitcnt vmcnt(0)
	s_cmpk_gt_u32 s20, 0xff
	s_cbranch_scc1 .LBB0_990
	s_barrier

.LBB0_1097:
	s_add_u32 s0, s64, 0x100
	v_mov_b32_e32 v0, 0
	s_addc_u32 s1, s65, 0
	s_mov_b32 s76, -2
	v_mov_b32_e32 v1, v0
	v_mov_b32_e32 v2, v0
	v_mov_b32_e32 v3, v0
	v_mov_b32_e32 v16, v0
	v_mov_b32_e32 v17, v0
	v_mov_b32_e32 v18, v0
	v_mov_b32_e32 v19, v0
	v_mov_b32_e32 v4, v0
	v_mov_b32_e32 v5, v0
	v_mov_b32_e32 v6, v0
	v_mov_b32_e32 v7, v0
	v_mov_b32_e32 v20, v0
	v_mov_b32_e32 v21, v0
	v_mov_b32_e32 v22, v0
	v_mov_b32_e32 v23, v0
	v_mov_b32_e32 v8, v0
	v_mov_b32_e32 v9, v0
	v_mov_b32_e32 v10, v0
	v_mov_b32_e32 v11, v0
	v_mov_b32_e32 v24, v0
	v_mov_b32_e32 v25, v0
	v_mov_b32_e32 v26, v0
	v_mov_b32_e32 v27, v0
	v_mov_b32_e32 v12, v0
	v_mov_b32_e32 v13, v0
	v_mov_b32_e32 v14, v0
	v_mov_b32_e32 v15, v0
	v_mov_b32_e32 v32, v0
	v_mov_b32_e32 v33, v0
	v_mov_b32_e32 v34, v0
	v_mov_b32_e32 v35, v0
	v_mov_b32_e32 v52, v0
	v_mov_b32_e32 v53, v0
	v_mov_b32_e32 v54, v0
	v_mov_b32_e32 v55, v0
	v_mov_b32_e32 v80, v0
	v_mov_b32_e32 v81, v0
	v_mov_b32_e32 v82, v0
	v_mov_b32_e32 v83, v0
	v_mov_b32_e32 v60, v0
	v_mov_b32_e32 v61, v0
	v_mov_b32_e32 v62, v0
	v_mov_b32_e32 v63, v0
	v_mov_b32_e32 v88, v0
	v_mov_b32_e32 v89, v0
	v_mov_b32_e32 v90, v0
	v_mov_b32_e32 v91, v0
	v_mov_b32_e32 v68, v0
	v_mov_b32_e32 v69, v0
	v_mov_b32_e32 v70, v0
	v_mov_b32_e32 v71, v0
	v_mov_b32_e32 v104, v0
	v_mov_b32_e32 v105, v0
	v_mov_b32_e32 v106, v0
	v_mov_b32_e32 v107, v0
	v_mov_b32_e32 v76, v0
	v_mov_b32_e32 v77, v0
	v_mov_b32_e32 v78, v0
	v_mov_b32_e32 v79, v0
	v_mov_b32_e32 v108, v0
	v_mov_b32_e32 v109, v0
	v_mov_b32_e32 v110, v0
	v_mov_b32_e32 v111, v0
	v_mov_b32_e32 v28, v0
	v_mov_b32_e32 v29, v0
	v_mov_b32_e32 v30, v0
	v_mov_b32_e32 v31, v0
	v_mov_b32_e32 v48, v0
	v_mov_b32_e32 v49, v0
	v_mov_b32_e32 v50, v0
	v_mov_b32_e32 v51, v0
	v_mov_b32_e32 v36, v0
	v_mov_b32_e32 v37, v0
	v_mov_b32_e32 v38, v0
	v_mov_b32_e32 v39, v0
	v_mov_b32_e32 v56, v0
	v_mov_b32_e32 v57, v0
	v_mov_b32_e32 v58, v0
	v_mov_b32_e32 v59, v0
	v_mov_b32_e32 v40, v0
	v_mov_b32_e32 v41, v0
	v_mov_b32_e32 v42, v0
	v_mov_b32_e32 v43, v0
	v_mov_b32_e32 v64, v0
	v_mov_b32_e32 v65, v0
	v_mov_b32_e32 v66, v0
	v_mov_b32_e32 v67, v0
	v_mov_b32_e32 v44, v0
	v_mov_b32_e32 v45, v0
	v_mov_b32_e32 v46, v0
	v_mov_b32_e32 v47, v0
	v_mov_b32_e32 v72, v0
	v_mov_b32_e32 v73, v0
	v_mov_b32_e32 v74, v0
	v_mov_b32_e32 v75, v0
	v_mov_b32_e32 v84, v0
	v_mov_b32_e32 v85, v0
	v_mov_b32_e32 v86, v0
	v_mov_b32_e32 v87, v0
	v_mov_b32_e32 v112, v0
	v_mov_b32_e32 v113, v0
	v_mov_b32_e32 v114, v0
	v_mov_b32_e32 v115, v0
	v_mov_b32_e32 v92, v0
	v_mov_b32_e32 v93, v0
	v_mov_b32_e32 v94, v0
	v_mov_b32_e32 v95, v0
	v_mov_b32_e32 v116, v0
	v_mov_b32_e32 v117, v0
	v_mov_b32_e32 v118, v0
	v_mov_b32_e32 v119, v0
	v_mov_b32_e32 v96, v0
	v_mov_b32_e32 v97, v0
	v_mov_b32_e32 v98, v0
	v_mov_b32_e32 v99, v0
	v_mov_b32_e32 v120, v0
	v_mov_b32_e32 v121, v0
	v_mov_b32_e32 v122, v0
	v_mov_b32_e32 v123, v0
	v_mov_b32_e32 v100, v0
	v_mov_b32_e32 v101, v0
	v_mov_b32_e32 v102, v0
	v_mov_b32_e32 v103, v0
	v_mov_b32_e32 v124, v0
	v_mov_b32_e32 v125, v0
	v_mov_b32_e32 v126, v0
	v_mov_b32_e32 v127, v0
	ds_read_b128 v[128:131], v221
	ds_read_b128 v[132:135], v221 offset:1024
	ds_read_b128 v[136:139], v221 offset:2048
	ds_read_b128 v[140:143], v221 offset:3072
.LBB0_1098:
	s_add_u32 s64, s62, 0x100
	s_addc_u32 s65, s63, 0
	s_cmpk_eq_i32 s76, 0x54
	s_cselect_b32 s5, s9, s65
	s_cselect_b32 s4, s8, s64
	s_cselect_b32 s67, s11, s1
	s_cselect_b32 s66, s10, s0
	v_lshl_add_u64 v[188:189], s[62:63], 0, v[168:169]
	s_add_i32 m0, s25, 0xc000
	ds_read_b128 v[144:147], v222
	ds_read_b128 v[148:151], v222 offset:1024
	ds_read_b128 v[152:155], v222 offset:2048
	ds_read_b128 v[156:159], v222 offset:3072
	ds_read_b128 v[160:163], v222 offset:4096
	ds_read_b128 v[176:179], v222 offset:5120
	ds_read_b128 v[180:183], v222 offset:6144
	ds_read_b128 v[184:187], v222 offset:7168
	global_load_lds_dwordx4 v[188:189], off
	v_lshl_add_u64 v[188:189], s[62:63], 0, v[170:171]
	s_add_i32 m0, s25, 0xe000
	s_nop 0
	global_load_lds_dwordx4 v[188:189], off
	s_waitcnt lgkmcnt(8)
	s_barrier
	s_waitcnt lgkmcnt(0)
	s_waitcnt lgkmcnt(0)
	v_mfma_f32_16x16x32_bf16 v[124:127], v[128:131], v[144:147], v[124:127]
	v_mfma_f32_16x16x32_bf16 v[100:103], v[136:139], v[144:147], v[100:103]
	v_mfma_f32_16x16x32_bf16 v[120:123], v[128:131], v[152:155], v[120:123]
	v_mfma_f32_16x16x32_bf16 v[96:99], v[136:139], v[152:155], v[96:99]
	v_mfma_f32_16x16x32_bf16 v[116:119], v[128:131], v[160:163], v[116:119]
	v_mfma_f32_16x16x32_bf16 v[92:95], v[136:139], v[160:163], v[92:95]
	v_mfma_f32_16x16x32_bf16 v[112:115], v[128:131], v[180:183], v[112:115]
	v_mfma_f32_16x16x32_bf16 v[84:87], v[136:139], v[180:183], v[84:87]
	v_mfma_f32_16x16x32_bf16 v[124:127], v[132:135], v[148:151], v[124:127]
	v_mfma_f32_16x16x32_bf16 v[100:103], v[140:143], v[148:151], v[100:103]
	v_mfma_f32_16x16x32_bf16 v[120:123], v[132:135], v[156:159], v[120:123]
	v_mfma_f32_16x16x32_bf16 v[96:99], v[140:143], v[156:159], v[96:99]
	v_mfma_f32_16x16x32_bf16 v[116:119], v[132:135], v[176:179], v[116:119]
	v_mfma_f32_16x16x32_bf16 v[92:95], v[140:143], v[176:179], v[92:95]
	v_mfma_f32_16x16x32_bf16 v[112:115], v[132:135], v[184:187], v[112:115]
	v_mfma_f32_16x16x32_bf16 v[84:87], v[140:143], v[184:187], v[84:87]
	s_barrier
	s_add_i32 s42, s41, s24
	v_lshl_add_u64 v[204:205], s[66:67], 0, v[166:167]
	s_mov_b32 m0, s42
	ds_read_b128 v[188:191], v223
	ds_read_b128 v[192:195], v223 offset:1024
	ds_read_b128 v[196:199], v223 offset:2048
	ds_read_b128 v[200:203], v223 offset:3072
	global_load_lds_dwordx4 v[204:205], off
	v_lshl_add_u64 v[206:207], s[66:67], 0, v[164:165]
	s_add_i32 m0, s42, 0x2000
	s_nop 0
	global_load_lds_dwordx4 v[206:207], off
	s_barrier
	s_waitcnt lgkmcnt(0)
	s_waitcnt lgkmcnt(0)
	v_mfma_f32_16x16x32_bf16 v[72:75], v[188:191], v[144:147], v[72:75]
	v_mfma_f32_16x16x32_bf16 v[44:47], v[196:199], v[144:147], v[44:47]
	v_mfma_f32_16x16x32_bf16 v[64:67], v[188:191], v[152:155], v[64:67]
	v_mfma_f32_16x16x32_bf16 v[40:43], v[196:199], v[152:155], v[40:43]
	v_mfma_f32_16x16x32_bf16 v[56:59], v[188:191], v[160:163], v[56:59]
	v_mfma_f32_16x16x32_bf16 v[36:39], v[196:199], v[160:163], v[36:39]
	v_mfma_f32_16x16x32_bf16 v[48:51], v[188:191], v[180:183], v[48:51]
	v_mfma_f32_16x16x32_bf16 v[28:31], v[196:199], v[180:183], v[28:31]
	v_mfma_f32_16x16x32_bf16 v[72:75], v[192:195], v[148:151], v[72:75]
	v_mfma_f32_16x16x32_bf16 v[44:47], v[200:203], v[148:151], v[44:47]
	v_mfma_f32_16x16x32_bf16 v[64:67], v[192:195], v[156:159], v[64:67]
	v_mfma_f32_16x16x32_bf16 v[40:43], v[200:203], v[156:159], v[40:43]
	v_mfma_f32_16x16x32_bf16 v[56:59], v[192:195], v[176:179], v[56:59]
	v_mfma_f32_16x16x32_bf16 v[36:39], v[200:203], v[176:179], v[36:39]
	v_mfma_f32_16x16x32_bf16 v[48:51], v[192:195], v[184:187], v[48:51]
	v_mfma_f32_16x16x32_bf16 v[28:31], v[200:203], v[184:187], v[28:31]
	s_mov_b32 m0, s25
	v_lshl_add_u64 v[208:209], s[4:5], 0, v[166:167]
	s_barrier
	s_waitcnt vmcnt(8)
	ds_read_b128 v[144:147], v222 offset:16384
	ds_read_b128 v[148:151], v222 offset:17408
	ds_read_b128 v[152:155], v222 offset:18432
	ds_read_b128 v[156:159], v222 offset:19456
	ds_read_b128 v[160:163], v222 offset:20480
	ds_read_b128 v[176:179], v222 offset:21504
	ds_read_b128 v[180:183], v222 offset:22528
	ds_read_b128 v[184:187], v222 offset:23552
	global_load_lds_dwordx4 v[208:209], off
	v_lshl_add_u64 v[210:211], s[4:5], 0, v[164:165]
	s_mov_b32 m0, s28
	s_nop 0
	global_load_lds_dwordx4 v[210:211], off
	s_barrier
	s_waitcnt lgkmcnt(0)
	s_waitcnt lgkmcnt(0)
	v_mfma_f32_16x16x32_bf16 v[108:111], v[128:131], v[144:147], v[108:111]
	v_mfma_f32_16x16x32_bf16 v[76:79], v[136:139], v[144:147], v[76:79]
	v_mfma_f32_16x16x32_bf16 v[104:107], v[128:131], v[152:155], v[104:107]
	v_mfma_f32_16x16x32_bf16 v[68:71], v[136:139], v[152:155], v[68:71]
	v_mfma_f32_16x16x32_bf16 v[88:91], v[128:131], v[160:163], v[88:91]
	v_mfma_f32_16x16x32_bf16 v[60:63], v[136:139], v[160:163], v[60:63]
	v_mfma_f32_16x16x32_bf16 v[80:83], v[128:131], v[180:183], v[80:83]
	v_mfma_f32_16x16x32_bf16 v[52:55], v[136:139], v[180:183], v[52:55]
	v_mfma_f32_16x16x32_bf16 v[108:111], v[132:135], v[148:151], v[108:111]
	v_mfma_f32_16x16x32_bf16 v[76:79], v[140:143], v[148:151], v[76:79]
	v_mfma_f32_16x16x32_bf16 v[104:107], v[132:135], v[156:159], v[104:107]
	v_mfma_f32_16x16x32_bf16 v[68:71], v[140:143], v[156:159], v[68:71]
	v_mfma_f32_16x16x32_bf16 v[88:91], v[132:135], v[176:179], v[88:91]
	v_mfma_f32_16x16x32_bf16 v[60:63], v[140:143], v[176:179], v[60:63]
	v_mfma_f32_16x16x32_bf16 v[80:83], v[132:135], v[184:187], v[80:83]
	v_mfma_f32_16x16x32_bf16 v[52:55], v[140:143], v[184:187], v[52:55]
	s_barrier
	s_add_u32 s42, s66, 0x160000
	s_addc_u32 s43, s67, 0
	s_add_i32 s44, s53, s24
	v_lshl_add_u64 v[128:129], s[42:43], 0, v[166:167]
	s_mov_b32 m0, s44
	s_nop 0
	global_load_lds_dwordx4 v[128:129], off
	v_lshl_add_u64 v[128:129], s[42:43], 0, v[164:165]
	s_add_i32 m0, s44, 0x2000
	s_nop 0
	global_load_lds_dwordx4 v[128:129], off
	v_add_u32_e32 v140, 0x18000, v219
	ds_read_b128 v[128:131], v140
	ds_read_b128 v[132:135], v140 offset:1024
	ds_read_b128 v[136:139], v140 offset:2048
	ds_read_b128 v[140:143], v140 offset:3072
	s_waitcnt vmcnt(6)
	s_barrier
	v_mfma_f32_16x16x32_bf16 v[32:35], v[188:191], v[144:147], v[32:35]
	v_mfma_f32_16x16x32_bf16 v[12:15], v[196:199], v[144:147], v[12:15]
	v_mfma_f32_16x16x32_bf16 v[24:27], v[188:191], v[152:155], v[24:27]
	v_mfma_f32_16x16x32_bf16 v[8:11], v[196:199], v[152:155], v[8:11]
	v_mfma_f32_16x16x32_bf16 v[20:23], v[188:191], v[160:163], v[20:23]
	v_mfma_f32_16x16x32_bf16 v[4:7], v[196:199], v[160:163], v[4:7]
	v_mfma_f32_16x16x32_bf16 v[16:19], v[188:191], v[180:183], v[16:19]
	v_mfma_f32_16x16x32_bf16 v[0:3], v[196:199], v[180:183], v[0:3]
	v_mfma_f32_16x16x32_bf16 v[32:35], v[192:195], v[148:151], v[32:35]
	v_mfma_f32_16x16x32_bf16 v[12:15], v[200:203], v[148:151], v[12:15]
	v_mfma_f32_16x16x32_bf16 v[24:27], v[192:195], v[156:159], v[24:27]
	v_mfma_f32_16x16x32_bf16 v[8:11], v[200:203], v[156:159], v[8:11]
	v_mfma_f32_16x16x32_bf16 v[20:23], v[192:195], v[176:179], v[20:23]
	v_mfma_f32_16x16x32_bf16 v[4:7], v[200:203], v[176:179], v[4:7]
	v_mfma_f32_16x16x32_bf16 v[16:19], v[192:195], v[184:187], v[16:19]
	v_mfma_f32_16x16x32_bf16 v[0:3], v[200:203], v[184:187], v[0:3]
	s_add_i32 s42, 0, 0x18000
	s_barrier
	s_add_u32 s4, s4, 0x160000
	s_addc_u32 s5, s5, 0
	s_mov_b32 m0, s29
	v_lshl_add_u64 v[188:189], s[4:5], 0, v[166:167]
	ds_read_b128 v[144:147], v222 offset:32768
	ds_read_b128 v[148:151], v222 offset:33792
	ds_read_b128 v[152:155], v222 offset:34816
	ds_read_b128 v[156:159], v222 offset:35840
	ds_read_b128 v[160:163], v222 offset:36864
	ds_read_b128 v[176:179], v222 offset:37888
	ds_read_b128 v[180:183], v222 offset:38912
	ds_read_b128 v[184:187], v222 offset:39936
	global_load_lds_dwordx4 v[188:189], off
	v_lshl_add_u64 v[188:189], s[4:5], 0, v[164:165]
	s_mov_b32 m0, s33
	s_nop 0
	global_load_lds_dwordx4 v[188:189], off
	s_waitcnt lgkmcnt(8)
	s_barrier
	s_waitcnt lgkmcnt(0)
	s_waitcnt lgkmcnt(0)
	v_mfma_f32_16x16x32_bf16 v[124:127], v[128:131], v[144:147], v[124:127]
	v_mfma_f32_16x16x32_bf16 v[100:103], v[136:139], v[144:147], v[100:103]
	v_mfma_f32_16x16x32_bf16 v[120:123], v[128:131], v[152:155], v[120:123]
	v_mfma_f32_16x16x32_bf16 v[96:99], v[136:139], v[152:155], v[96:99]
	v_mfma_f32_16x16x32_bf16 v[116:119], v[128:131], v[160:163], v[116:119]
	v_mfma_f32_16x16x32_bf16 v[92:95], v[136:139], v[160:163], v[92:95]
	v_mfma_f32_16x16x32_bf16 v[112:115], v[128:131], v[180:183], v[112:115]
	v_mfma_f32_16x16x32_bf16 v[84:87], v[136:139], v[180:183], v[84:87]
	v_mfma_f32_16x16x32_bf16 v[124:127], v[132:135], v[148:151], v[124:127]
	v_mfma_f32_16x16x32_bf16 v[100:103], v[140:143], v[148:151], v[100:103]
	v_mfma_f32_16x16x32_bf16 v[120:123], v[132:135], v[156:159], v[120:123]
	v_mfma_f32_16x16x32_bf16 v[96:99], v[140:143], v[156:159], v[96:99]
	v_mfma_f32_16x16x32_bf16 v[116:119], v[132:135], v[176:179], v[116:119]
	v_mfma_f32_16x16x32_bf16 v[92:95], v[140:143], v[176:179], v[92:95]
	v_mfma_f32_16x16x32_bf16 v[112:115], v[132:135], v[184:187], v[112:115]
	v_mfma_f32_16x16x32_bf16 v[84:87], v[140:143], v[184:187], v[84:87]
	s_barrier
	s_add_i32 s43, 0, 0x1c000
	s_add_i32 s4, s42, s24
	v_add_u32_e32 v200, s43, v219
	v_lshl_add_u64 v[204:205], v[204:205], 0, s[18:19]
	s_mov_b32 m0, s4
	ds_read_b128 v[188:191], v200
	ds_read_b128 v[192:195], v200 offset:1024
	ds_read_b128 v[196:199], v200 offset:2048
	ds_read_b128 v[200:203], v200 offset:3072
	global_load_lds_dwordx4 v[204:205], off
	v_lshl_add_u64 v[204:205], v[206:207], 0, s[18:19]
	s_add_i32 m0, s4, 0x2000
	s_nop 0
	global_load_lds_dwordx4 v[204:205], off
	s_barrier
	s_waitcnt lgkmcnt(0)
	s_waitcnt lgkmcnt(0)
	v_mfma_f32_16x16x32_bf16 v[72:75], v[188:191], v[144:147], v[72:75]
	v_mfma_f32_16x16x32_bf16 v[44:47], v[196:199], v[144:147], v[44:47]
	v_mfma_f32_16x16x32_bf16 v[64:67], v[188:191], v[152:155], v[64:67]
	v_mfma_f32_16x16x32_bf16 v[40:43], v[196:199], v[152:155], v[40:43]
	v_mfma_f32_16x16x32_bf16 v[56:59], v[188:191], v[160:163], v[56:59]
	v_mfma_f32_16x16x32_bf16 v[36:39], v[196:199], v[160:163], v[36:39]
	v_mfma_f32_16x16x32_bf16 v[48:51], v[188:191], v[180:183], v[48:51]
	v_mfma_f32_16x16x32_bf16 v[28:31], v[196:199], v[180:183], v[28:31]
	v_mfma_f32_16x16x32_bf16 v[72:75], v[192:195], v[148:151], v[72:75]
	v_mfma_f32_16x16x32_bf16 v[44:47], v[200:203], v[148:151], v[44:47]
	v_mfma_f32_16x16x32_bf16 v[64:67], v[192:195], v[156:159], v[64:67]
	v_mfma_f32_16x16x32_bf16 v[40:43], v[200:203], v[156:159], v[40:43]
	v_mfma_f32_16x16x32_bf16 v[56:59], v[192:195], v[176:179], v[56:59]
	v_mfma_f32_16x16x32_bf16 v[36:39], v[200:203], v[176:179], v[36:39]
	v_mfma_f32_16x16x32_bf16 v[48:51], v[192:195], v[184:187], v[48:51]
	v_mfma_f32_16x16x32_bf16 v[28:31], v[200:203], v[184:187], v[28:31]
	s_mov_b32 m0, s37
	v_lshl_add_u64 v[204:205], v[208:209], 0, s[18:19]
	s_barrier
	s_waitcnt vmcnt(8)
	ds_read_b128 v[144:147], v222 offset:49152
	ds_read_b128 v[148:151], v222 offset:50176
	ds_read_b128 v[152:155], v222 offset:51200
	ds_read_b128 v[156:159], v222 offset:52224
	ds_read_b128 v[160:163], v222 offset:53248
	ds_read_b128 v[176:179], v222 offset:54272
	ds_read_b128 v[180:183], v222 offset:55296
	ds_read_b128 v[184:187], v222 offset:56320
	global_load_lds_dwordx4 v[204:205], off
	v_lshl_add_u64 v[204:205], v[210:211], 0, s[18:19]
	s_mov_b32 m0, s40
	s_nop 0
	global_load_lds_dwordx4 v[204:205], off
	s_barrier
	s_waitcnt lgkmcnt(0)
	s_waitcnt lgkmcnt(0)
	v_mfma_f32_16x16x32_bf16 v[108:111], v[128:131], v[144:147], v[108:111]
	v_mfma_f32_16x16x32_bf16 v[76:79], v[136:139], v[144:147], v[76:79]
	v_mfma_f32_16x16x32_bf16 v[104:107], v[128:131], v[152:155], v[104:107]
	v_mfma_f32_16x16x32_bf16 v[68:71], v[136:139], v[152:155], v[68:71]
	v_mfma_f32_16x16x32_bf16 v[88:91], v[128:131], v[160:163], v[88:91]
	v_mfma_f32_16x16x32_bf16 v[60:63], v[136:139], v[160:163], v[60:63]
	v_mfma_f32_16x16x32_bf16 v[80:83], v[128:131], v[180:183], v[80:83]
	v_mfma_f32_16x16x32_bf16 v[52:55], v[136:139], v[180:183], v[52:55]
	v_mfma_f32_16x16x32_bf16 v[108:111], v[132:135], v[148:151], v[108:111]
	v_mfma_f32_16x16x32_bf16 v[76:79], v[140:143], v[148:151], v[76:79]
	v_mfma_f32_16x16x32_bf16 v[104:107], v[132:135], v[156:159], v[104:107]
	v_mfma_f32_16x16x32_bf16 v[68:71], v[140:143], v[156:159], v[68:71]
	v_mfma_f32_16x16x32_bf16 v[88:91], v[132:135], v[176:179], v[88:91]
	v_mfma_f32_16x16x32_bf16 v[60:63], v[140:143], v[176:179], v[60:63]
	v_mfma_f32_16x16x32_bf16 v[80:83], v[132:135], v[184:187], v[80:83]
	v_mfma_f32_16x16x32_bf16 v[52:55], v[140:143], v[184:187], v[52:55]
	s_barrier
	s_add_u32 s4, s66, 0x160080
	s_addc_u32 s5, s67, 0
	s_add_i32 s42, s43, s24
	v_lshl_add_u64 v[128:129], s[4:5], 0, v[166:167]
	s_mov_b32 m0, s42
	s_nop 0
	global_load_lds_dwordx4 v[128:129], off
	v_lshl_add_u64 v[128:129], s[4:5], 0, v[164:165]
	s_add_i32 m0, s42, 0x2000
	s_nop 0
	global_load_lds_dwordx4 v[128:129], off
	ds_read_b128 v[128:131], v221
	ds_read_b128 v[132:135], v221 offset:1024
	ds_read_b128 v[136:139], v221 offset:2048
	ds_read_b128 v[140:143], v221 offset:3072
	s_waitcnt vmcnt(6)
	s_barrier
	v_mfma_f32_16x16x32_bf16 v[32:35], v[188:191], v[144:147], v[32:35]
	v_mfma_f32_16x16x32_bf16 v[12:15], v[196:199], v[144:147], v[12:15]
	v_mfma_f32_16x16x32_bf16 v[24:27], v[188:191], v[152:155], v[24:27]
	v_mfma_f32_16x16x32_bf16 v[8:11], v[196:199], v[152:155], v[8:11]
	v_mfma_f32_16x16x32_bf16 v[20:23], v[188:191], v[160:163], v[20:23]
	v_mfma_f32_16x16x32_bf16 v[4:7], v[196:199], v[160:163], v[4:7]
	v_mfma_f32_16x16x32_bf16 v[16:19], v[188:191], v[180:183], v[16:19]
	v_mfma_f32_16x16x32_bf16 v[0:3], v[196:199], v[180:183], v[0:3]
	v_mfma_f32_16x16x32_bf16 v[32:35], v[192:195], v[148:151], v[32:35]
	v_mfma_f32_16x16x32_bf16 v[12:15], v[200:203], v[148:151], v[12:15]
	v_mfma_f32_16x16x32_bf16 v[24:27], v[192:195], v[156:159], v[24:27]
	v_mfma_f32_16x16x32_bf16 v[8:11], v[200:203], v[156:159], v[8:11]
	v_mfma_f32_16x16x32_bf16 v[20:23], v[192:195], v[176:179], v[20:23]
	v_mfma_f32_16x16x32_bf16 v[4:7], v[200:203], v[176:179], v[4:7]
	v_mfma_f32_16x16x32_bf16 v[16:19], v[192:195], v[184:187], v[16:19]
	v_mfma_f32_16x16x32_bf16 v[0:3], v[200:203], v[184:187], v[0:3]
	s_add_i32 s76, s76, 2
	s_add_u32 s0, s0, 0x100
	s_addc_u32 s1, s1, 0
	s_cmpk_gt_u32 s76, 0x55
	s_mov_b64 s[62:63], s[64:65]
	s_barrier
	s_cbranch_scc0 .LBB0_1098
	v_lshl_add_u32 v144, s74, 8, v218
	v_lshl_or_b32 v184, s75, 8, v220
	v_ashrrev_i32_e32 v145, 31, v144
	v_ashrrev_i32_e32 v185, 31, v184
	v_lshlrev_b64 v[132:133], 13, v[144:145]
	v_lshlrev_b64 v[146:147], 2, v[184:185]
	v_lshl_add_u64 v[132:133], s[12:13], 0, v[132:133]
	v_lshl_add_u64 v[176:177], v[132:133], 0, v[146:147]
	v_or_b32_e32 v136, 16, v144
	v_add_co_u32_e32 v186, vcc, s68, v176
	v_ashrrev_i32_e32 v137, 31, v136
	v_or_b32_e32 v140, 32, v144
	v_or_b32_e32 v144, 48, v144
	v_addc_co_u32_e32 v187, vcc, 0, v177, vcc
	v_lshlrev_b64 v[136:137], 13, v[136:137]
	v_ashrrev_i32_e32 v141, 31, v140
	v_ashrrev_i32_e32 v145, 31, v144
	v_add_co_u32_e32 v190, vcc, s69, v176
	v_lshl_add_u64 v[128:129], s[16:17], 0, v[146:147]
	v_lshl_add_u64 v[136:137], s[12:13], 0, v[136:137]
	v_lshlrev_b64 v[140:141], 13, v[140:141]
	v_lshlrev_b64 v[144:145], 13, v[144:145]
	v_addc_co_u32_e32 v191, vcc, 0, v177, vcc
	global_load_dwordx4 v[128:131], v[128:129], off
	v_lshl_add_u64 v[178:179], v[136:137], 0, v[146:147]
	global_load_dwordx4 v[132:135], v[176:177], off
	global_load_dwordx4 v[136:139], v[178:179], off
	v_lshl_add_u64 v[140:141], s[12:13], 0, v[140:141]
	v_lshl_add_u64 v[144:145], s[12:13], 0, v[144:145]
	v_add_co_u32_e32 v192, vcc, s70, v176
	v_lshl_add_u64 v[180:181], v[140:141], 0, v[146:147]
	v_lshl_add_u64 v[182:183], v[144:145], 0, v[146:147]
	v_addc_co_u32_e32 v193, vcc, 0, v177, vcc
	global_load_dwordx4 v[140:143], v[180:181], off
	global_load_dwordx4 v[144:147], v[182:183], off
	global_load_dwordx4 v[148:151], v[186:187], off
	global_load_dwordx4 v[160:163], v[190:191], off
	global_load_dwordx4 v[156:159], v[192:193], off
	v_add_co_u32_e32 v188, vcc, s71, v176
	v_pk_add_f32 v[212:213], v[126:127], 0 op_sel_hi:[1,0]
	s_nop 0
	v_addc_co_u32_e32 v189, vcc, 0, v177, vcc
	global_load_dwordx4 v[152:155], v[188:189], off
	v_pk_add_f32 v[214:215], v[124:125], 0 op_sel_hi:[1,0]
	v_pk_add_f32 v[126:127], v[122:123], 0 op_sel_hi:[1,0]
	v_pk_add_f32 v[194:195], v[120:121], 0 op_sel_hi:[1,0]
	v_pk_add_f32 v[196:197], v[118:119], 0 op_sel_hi:[1,0]
	v_pk_add_f32 v[198:199], v[116:117], 0 op_sel_hi:[1,0]
	v_pk_add_f32 v[200:201], v[114:115], 0 op_sel_hi:[1,0]
	v_pk_add_f32 v[202:203], v[112:113], 0 op_sel_hi:[1,0]
	v_pk_add_f32 v[204:205], v[110:111], 0 op_sel_hi:[1,0]
	v_pk_add_f32 v[206:207], v[108:109], 0 op_sel_hi:[1,0]
	v_pk_add_f32 v[208:209], v[106:107], 0 op_sel_hi:[1,0]
	v_pk_add_f32 v[210:211], v[104:105], 0 op_sel_hi:[1,0]
	v_lshl_add_u64 v[120:121], v[176:177], 0, s[20:21]
	v_lshl_add_u64 v[122:123], v[176:177], 0, s[46:47]
	global_load_dwordx4 v[104:107], v[176:177], off offset:64
	global_load_dwordx4 v[108:111], v[178:179], off offset:64
	global_load_dwordx4 v[112:115], v[180:181], off offset:64
	global_load_dwordx4 v[116:119], v[182:183], off offset:64
	global_load_dwordx4 v[224:227], v[120:121], off offset:576
	global_load_dwordx4 v[228:231], v[122:123], off offset:576
	v_lshl_add_u64 v[124:125], v[176:177], 0, s[60:61]
	v_pk_add_f32 v[102:103], v[102:103], 0 op_sel_hi:[1,0]
	v_pk_add_f32 v[100:101], v[100:101], 0 op_sel_hi:[1,0]
	v_pk_add_f32 v[98:99], v[98:99], 0 op_sel_hi:[1,0]
	v_pk_add_f32 v[96:97], v[96:97], 0 op_sel_hi:[1,0]
	v_pk_add_f32 v[74:75], v[74:75], 0 op_sel_hi:[1,0]
	v_pk_add_f32 v[72:73], v[72:73], 0 op_sel_hi:[1,0]
	v_pk_add_f32 v[66:67], v[66:67], 0 op_sel_hi:[1,0]
	v_pk_add_f32 v[64:65], v[64:65], 0 op_sel_hi:[1,0]
	v_pk_add_f32 v[58:59], v[58:59], 0 op_sel_hi:[1,0]
	v_pk_add_f32 v[56:57], v[56:57], 0 op_sel_hi:[1,0]
	v_pk_add_f32 v[46:47], v[46:47], 0 op_sel_hi:[1,0]
	v_pk_add_f32 v[44:45], v[44:45], 0 op_sel_hi:[1,0]
	v_pk_add_f32 v[42:43], v[42:43], 0 op_sel_hi:[1,0]
	v_pk_add_f32 v[40:41], v[40:41], 0 op_sel_hi:[1,0]
	v_pk_add_f32 v[38:39], v[38:39], 0 op_sel_hi:[1,0]
	v_pk_add_f32 v[36:37], v[36:37], 0 op_sel_hi:[1,0]
	v_pk_add_f32 v[30:31], v[30:31], 0 op_sel_hi:[1,0]
	v_pk_add_f32 v[28:29], v[28:29], 0 op_sel_hi:[1,0]
	s_and_b64 vcc, exec, s[6:7]
	s_mov_b32 s75, s72
	s_mov_b32 s74, s73
	s_mov_b64 s[64:65], s[10:11]
	s_mov_b64 s[62:63], s[8:9]
	s_waitcnt vmcnt(0)
	v_pk_fma_f32 v[134:135], v[212:213], v[130:131], v[134:135]
	v_pk_fma_f32 v[132:133], v[214:215], v[128:129], v[132:133]
	global_store_dwordx4 v[176:177], v[132:135], off
	s_nop 1
	v_pk_fma_f32 v[134:135], v[126:127], v[130:131], v[138:139]
	v_pk_fma_f32 v[132:133], v[194:195], v[128:129], v[136:137]
	v_pk_add_f32 v[126:127], v[90:91], 0 op_sel_hi:[1,0]
	v_pk_fma_f32 v[138:139], v[196:197], v[130:131], v[142:143]
	v_pk_fma_f32 v[136:137], v[198:199], v[128:129], v[140:141]
	v_pk_fma_f32 v[142:143], v[200:201], v[130:131], v[146:147]
	v_pk_fma_f32 v[140:141], v[202:203], v[128:129], v[144:145]
	v_pk_fma_f32 v[146:147], v[204:205], v[130:131], v[150:151]
	v_pk_fma_f32 v[144:145], v[206:207], v[128:129], v[148:149]
	v_pk_fma_f32 v[150:151], v[208:209], v[130:131], v[162:163]
	v_pk_fma_f32 v[148:149], v[210:211], v[128:129], v[160:161]
	global_store_dwordx4 v[178:179], v[132:135], off
	global_store_dwordx4 v[180:181], v[136:139], off
	global_store_dwordx4 v[182:183], v[140:143], off
	global_store_dwordx4 v[186:187], v[144:147], off
	global_store_dwordx4 v[190:191], v[148:151], off
	v_pk_add_f32 v[132:133], v[88:89], 0 op_sel_hi:[1,0]
	v_pk_fma_f32 v[134:135], v[126:127], v[130:131], v[158:159]
	v_pk_fma_f32 v[132:133], v[132:133], v[128:129], v[156:157]
	v_pk_add_f32 v[126:127], v[82:83], 0 op_sel_hi:[1,0]
	global_store_dwordx4 v[192:193], v[132:135], off
	v_pk_fma_f32 v[130:131], v[126:127], v[130:131], v[154:155]
	v_or_b32_e32 v126, 16, v184
	v_pk_add_f32 v[132:133], v[80:81], 0 op_sel_hi:[1,0]
	v_ashrrev_i32_e32 v127, 31, v126
	v_pk_fma_f32 v[128:129], v[132:133], v[128:129], v[152:153]
	v_lshl_add_u64 v[146:147], v[176:177], 0, s[14:15]
	global_store_dwordx4 v[188:189], v[128:131], off
	v_lshl_add_u64 v[126:127], v[126:127], 2, s[16:17]
	global_load_dwordx4 v[88:91], v[124:125], off offset:576
	global_load_dwordx4 v[80:83], v[146:147], off offset:576
	s_nop 0
	global_load_dwordx4 v[126:129], v[126:127], off
	s_nop 0
	global_load_dwordx4 v[130:133], v[120:121], off offset:64
	global_load_dwordx4 v[134:137], v[122:123], off offset:64
	global_load_dwordx4 v[138:141], v[124:125], off offset:64
	global_load_dwordx4 v[142:145], v[146:147], off offset:64
	v_pk_add_f32 v[192:193], v[52:53], 0 op_sel_hi:[1,0]
	v_or_b32_e32 v52, 0x80, v184
	v_pk_add_f32 v[148:149], v[94:95], 0 op_sel_hi:[1,0]
	v_pk_add_f32 v[150:151], v[92:93], 0 op_sel_hi:[1,0]
	v_pk_add_f32 v[152:153], v[86:87], 0 op_sel_hi:[1,0]
	v_pk_add_f32 v[154:155], v[84:85], 0 op_sel_hi:[1,0]
	v_pk_add_f32 v[156:157], v[78:79], 0 op_sel_hi:[1,0]
	v_pk_add_f32 v[158:159], v[76:77], 0 op_sel_hi:[1,0]
	v_pk_add_f32 v[160:161], v[70:71], 0 op_sel_hi:[1,0]
	v_pk_add_f32 v[162:163], v[68:69], 0 op_sel_hi:[1,0]
	v_pk_add_f32 v[186:187], v[62:63], 0 op_sel_hi:[1,0]
	v_pk_add_f32 v[188:189], v[60:61], 0 op_sel_hi:[1,0]
	v_pk_add_f32 v[190:191], v[54:55], 0 op_sel_hi:[1,0]
	v_ashrrev_i32_e32 v53, 31, v52
	v_lshl_add_u64 v[194:195], v[52:53], 2, s[16:17]
	global_load_dwordx4 v[52:55], v[176:177], off offset:512
	global_load_dwordx4 v[60:63], v[120:121], off offset:512
	global_load_dwordx4 v[68:71], v[122:123], off offset:512
	global_load_dwordx4 v[76:79], v[124:125], off offset:512
	global_load_dwordx4 v[84:87], v[146:147], off offset:512
	s_waitcnt vmcnt(0)
	v_pk_fma_f32 v[94:95], v[102:103], v[128:129], v[106:107]
	v_pk_fma_f32 v[92:93], v[100:101], v[126:127], v[104:105]
	v_pk_fma_f32 v[98:99], v[98:99], v[128:129], v[110:111]
	v_pk_fma_f32 v[96:97], v[96:97], v[126:127], v[108:109]
	v_pk_fma_f32 v[102:103], v[148:149], v[128:129], v[114:115]
	v_pk_fma_f32 v[100:101], v[150:151], v[126:127], v[112:113]
	v_pk_fma_f32 v[106:107], v[152:153], v[128:129], v[118:119]
	v_pk_fma_f32 v[104:105], v[154:155], v[126:127], v[116:117]
	v_pk_fma_f32 v[110:111], v[156:157], v[128:129], v[132:133]
	v_pk_fma_f32 v[108:109], v[158:159], v[126:127], v[130:131]
	v_pk_fma_f32 v[114:115], v[160:161], v[128:129], v[136:137]
	v_pk_fma_f32 v[112:113], v[162:163], v[126:127], v[134:135]
	v_pk_fma_f32 v[118:119], v[186:187], v[128:129], v[140:141]
	v_pk_fma_f32 v[116:117], v[188:189], v[126:127], v[138:139]
	v_pk_fma_f32 v[128:129], v[190:191], v[128:129], v[144:145]
	v_pk_fma_f32 v[126:127], v[192:193], v[126:127], v[142:143]
	global_store_dwordx4 v[176:177], v[92:95], off offset:64
	global_store_dwordx4 v[178:179], v[96:99], off offset:64
	global_store_dwordx4 v[180:181], v[100:103], off offset:64
	global_store_dwordx4 v[182:183], v[104:107], off offset:64
	global_store_dwordx4 v[120:121], v[108:111], off offset:64
	global_store_dwordx4 v[122:123], v[112:115], off offset:64
	global_store_dwordx4 v[124:125], v[116:119], off offset:64
	global_store_dwordx4 v[146:147], v[126:129], off offset:64
	global_load_dwordx4 v[92:95], v[194:195], off
	global_load_dwordx4 v[96:99], v[178:179], off offset:512
	global_load_dwordx4 v[100:103], v[180:181], off offset:512
	global_load_dwordx4 v[104:107], v[182:183], off offset:512
	v_pk_add_f32 v[132:133], v[16:17], 0 op_sel_hi:[1,0]
	v_or_b32_e32 v16, 0x90, v184
	v_pk_add_f32 v[108:109], v[50:51], 0 op_sel_hi:[1,0]
	v_pk_add_f32 v[110:111], v[48:49], 0 op_sel_hi:[1,0]
	v_pk_add_f32 v[112:113], v[34:35], 0 op_sel_hi:[1,0]
	v_pk_add_f32 v[114:115], v[32:33], 0 op_sel_hi:[1,0]
	v_pk_add_f32 v[116:117], v[26:27], 0 op_sel_hi:[1,0]
	v_pk_add_f32 v[118:119], v[24:25], 0 op_sel_hi:[1,0]
	v_pk_add_f32 v[126:127], v[22:23], 0 op_sel_hi:[1,0]
	v_pk_add_f32 v[128:129], v[20:21], 0 op_sel_hi:[1,0]
	v_pk_add_f32 v[130:131], v[18:19], 0 op_sel_hi:[1,0]
	v_ashrrev_i32_e32 v17, 31, v16
	v_lshl_add_u64 v[134:135], v[16:17], 2, s[16:17]
	global_load_dwordx4 v[16:19], v[176:177], off offset:576
	global_load_dwordx4 v[20:23], v[178:179], off offset:576
	global_load_dwordx4 v[24:27], v[180:181], off offset:576
	global_load_dwordx4 v[32:35], v[182:183], off offset:576
	s_waitcnt vmcnt(0)
	v_pk_fma_f32 v[50:51], v[74:75], v[94:95], v[54:55]
	v_pk_fma_f32 v[48:49], v[72:73], v[92:93], v[52:53]
	v_pk_fma_f32 v[54:55], v[66:67], v[94:95], v[98:99]
	v_pk_fma_f32 v[52:53], v[64:65], v[92:93], v[96:97]
	v_pk_fma_f32 v[58:59], v[58:59], v[94:95], v[102:103]
	v_pk_fma_f32 v[56:57], v[56:57], v[92:93], v[100:101]
	v_pk_fma_f32 v[66:67], v[108:109], v[94:95], v[106:107]
	v_pk_fma_f32 v[64:65], v[110:111], v[92:93], v[104:105]
	v_pk_fma_f32 v[62:63], v[112:113], v[94:95], v[62:63]
	v_pk_fma_f32 v[60:61], v[114:115], v[92:93], v[60:61]
	v_pk_fma_f32 v[70:71], v[116:117], v[94:95], v[70:71]
	v_pk_fma_f32 v[68:69], v[118:119], v[92:93], v[68:69]
	v_pk_fma_f32 v[74:75], v[126:127], v[94:95], v[78:79]
	v_pk_fma_f32 v[72:73], v[128:129], v[92:93], v[76:77]
	v_pk_fma_f32 v[78:79], v[130:131], v[94:95], v[86:87]
	v_pk_fma_f32 v[76:77], v[132:133], v[92:93], v[84:85]
	global_store_dwordx4 v[176:177], v[48:51], off offset:512
	global_store_dwordx4 v[178:179], v[52:55], off offset:512
	global_store_dwordx4 v[180:181], v[56:59], off offset:512
	global_store_dwordx4 v[182:183], v[64:67], off offset:512
	global_store_dwordx4 v[120:121], v[60:63], off offset:512
	global_store_dwordx4 v[122:123], v[68:71], off offset:512
	global_store_dwordx4 v[124:125], v[72:75], off offset:512
	global_store_dwordx4 v[146:147], v[76:79], off offset:512
	global_load_dwordx4 v[48:51], v[134:135], off
	v_pk_add_f32 v[52:53], v[14:15], 0 op_sel_hi:[1,0]
	v_pk_add_f32 v[54:55], v[12:13], 0 op_sel_hi:[1,0]
	v_pk_add_f32 v[56:57], v[10:11], 0 op_sel_hi:[1,0]
	v_pk_add_f32 v[58:59], v[8:9], 0 op_sel_hi:[1,0]
	v_pk_add_f32 v[60:61], v[6:7], 0 op_sel_hi:[1,0]
	v_pk_add_f32 v[62:63], v[4:5], 0 op_sel_hi:[1,0]
	v_pk_add_f32 v[64:65], v[2:3], 0 op_sel_hi:[1,0]
	v_pk_add_f32 v[66:67], v[0:1], 0 op_sel_hi:[1,0]
	s_waitcnt vmcnt(0)
	v_pk_fma_f32 v[2:3], v[46:47], v[50:51], v[18:19]
	v_pk_fma_f32 v[0:1], v[44:45], v[48:49], v[16:17]
	v_pk_fma_f32 v[6:7], v[42:43], v[50:51], v[22:23]
	v_pk_fma_f32 v[4:5], v[40:41], v[48:49], v[20:21]
	v_pk_fma_f32 v[10:11], v[38:39], v[50:51], v[26:27]
	v_pk_fma_f32 v[8:9], v[36:37], v[48:49], v[24:25]
	v_pk_fma_f32 v[14:15], v[30:31], v[50:51], v[34:35]
	v_pk_fma_f32 v[12:13], v[28:29], v[48:49], v[32:33]
	v_pk_fma_f32 v[18:19], v[52:53], v[50:51], v[226:227]
	v_pk_fma_f32 v[16:17], v[54:55], v[48:49], v[224:225]
	v_pk_fma_f32 v[22:23], v[56:57], v[50:51], v[230:231]
	v_pk_fma_f32 v[20:21], v[58:59], v[48:49], v[228:229]
	v_pk_fma_f32 v[26:27], v[60:61], v[50:51], v[90:91]
	v_pk_fma_f32 v[24:25], v[62:63], v[48:49], v[88:89]
	v_pk_fma_f32 v[30:31], v[64:65], v[50:51], v[82:83]
	v_pk_fma_f32 v[28:29], v[66:67], v[48:49], v[80:81]
	global_store_dwordx4 v[176:177], v[0:3], off offset:576
	global_store_dwordx4 v[178:179], v[4:7], off offset:576
	global_store_dwordx4 v[180:181], v[8:11], off offset:576
	global_store_dwordx4 v[182:183], v[12:15], off offset:576
	global_store_dwordx4 v[120:121], v[16:19], off offset:576
	global_store_dwordx4 v[122:123], v[20:23], off offset:576
	global_store_dwordx4 v[124:125], v[24:27], off offset:576
	global_store_dwordx4 v[146:147], v[28:31], off offset:576
	s_cbranch_vccz .LBB0_1087
	s_waitcnt vmcnt(0)
	s_cmpk_gt_u32 s23, 0xff
	s_cbranch_scc1 .LBB0_1102
	s_barrier

.LBB0_1233:
	s_ashr_i32 s15, s14, 31
	v_cmp_lt_i64_e32 vcc, s[0:1], v[148:149]
	s_lshl_b64 s[0:1], s[14:15], 20
	s_add_u32 s16, s38, s0
	s_addc_u32 s17, s39, s1
	s_and_b64 s[0:1], vcc, exec
	s_cselect_b32 s0, s17, s37
	s_cselect_b32 s1, s16, s36
	s_ashr_i32 s13, s12, 31
	s_lshl_b64 s[4:5], s[12:13], 20
	s_add_u32 s18, s54, s4
	s_addc_u32 s19, s55, s5
	s_and_b64 s[4:5], vcc, exec
	s_cselect_b32 s13, s19, s59
	s_cselect_b32 s15, s18, s58
	s_add_u32 s46, s36, 0x80080
	s_addc_u32 s47, s37, 0
	s_add_u32 s36, s58, 0x100
	v_mov_b32_e32 v0, 0
	s_addc_u32 s37, s59, 0
	s_mov_b32 s64, -2
	v_mov_b32_e32 v1, v0
	v_mov_b32_e32 v2, v0
	v_mov_b32_e32 v3, v0
	v_mov_b32_e32 v4, v0
	v_mov_b32_e32 v5, v0
	v_mov_b32_e32 v6, v0
	v_mov_b32_e32 v7, v0
	v_mov_b32_e32 v8, v0
	v_mov_b32_e32 v9, v0
	v_mov_b32_e32 v10, v0
	v_mov_b32_e32 v11, v0
	v_mov_b32_e32 v12, v0
	v_mov_b32_e32 v13, v0
	v_mov_b32_e32 v14, v0
	v_mov_b32_e32 v15, v0
	v_mov_b32_e32 v16, v0
	v_mov_b32_e32 v17, v0
	v_mov_b32_e32 v18, v0
	v_mov_b32_e32 v19, v0
	v_mov_b32_e32 v20, v0
	v_mov_b32_e32 v21, v0
	v_mov_b32_e32 v22, v0
	v_mov_b32_e32 v23, v0
	v_mov_b32_e32 v24, v0
	v_mov_b32_e32 v25, v0
	v_mov_b32_e32 v26, v0
	v_mov_b32_e32 v27, v0
	v_mov_b32_e32 v28, v0
	v_mov_b32_e32 v29, v0
	v_mov_b32_e32 v30, v0
	v_mov_b32_e32 v31, v0
	v_mov_b32_e32 v56, v0
	v_mov_b32_e32 v57, v0
	v_mov_b32_e32 v58, v0
	v_mov_b32_e32 v59, v0
	v_mov_b32_e32 v60, v0
	v_mov_b32_e32 v61, v0
	v_mov_b32_e32 v62, v0
	v_mov_b32_e32 v63, v0
	v_mov_b32_e32 v72, v0
	v_mov_b32_e32 v73, v0
	v_mov_b32_e32 v74, v0
	v_mov_b32_e32 v75, v0
	v_mov_b32_e32 v76, v0
	v_mov_b32_e32 v77, v0
	v_mov_b32_e32 v78, v0
	v_mov_b32_e32 v79, v0
	v_mov_b32_e32 v80, v0
	v_mov_b32_e32 v81, v0
	v_mov_b32_e32 v82, v0
	v_mov_b32_e32 v83, v0
	v_mov_b32_e32 v84, v0
	v_mov_b32_e32 v85, v0
	v_mov_b32_e32 v86, v0
	v_mov_b32_e32 v87, v0
	v_mov_b32_e32 v88, v0
	v_mov_b32_e32 v89, v0
	v_mov_b32_e32 v90, v0
	v_mov_b32_e32 v91, v0
	v_mov_b32_e32 v92, v0
	v_mov_b32_e32 v93, v0
	v_mov_b32_e32 v94, v0
	v_mov_b32_e32 v95, v0
	v_mov_b32_e32 v32, v0
	v_mov_b32_e32 v33, v0
	v_mov_b32_e32 v34, v0
	v_mov_b32_e32 v35, v0
	v_mov_b32_e32 v36, v0
	v_mov_b32_e32 v37, v0
	v_mov_b32_e32 v38, v0
	v_mov_b32_e32 v39, v0
	v_mov_b32_e32 v40, v0
	v_mov_b32_e32 v41, v0
	v_mov_b32_e32 v42, v0
	v_mov_b32_e32 v43, v0
	v_mov_b32_e32 v44, v0
	v_mov_b32_e32 v45, v0
	v_mov_b32_e32 v46, v0
	v_mov_b32_e32 v47, v0
	v_mov_b32_e32 v48, v0
	v_mov_b32_e32 v49, v0
	v_mov_b32_e32 v50, v0
	v_mov_b32_e32 v51, v0
	v_mov_b32_e32 v52, v0
	v_mov_b32_e32 v53, v0
	v_mov_b32_e32 v54, v0
	v_mov_b32_e32 v55, v0
	v_mov_b32_e32 v64, v0
	v_mov_b32_e32 v65, v0
	v_mov_b32_e32 v66, v0
	v_mov_b32_e32 v67, v0
	v_mov_b32_e32 v68, v0
	v_mov_b32_e32 v69, v0
	v_mov_b32_e32 v70, v0
	v_mov_b32_e32 v71, v0
	v_mov_b32_e32 v96, v0
	v_mov_b32_e32 v97, v0
	v_mov_b32_e32 v98, v0
	v_mov_b32_e32 v99, v0
	v_mov_b32_e32 v100, v0
	v_mov_b32_e32 v101, v0
	v_mov_b32_e32 v102, v0
	v_mov_b32_e32 v103, v0
	v_mov_b32_e32 v104, v0
	v_mov_b32_e32 v105, v0
	v_mov_b32_e32 v106, v0
	v_mov_b32_e32 v107, v0
	v_mov_b32_e32 v108, v0
	v_mov_b32_e32 v109, v0
	v_mov_b32_e32 v110, v0
	v_mov_b32_e32 v111, v0
	v_mov_b32_e32 v112, v0
	v_mov_b32_e32 v113, v0
	v_mov_b32_e32 v114, v0
	v_mov_b32_e32 v115, v0
	v_mov_b32_e32 v116, v0
	v_mov_b32_e32 v117, v0
	v_mov_b32_e32 v118, v0
	v_mov_b32_e32 v119, v0
	v_mov_b32_e32 v120, v0
	v_mov_b32_e32 v121, v0
	v_mov_b32_e32 v122, v0
	v_mov_b32_e32 v123, v0
	v_mov_b32_e32 v124, v0
	v_mov_b32_e32 v125, v0
	v_mov_b32_e32 v126, v0
	v_mov_b32_e32 v127, v0
	ds_read_b128 v[128:131], v171
	ds_read_b128 v[132:135], v171 offset:1024
	ds_read_b128 v[152:155], v171 offset:2048
	ds_read_b128 v[156:159], v171 offset:3072
.LBB0_1234:
	s_add_u32 s4, s46, 0xfff80080
	s_addc_u32 s5, s47, -1
	s_cmp_eq_u32 s64, 28
	s_cselect_b32 s5, s0, s5
	s_cselect_b32 s4, s1, s4
	s_cselect_b32 s59, s13, s37
	s_cselect_b32 s58, s15, s36
	v_lshl_add_u64 v[198:199], s[46:47], 0, v[144:145]
	s_add_i32 m0, s21, 0xc000
	ds_read_b128 v[160:163], v172
	ds_read_b128 v[164:167], v172 offset:1024
	ds_read_b128 v[174:177], v172 offset:2048
	ds_read_b128 v[178:181], v172 offset:3072
	ds_read_b128 v[182:185], v172 offset:4096
	ds_read_b128 v[186:189], v172 offset:5120
	ds_read_b128 v[190:193], v172 offset:6144
	ds_read_b128 v[194:197], v172 offset:7168
	global_load_lds_dwordx4 v[198:199], off
	v_lshl_add_u64 v[198:199], s[46:47], 0, v[146:147]
	s_add_i32 m0, s21, 0xe000
	s_nop 0
	global_load_lds_dwordx4 v[198:199], off
	s_waitcnt lgkmcnt(8)
	s_barrier
	s_waitcnt lgkmcnt(0)
	s_waitcnt lgkmcnt(0)
	v_mfma_f32_16x16x32_bf16 v[124:127], v[128:131], v[160:163], v[124:127]
	v_mfma_f32_16x16x32_bf16 v[120:123], v[152:155], v[160:163], v[120:123]
	v_mfma_f32_16x16x32_bf16 v[116:119], v[128:131], v[174:177], v[116:119]
	v_mfma_f32_16x16x32_bf16 v[112:115], v[152:155], v[174:177], v[112:115]
	v_mfma_f32_16x16x32_bf16 v[108:111], v[128:131], v[182:185], v[108:111]
	v_mfma_f32_16x16x32_bf16 v[104:107], v[152:155], v[182:185], v[104:107]
	v_mfma_f32_16x16x32_bf16 v[100:103], v[128:131], v[190:193], v[100:103]
	v_mfma_f32_16x16x32_bf16 v[96:99], v[152:155], v[190:193], v[96:99]
	v_mfma_f32_16x16x32_bf16 v[124:127], v[132:135], v[164:167], v[124:127]
	v_mfma_f32_16x16x32_bf16 v[120:123], v[156:159], v[164:167], v[120:123]
	v_mfma_f32_16x16x32_bf16 v[116:119], v[132:135], v[178:181], v[116:119]
	v_mfma_f32_16x16x32_bf16 v[112:115], v[156:159], v[178:181], v[112:115]
	v_mfma_f32_16x16x32_bf16 v[108:111], v[132:135], v[186:189], v[108:111]
	v_mfma_f32_16x16x32_bf16 v[104:107], v[156:159], v[186:189], v[104:107]
	v_mfma_f32_16x16x32_bf16 v[100:103], v[132:135], v[194:197], v[100:103]
	v_mfma_f32_16x16x32_bf16 v[96:99], v[156:159], v[194:197], v[96:99]
	s_barrier
	s_add_i32 s42, s60, s24
	v_lshl_add_u64 v[214:215], s[58:59], 0, v[140:141]
	s_mov_b32 m0, s42
	ds_read_b128 v[198:201], v173
	ds_read_b128 v[202:205], v173 offset:1024
	ds_read_b128 v[206:209], v173 offset:2048
	ds_read_b128 v[210:213], v173 offset:3072
	global_load_lds_dwordx4 v[214:215], off
	v_lshl_add_u64 v[216:217], s[58:59], 0, v[136:137]
	s_add_i32 m0, s42, 0x2000
	s_nop 0
	global_load_lds_dwordx4 v[216:217], off
	s_barrier
	s_waitcnt lgkmcnt(0)
	s_waitcnt lgkmcnt(0)
	v_mfma_f32_16x16x32_bf16 v[68:71], v[198:201], v[160:163], v[68:71]
	v_mfma_f32_16x16x32_bf16 v[64:67], v[206:209], v[160:163], v[64:67]
	v_mfma_f32_16x16x32_bf16 v[52:55], v[198:201], v[174:177], v[52:55]
	v_mfma_f32_16x16x32_bf16 v[48:51], v[206:209], v[174:177], v[48:51]
	v_mfma_f32_16x16x32_bf16 v[44:47], v[198:201], v[182:185], v[44:47]
	v_mfma_f32_16x16x32_bf16 v[40:43], v[206:209], v[182:185], v[40:43]
	v_mfma_f32_16x16x32_bf16 v[36:39], v[198:201], v[190:193], v[36:39]
	v_mfma_f32_16x16x32_bf16 v[32:35], v[206:209], v[190:193], v[32:35]
	v_mfma_f32_16x16x32_bf16 v[68:71], v[202:205], v[164:167], v[68:71]
	v_mfma_f32_16x16x32_bf16 v[64:67], v[210:213], v[164:167], v[64:67]
	v_mfma_f32_16x16x32_bf16 v[52:55], v[202:205], v[178:181], v[52:55]
	v_mfma_f32_16x16x32_bf16 v[48:51], v[210:213], v[178:181], v[48:51]
	v_mfma_f32_16x16x32_bf16 v[44:47], v[202:205], v[186:189], v[44:47]
	v_mfma_f32_16x16x32_bf16 v[40:43], v[210:213], v[186:189], v[40:43]
	v_mfma_f32_16x16x32_bf16 v[36:39], v[202:205], v[194:197], v[36:39]
	v_mfma_f32_16x16x32_bf16 v[32:35], v[210:213], v[194:197], v[32:35]
	s_mov_b32 m0, s21
	v_lshl_add_u64 v[218:219], s[4:5], 0, v[142:143]
	s_barrier
	s_waitcnt vmcnt(8)
	ds_read_b128 v[160:163], v172 offset:16384
	ds_read_b128 v[164:167], v172 offset:17408
	ds_read_b128 v[174:177], v172 offset:18432
	ds_read_b128 v[178:181], v172 offset:19456
	ds_read_b128 v[182:185], v172 offset:20480
	ds_read_b128 v[186:189], v172 offset:21504
	ds_read_b128 v[190:193], v172 offset:22528
	ds_read_b128 v[194:197], v172 offset:23552
	global_load_lds_dwordx4 v[218:219], off
	v_lshl_add_u64 v[220:221], s[4:5], 0, v[138:139]
	s_mov_b32 m0, s28
	s_nop 0
	global_load_lds_dwordx4 v[220:221], off
	s_barrier
	s_waitcnt lgkmcnt(0)
	s_waitcnt lgkmcnt(0)
	v_mfma_f32_16x16x32_bf16 v[92:95], v[128:131], v[160:163], v[92:95]
	v_mfma_f32_16x16x32_bf16 v[88:91], v[152:155], v[160:163], v[88:91]
	v_mfma_f32_16x16x32_bf16 v[84:87], v[128:131], v[174:177], v[84:87]
	v_mfma_f32_16x16x32_bf16 v[80:83], v[152:155], v[174:177], v[80:83]
	v_mfma_f32_16x16x32_bf16 v[76:79], v[128:131], v[182:185], v[76:79]
	v_mfma_f32_16x16x32_bf16 v[72:75], v[152:155], v[182:185], v[72:75]
	v_mfma_f32_16x16x32_bf16 v[60:63], v[128:131], v[190:193], v[60:63]
	v_mfma_f32_16x16x32_bf16 v[56:59], v[152:155], v[190:193], v[56:59]
	v_mfma_f32_16x16x32_bf16 v[92:95], v[132:135], v[164:167], v[92:95]
	v_mfma_f32_16x16x32_bf16 v[88:91], v[156:159], v[164:167], v[88:91]
	v_mfma_f32_16x16x32_bf16 v[84:87], v[132:135], v[178:181], v[84:87]
	v_mfma_f32_16x16x32_bf16 v[80:83], v[156:159], v[178:181], v[80:83]
	v_mfma_f32_16x16x32_bf16 v[76:79], v[132:135], v[186:189], v[76:79]
	v_mfma_f32_16x16x32_bf16 v[72:75], v[156:159], v[186:189], v[72:75]
	v_mfma_f32_16x16x32_bf16 v[60:63], v[132:135], v[194:197], v[60:63]
	v_mfma_f32_16x16x32_bf16 v[56:59], v[156:159], v[194:197], v[56:59]
	s_barrier
	s_add_u32 s42, s58, 0x80000
	s_addc_u32 s43, s59, 0
	s_add_i32 s44, s61, s24
	v_lshl_add_u64 v[128:129], s[42:43], 0, v[140:141]
	s_mov_b32 m0, s44
	s_nop 0
	global_load_lds_dwordx4 v[128:129], off
	v_lshl_add_u64 v[128:129], s[42:43], 0, v[136:137]
	s_add_i32 m0, s44, 0x2000
	s_nop 0
	global_load_lds_dwordx4 v[128:129], off
	v_add_u32_e32 v156, 0x18000, v169
	ds_read_b128 v[128:131], v156
	ds_read_b128 v[132:135], v156 offset:1024
	ds_read_b128 v[152:155], v156 offset:2048
	ds_read_b128 v[156:159], v156 offset:3072
	s_waitcnt vmcnt(6)
	s_barrier
	v_mfma_f32_16x16x32_bf16 v[28:31], v[198:201], v[160:163], v[28:31]
	v_mfma_f32_16x16x32_bf16 v[24:27], v[206:209], v[160:163], v[24:27]
	v_mfma_f32_16x16x32_bf16 v[20:23], v[198:201], v[174:177], v[20:23]
	v_mfma_f32_16x16x32_bf16 v[16:19], v[206:209], v[174:177], v[16:19]
	v_mfma_f32_16x16x32_bf16 v[12:15], v[198:201], v[182:185], v[12:15]
	v_mfma_f32_16x16x32_bf16 v[8:11], v[206:209], v[182:185], v[8:11]
	v_mfma_f32_16x16x32_bf16 v[4:7], v[198:201], v[190:193], v[4:7]
	v_mfma_f32_16x16x32_bf16 v[0:3], v[206:209], v[190:193], v[0:3]
	v_mfma_f32_16x16x32_bf16 v[28:31], v[202:205], v[164:167], v[28:31]
	v_mfma_f32_16x16x32_bf16 v[24:27], v[210:213], v[164:167], v[24:27]
	v_mfma_f32_16x16x32_bf16 v[20:23], v[202:205], v[178:181], v[20:23]
	v_mfma_f32_16x16x32_bf16 v[16:19], v[210:213], v[178:181], v[16:19]
	v_mfma_f32_16x16x32_bf16 v[12:15], v[202:205], v[186:189], v[12:15]
	v_mfma_f32_16x16x32_bf16 v[8:11], v[210:213], v[186:189], v[8:11]
	v_mfma_f32_16x16x32_bf16 v[4:7], v[202:205], v[194:197], v[4:7]
	v_mfma_f32_16x16x32_bf16 v[0:3], v[210:213], v[194:197], v[0:3]
	s_add_i32 s42, 0, 0x18000
	s_barrier
	s_add_u32 s4, s4, 0x80000
	s_addc_u32 s5, s5, 0
	s_mov_b32 m0, s29
	v_lshl_add_u64 v[198:199], s[4:5], 0, v[142:143]
	ds_read_b128 v[160:163], v172 offset:32768
	ds_read_b128 v[164:167], v172 offset:33792
	ds_read_b128 v[174:177], v172 offset:34816
	ds_read_b128 v[178:181], v172 offset:35840
	ds_read_b128 v[182:185], v172 offset:36864
	ds_read_b128 v[186:189], v172 offset:37888
	ds_read_b128 v[190:193], v172 offset:38912
	ds_read_b128 v[194:197], v172 offset:39936
	global_load_lds_dwordx4 v[198:199], off
	v_lshl_add_u64 v[198:199], s[4:5], 0, v[138:139]
	s_mov_b32 m0, s33
	s_nop 0
	global_load_lds_dwordx4 v[198:199], off
	s_waitcnt lgkmcnt(8)
	s_barrier
	s_waitcnt lgkmcnt(0)
	s_waitcnt lgkmcnt(0)
	v_mfma_f32_16x16x32_bf16 v[124:127], v[128:131], v[160:163], v[124:127]
	v_mfma_f32_16x16x32_bf16 v[120:123], v[152:155], v[160:163], v[120:123]
	v_mfma_f32_16x16x32_bf16 v[116:119], v[128:131], v[174:177], v[116:119]
	v_mfma_f32_16x16x32_bf16 v[112:115], v[152:155], v[174:177], v[112:115]
	v_mfma_f32_16x16x32_bf16 v[108:111], v[128:131], v[182:185], v[108:111]
	v_mfma_f32_16x16x32_bf16 v[104:107], v[152:155], v[182:185], v[104:107]
	v_mfma_f32_16x16x32_bf16 v[100:103], v[128:131], v[190:193], v[100:103]
	v_mfma_f32_16x16x32_bf16 v[96:99], v[152:155], v[190:193], v[96:99]
	v_mfma_f32_16x16x32_bf16 v[124:127], v[132:135], v[164:167], v[124:127]
	v_mfma_f32_16x16x32_bf16 v[120:123], v[156:159], v[164:167], v[120:123]
	v_mfma_f32_16x16x32_bf16 v[116:119], v[132:135], v[178:181], v[116:119]
	v_mfma_f32_16x16x32_bf16 v[112:115], v[156:159], v[178:181], v[112:115]
	v_mfma_f32_16x16x32_bf16 v[108:111], v[132:135], v[186:189], v[108:111]
	v_mfma_f32_16x16x32_bf16 v[104:107], v[156:159], v[186:189], v[104:107]
	v_mfma_f32_16x16x32_bf16 v[100:103], v[132:135], v[194:197], v[100:103]
	v_mfma_f32_16x16x32_bf16 v[96:99], v[156:159], v[194:197], v[96:99]
	s_barrier
	s_add_i32 s43, 0, 0x1c000
	s_add_i32 s4, s42, s24
	v_add_u32_e32 v210, s43, v169
	v_lshl_add_u64 v[214:215], v[214:215], 0, s[10:11]
	s_mov_b32 m0, s4
	ds_read_b128 v[198:201], v210
	ds_read_b128 v[202:205], v210 offset:1024
	ds_read_b128 v[206:209], v210 offset:2048
	ds_read_b128 v[210:213], v210 offset:3072
	global_load_lds_dwordx4 v[214:215], off
	v_lshl_add_u64 v[214:215], v[216:217], 0, s[10:11]
	s_add_i32 m0, s4, 0x2000
	s_nop 0
	global_load_lds_dwordx4 v[214:215], off
	s_barrier
	s_waitcnt lgkmcnt(0)
	s_waitcnt lgkmcnt(0)
	v_mfma_f32_16x16x32_bf16 v[68:71], v[198:201], v[160:163], v[68:71]
	v_mfma_f32_16x16x32_bf16 v[64:67], v[206:209], v[160:163], v[64:67]
	v_mfma_f32_16x16x32_bf16 v[52:55], v[198:201], v[174:177], v[52:55]
	v_mfma_f32_16x16x32_bf16 v[48:51], v[206:209], v[174:177], v[48:51]
	v_mfma_f32_16x16x32_bf16 v[44:47], v[198:201], v[182:185], v[44:47]
	v_mfma_f32_16x16x32_bf16 v[40:43], v[206:209], v[182:185], v[40:43]
	v_mfma_f32_16x16x32_bf16 v[36:39], v[198:201], v[190:193], v[36:39]
	v_mfma_f32_16x16x32_bf16 v[32:35], v[206:209], v[190:193], v[32:35]
	v_mfma_f32_16x16x32_bf16 v[68:71], v[202:205], v[164:167], v[68:71]
	v_mfma_f32_16x16x32_bf16 v[64:67], v[210:213], v[164:167], v[64:67]
	v_mfma_f32_16x16x32_bf16 v[52:55], v[202:205], v[178:181], v[52:55]
	v_mfma_f32_16x16x32_bf16 v[48:51], v[210:213], v[178:181], v[48:51]
	v_mfma_f32_16x16x32_bf16 v[44:47], v[202:205], v[186:189], v[44:47]
	v_mfma_f32_16x16x32_bf16 v[40:43], v[210:213], v[186:189], v[40:43]
	v_mfma_f32_16x16x32_bf16 v[36:39], v[202:205], v[194:197], v[36:39]
	v_mfma_f32_16x16x32_bf16 v[32:35], v[210:213], v[194:197], v[32:35]
	s_mov_b32 m0, s41
	v_lshl_add_u64 v[214:215], v[218:219], 0, s[10:11]
	s_barrier
	s_waitcnt vmcnt(8)
	ds_read_b128 v[160:163], v172 offset:49152
	ds_read_b128 v[164:167], v172 offset:50176
	ds_read_b128 v[174:177], v172 offset:51200
	ds_read_b128 v[178:181], v172 offset:52224
	ds_read_b128 v[182:185], v172 offset:53248
	ds_read_b128 v[186:189], v172 offset:54272
	ds_read_b128 v[190:193], v172 offset:55296
	ds_read_b128 v[194:197], v172 offset:56320
	global_load_lds_dwordx4 v[214:215], off
	v_lshl_add_u64 v[214:215], v[220:221], 0, s[10:11]
	s_mov_b32 m0, s53
	s_nop 0
	global_load_lds_dwordx4 v[214:215], off
	s_barrier
	s_waitcnt lgkmcnt(0)
	s_waitcnt lgkmcnt(0)
	v_mfma_f32_16x16x32_bf16 v[92:95], v[128:131], v[160:163], v[92:95]
	v_mfma_f32_16x16x32_bf16 v[88:91], v[152:155], v[160:163], v[88:91]
	v_mfma_f32_16x16x32_bf16 v[84:87], v[128:131], v[174:177], v[84:87]
	v_mfma_f32_16x16x32_bf16 v[80:83], v[152:155], v[174:177], v[80:83]
	v_mfma_f32_16x16x32_bf16 v[76:79], v[128:131], v[182:185], v[76:79]
	v_mfma_f32_16x16x32_bf16 v[72:75], v[152:155], v[182:185], v[72:75]
	v_mfma_f32_16x16x32_bf16 v[60:63], v[128:131], v[190:193], v[60:63]
	v_mfma_f32_16x16x32_bf16 v[56:59], v[152:155], v[190:193], v[56:59]
	v_mfma_f32_16x16x32_bf16 v[92:95], v[132:135], v[164:167], v[92:95]
	v_mfma_f32_16x16x32_bf16 v[88:91], v[156:159], v[164:167], v[88:91]
	v_mfma_f32_16x16x32_bf16 v[84:87], v[132:135], v[178:181], v[84:87]
	v_mfma_f32_16x16x32_bf16 v[80:83], v[156:159], v[178:181], v[80:83]
	v_mfma_f32_16x16x32_bf16 v[76:79], v[132:135], v[186:189], v[76:79]
	v_mfma_f32_16x16x32_bf16 v[72:75], v[156:159], v[186:189], v[72:75]
	v_mfma_f32_16x16x32_bf16 v[60:63], v[132:135], v[194:197], v[60:63]
	v_mfma_f32_16x16x32_bf16 v[56:59], v[156:159], v[194:197], v[56:59]
	s_barrier
	s_add_u32 s4, s58, 0x80080
	s_addc_u32 s5, s59, 0
	s_add_i32 s42, s43, s24
	v_lshl_add_u64 v[128:129], s[4:5], 0, v[140:141]
	s_mov_b32 m0, s42
	s_nop 0
	global_load_lds_dwordx4 v[128:129], off
	v_lshl_add_u64 v[128:129], s[4:5], 0, v[136:137]
	s_add_i32 m0, s42, 0x2000
	s_nop 0
	global_load_lds_dwordx4 v[128:129], off
	ds_read_b128 v[128:131], v171
	ds_read_b128 v[132:135], v171 offset:1024
	ds_read_b128 v[152:155], v171 offset:2048
	ds_read_b128 v[156:159], v171 offset:3072
	s_waitcnt vmcnt(6)
	s_barrier
	v_mfma_f32_16x16x32_bf16 v[28:31], v[198:201], v[160:163], v[28:31]
	v_mfma_f32_16x16x32_bf16 v[24:27], v[206:209], v[160:163], v[24:27]
	v_mfma_f32_16x16x32_bf16 v[20:23], v[198:201], v[174:177], v[20:23]
	v_mfma_f32_16x16x32_bf16 v[16:19], v[206:209], v[174:177], v[16:19]
	v_mfma_f32_16x16x32_bf16 v[12:15], v[198:201], v[182:185], v[12:15]
	v_mfma_f32_16x16x32_bf16 v[8:11], v[206:209], v[182:185], v[8:11]
	v_mfma_f32_16x16x32_bf16 v[4:7], v[198:201], v[190:193], v[4:7]
	v_mfma_f32_16x16x32_bf16 v[0:3], v[206:209], v[190:193], v[0:3]
	v_mfma_f32_16x16x32_bf16 v[28:31], v[202:205], v[164:167], v[28:31]
	v_mfma_f32_16x16x32_bf16 v[24:27], v[210:213], v[164:167], v[24:27]
	v_mfma_f32_16x16x32_bf16 v[20:23], v[202:205], v[178:181], v[20:23]
	v_mfma_f32_16x16x32_bf16 v[16:19], v[210:213], v[178:181], v[16:19]
	v_mfma_f32_16x16x32_bf16 v[12:15], v[202:205], v[186:189], v[12:15]
	v_mfma_f32_16x16x32_bf16 v[8:11], v[210:213], v[186:189], v[8:11]
	v_mfma_f32_16x16x32_bf16 v[4:7], v[202:205], v[194:197], v[4:7]
	v_mfma_f32_16x16x32_bf16 v[0:3], v[210:213], v[194:197], v[0:3]
	s_add_i32 s64, s64, 2
	s_add_u32 s46, s46, 0x100
	s_addc_u32 s47, s47, 0
	s_add_u32 s36, s36, 0x100
	s_addc_u32 s37, s37, 0
	s_cmp_gt_u32 s64, 29
	s_barrier
	s_cbranch_scc0 .LBB0_1234
	v_lshl_or_b32 v152, s63, 8, v170
	v_ashrrev_i32_e32 v153, 31, v152
	v_lshl_add_u64 v[164:165], v[152:153], 2, s[8:9]
	flat_load_dwordx4 v[132:135], v[164:165]
	flat_load_dwordx4 v[128:131], v[164:165] offset:16
	v_lshl_add_u32 v182, s20, 8, v168
	v_mov_b64_e32 v[166:167], s[48:49]
	v_add_u32_e32 v159, 0x80, v182
	v_mad_i64_i32 v[154:155], s[0:1], v182, s62, v[166:167]
	v_or_b32_e32 v156, 16, v182
	v_or_b32_e32 v157, 32, v182
	v_or_b32_e32 v158, 48, v182
	v_lshlrev_b64 v[174:175], 1, v[152:153]
	v_mad_i64_i32 v[178:179], s[0:1], v159, s62, v[166:167]
	v_add_u32_e32 v160, 0x90, v182
	v_mad_i64_i32 v[152:153], s[0:1], v156, s62, v[166:167]
	v_mad_i64_i32 v[156:157], s[0:1], v157, s62, v[166:167]
	v_mad_i64_i32 v[176:177], s[0:1], v158, s62, v[166:167]
	v_lshl_add_u64 v[162:163], v[154:155], 0, v[174:175]
	v_lshl_add_u64 v[154:155], v[178:179], 0, v[174:175]
	v_mad_i64_i32 v[180:181], s[0:1], v160, s62, v[166:167]
	v_lshl_add_u64 v[160:161], v[152:153], 0, v[174:175]
	v_lshl_add_u64 v[158:159], v[156:157], 0, v[174:175]
	v_lshl_add_u64 v[156:157], v[176:177], 0, v[174:175]
	v_lshl_add_u64 v[152:153], v[180:181], 0, v[174:175]
	s_and_b64 vcc, exec, s[6:7]
	s_mov_b32 s63, s12
	s_mov_b32 s20, s14
	s_mov_b64 s[58:59], s[18:19]
	s_mov_b64 s[36:37], s[16:17]
	s_waitcnt vmcnt(0) lgkmcnt(0)
	v_pk_add_f32 v[124:125], v[124:125], v[132:133]
	v_pk_add_f32 v[178:179], v[72:73], v[128:129]
	s_nop 1
	v_cvt_pk_bf16_f32 v72, v124, v125
	v_pk_add_f32 v[126:127], v[126:127], v[134:135]
	v_pk_add_f32 v[122:123], v[122:123], v[130:131]
	v_pk_add_f32 v[120:121], v[120:121], v[128:129]
	v_pk_add_f32 v[116:117], v[116:117], v[132:133]
	v_pk_add_f32 v[176:177], v[74:75], v[130:131]
	s_nop 1
	v_cvt_pk_bf16_f32 v73, v126, v127
	s_nop 1
	v_cvt_pk_bf16_f32 v74, v120, v121
	s_nop 1
	v_cvt_pk_bf16_f32 v75, v122, v123
	global_store_dwordx4 v[162:163], v[72:75], off
	v_pk_add_f32 v[118:119], v[118:119], v[134:135]
	v_pk_add_f32 v[114:115], v[114:115], v[130:131]
	s_nop 1
	v_cvt_pk_bf16_f32 v72, v116, v117
	v_pk_add_f32 v[112:113], v[112:113], v[128:129]
	v_pk_add_f32 v[108:109], v[108:109], v[132:133]
	s_nop 1
	v_cvt_pk_bf16_f32 v73, v118, v119
	s_nop 1
	v_cvt_pk_bf16_f32 v74, v112, v113
	s_nop 1
	v_cvt_pk_bf16_f32 v75, v114, v115
	global_store_dwordx4 v[160:161], v[72:75], off
	v_pk_add_f32 v[110:111], v[110:111], v[134:135]
	v_pk_add_f32 v[106:107], v[106:107], v[130:131]
	s_nop 1
	v_cvt_pk_bf16_f32 v72, v108, v109
	v_pk_add_f32 v[104:105], v[104:105], v[128:129]
	v_pk_add_f32 v[100:101], v[100:101], v[132:133]
	s_nop 1
	v_cvt_pk_bf16_f32 v73, v110, v111
	s_nop 1
	v_cvt_pk_bf16_f32 v74, v104, v105
	s_nop 1
	v_cvt_pk_bf16_f32 v75, v106, v107
	global_store_dwordx4 v[158:159], v[72:75], off
	v_pk_add_f32 v[102:103], v[102:103], v[134:135]
	v_pk_add_f32 v[98:99], v[98:99], v[130:131]
	s_nop 1
	v_cvt_pk_bf16_f32 v72, v100, v101
	v_pk_add_f32 v[96:97], v[96:97], v[128:129]
	v_pk_add_f32 v[92:93], v[92:93], v[132:133]
	s_nop 1
	v_cvt_pk_bf16_f32 v73, v102, v103
	s_nop 1
	v_cvt_pk_bf16_f32 v74, v96, v97
	s_nop 1
	v_cvt_pk_bf16_f32 v75, v98, v99
	global_store_dwordx4 v[156:157], v[72:75], off
	v_pk_add_f32 v[94:95], v[94:95], v[134:135]
	v_pk_add_f32 v[90:91], v[90:91], v[130:131]
	s_nop 1
	v_cvt_pk_bf16_f32 v72, v92, v93
	v_pk_add_f32 v[88:89], v[88:89], v[128:129]
	v_pk_add_f32 v[84:85], v[84:85], v[132:133]
	v_pk_add_f32 v[76:77], v[76:77], v[132:133]
	s_nop 1
	v_cvt_pk_bf16_f32 v73, v94, v95
	s_nop 1
	v_cvt_pk_bf16_f32 v74, v88, v89
	s_nop 1
	v_cvt_pk_bf16_f32 v75, v90, v91
	global_store_dwordx4 v[154:155], v[72:75], off
	v_pk_add_f32 v[86:87], v[86:87], v[134:135]
	v_pk_add_f32 v[82:83], v[82:83], v[130:131]
	s_nop 1
	v_cvt_pk_bf16_f32 v72, v84, v85
	v_pk_add_f32 v[80:81], v[80:81], v[128:129]
	s_nop 1
	v_cvt_pk_bf16_f32 v73, v86, v87
	v_pk_add_f32 v[78:79], v[78:79], v[134:135]
	s_nop 1
	v_cvt_pk_bf16_f32 v74, v80, v81
	s_nop 1
	v_cvt_pk_bf16_f32 v75, v82, v83
	global_store_dwordx4 v[152:153], v[72:75], off
	v_pk_add_f32 v[60:61], v[60:61], v[132:133]
	v_pk_add_f32 v[62:63], v[62:63], v[134:135]
	s_nop 1
	v_cvt_pk_bf16_f32 v72, v76, v77
	v_add_u32_e32 v76, 0xa0, v182
	v_mad_i64_i32 v[76:77], s[0:1], v76, s62, v[166:167]
	s_nop 1
	v_cvt_pk_bf16_f32 v73, v78, v79
	v_lshl_add_u64 v[76:77], v[76:77], 0, v[174:175]
	s_nop 1
	v_cvt_pk_bf16_f32 v74, v178, v179
	s_nop 1
	v_cvt_pk_bf16_f32 v75, v176, v177
	global_store_dwordx4 v[76:77], v[72:75], off
	s_nop 1
	v_pk_add_f32 v[72:73], v[58:59], v[130:131]
	v_pk_add_f32 v[58:59], v[56:57], v[128:129]
	s_nop 1
	v_cvt_pk_bf16_f32 v56, v60, v61
	v_add_u32_e32 v60, 0xb0, v182
	v_mad_i64_i32 v[60:61], s[0:1], v60, s62, v[166:167]
	s_nop 1
	v_cvt_pk_bf16_f32 v57, v62, v63
	s_nop 1
	v_cvt_pk_bf16_f32 v58, v58, v59
	s_nop 1
	v_cvt_pk_bf16_f32 v59, v72, v73
	v_lshl_add_u64 v[72:73], v[60:61], 0, v[174:175]
	global_store_dwordx4 v[72:73], v[56:59], off
	flat_load_dwordx4 v[56:59], v[164:165] offset:512
	s_nop 0
	flat_load_dwordx4 v[60:63], v[164:165] offset:528
	s_waitcnt vmcnt(0) lgkmcnt(0)
	v_pk_add_f32 v[70:71], v[70:71], v[58:59]
	v_pk_add_f32 v[68:69], v[68:69], v[56:57]
	v_pk_add_f32 v[66:67], v[66:67], v[62:63]
	v_pk_add_f32 v[64:65], v[64:65], v[60:61]
	v_pk_add_f32 v[54:55], v[54:55], v[58:59]
	v_pk_add_f32 v[52:53], v[52:53], v[56:57]
	v_pk_add_f32 v[46:47], v[46:47], v[58:59]
	v_pk_add_f32 v[44:45], v[44:45], v[56:57]
	v_pk_add_f32 v[38:39], v[38:39], v[58:59]
	v_pk_add_f32 v[36:37], v[36:37], v[56:57]
	v_pk_add_f32 v[30:31], v[30:31], v[58:59]
	v_pk_add_f32 v[28:29], v[28:29], v[56:57]
	v_pk_add_f32 v[22:23], v[22:23], v[58:59]
	v_pk_add_f32 v[20:21], v[20:21], v[56:57]
	v_pk_add_f32 v[14:15], v[14:15], v[58:59]
	v_pk_add_f32 v[12:13], v[12:13], v[56:57]
	v_pk_add_f32 v[6:7], v[6:7], v[58:59]
	v_pk_add_f32 v[4:5], v[4:5], v[56:57]
	v_pk_add_f32 v[56:57], v[2:3], v[62:63]
	v_pk_add_f32 v[58:59], v[0:1], v[60:61]
	s_nop 1
	v_cvt_pk_bf16_f32 v0, v68, v69
	s_nop 1
	v_cvt_pk_bf16_f32 v1, v70, v71
	s_nop 1
	v_cvt_pk_bf16_f32 v2, v64, v65
	s_nop 1
	v_cvt_pk_bf16_f32 v3, v66, v67
	v_pk_add_f32 v[50:51], v[50:51], v[62:63]
	v_pk_add_f32 v[48:49], v[48:49], v[60:61]
	global_store_dwordx4 v[162:163], v[0:3], off offset:256
	v_pk_add_f32 v[42:43], v[42:43], v[62:63]
	v_pk_add_f32 v[40:41], v[40:41], v[60:61]
	s_nop 1
	v_cvt_pk_bf16_f32 v0, v52, v53
	s_nop 1
	v_cvt_pk_bf16_f32 v1, v54, v55
	s_nop 1
	v_cvt_pk_bf16_f32 v2, v48, v49
	s_nop 1
	v_cvt_pk_bf16_f32 v3, v50, v51
	global_store_dwordx4 v[160:161], v[0:3], off offset:256
	v_pk_add_f32 v[34:35], v[34:35], v[62:63]
	v_pk_add_f32 v[32:33], v[32:33], v[60:61]
	s_nop 1
	v_cvt_pk_bf16_f32 v0, v44, v45
	s_nop 1
	v_cvt_pk_bf16_f32 v1, v46, v47
	s_nop 1
	v_cvt_pk_bf16_f32 v2, v40, v41
	s_nop 1
	v_cvt_pk_bf16_f32 v3, v42, v43
	global_store_dwordx4 v[158:159], v[0:3], off offset:256
	v_pk_add_f32 v[26:27], v[26:27], v[62:63]
	v_pk_add_f32 v[24:25], v[24:25], v[60:61]
	s_nop 1
	v_cvt_pk_bf16_f32 v0, v36, v37
	s_nop 1
	v_cvt_pk_bf16_f32 v1, v38, v39
	s_nop 1
	v_cvt_pk_bf16_f32 v2, v32, v33
	s_nop 1
	v_cvt_pk_bf16_f32 v3, v34, v35
	global_store_dwordx4 v[156:157], v[0:3], off offset:256
	v_pk_add_f32 v[18:19], v[18:19], v[62:63]
	v_pk_add_f32 v[16:17], v[16:17], v[60:61]
	s_nop 1
	v_cvt_pk_bf16_f32 v0, v28, v29
	s_nop 1
	v_cvt_pk_bf16_f32 v1, v30, v31
	s_nop 1
	v_cvt_pk_bf16_f32 v2, v24, v25
	s_nop 1
	v_cvt_pk_bf16_f32 v3, v26, v27
	global_store_dwordx4 v[154:155], v[0:3], off offset:256
	v_pk_add_f32 v[10:11], v[10:11], v[62:63]
	v_pk_add_f32 v[8:9], v[8:9], v[60:61]
	s_nop 1
	v_cvt_pk_bf16_f32 v0, v20, v21
	s_nop 1
	v_cvt_pk_bf16_f32 v1, v22, v23
	s_nop 1
	v_cvt_pk_bf16_f32 v2, v16, v17
	s_nop 1
	v_cvt_pk_bf16_f32 v3, v18, v19
	global_store_dwordx4 v[152:153], v[0:3], off offset:256
	s_nop 1
	s_nop 1
	v_cvt_pk_bf16_f32 v0, v12, v13
	s_nop 1
	v_cvt_pk_bf16_f32 v1, v14, v15
	s_nop 1
	v_cvt_pk_bf16_f32 v2, v8, v9
	s_nop 1
	v_cvt_pk_bf16_f32 v3, v10, v11
	global_store_dwordx4 v[76:77], v[0:3], off offset:256
	s_nop 1
	s_nop 1
	v_cvt_pk_bf16_f32 v0, v4, v5
	s_nop 1
	v_cvt_pk_bf16_f32 v1, v6, v7
	s_nop 1
	v_cvt_pk_bf16_f32 v2, v58, v59
	s_nop 1
	v_cvt_pk_bf16_f32 v3, v56, v57
	global_store_dwordx4 v[72:73], v[0:3], off offset:256
	s_cbranch_vccz .LBB0_1231
	s_waitcnt vmcnt(0)
	s_cmpk_gt_u32 s23, 0xff
	s_cbranch_scc1 .LBB0_1238
	s_barrier

.LBB0_1532:
	s_ashr_i32 s61, s60, 31
	v_cmp_lt_i64_e32 vcc, s[0:1], v[146:147]
	s_lshl_b64 s[0:1], s[60:61], 20
	s_add_u32 s62, s38, s0
	s_addc_u32 s63, s39, s1
	s_and_b64 s[0:1], vcc, exec
	s_cselect_b32 s0, s63, s9
	s_cselect_b32 s1, s62, s8
	s_ashr_i32 s59, s58, 31
	s_lshl_b64 s[4:5], s[58:59], 20
	v_readlane_b32 s42, v255, 26
	v_readlane_b32 s43, v255, 27
	s_add_u32 s64, s42, s4
	s_addc_u32 s65, s43, s5
	s_and_b64 s[4:5], vcc, exec
	s_cselect_b32 s59, s65, s69
	s_cselect_b32 s61, s64, s68
	s_add_u32 s76, s68, 0x100
	v_mov_b32_e32 v0, 0
	s_addc_u32 s77, s69, 0
	s_mov_b32 s78, -2
	v_mov_b32_e32 v1, v0
	v_mov_b32_e32 v2, v0
	v_mov_b32_e32 v3, v0
	v_mov_b32_e32 v32, v0
	v_mov_b32_e32 v33, v0
	v_mov_b32_e32 v34, v0
	v_mov_b32_e32 v35, v0
	v_mov_b32_e32 v4, v0
	v_mov_b32_e32 v5, v0
	v_mov_b32_e32 v6, v0
	v_mov_b32_e32 v7, v0
	v_mov_b32_e32 v36, v0
	v_mov_b32_e32 v37, v0
	v_mov_b32_e32 v38, v0
	v_mov_b32_e32 v39, v0
	v_mov_b32_e32 v8, v0
	v_mov_b32_e32 v9, v0
	v_mov_b32_e32 v10, v0
	v_mov_b32_e32 v11, v0
	v_mov_b32_e32 v40, v0
	v_mov_b32_e32 v41, v0
	v_mov_b32_e32 v42, v0
	v_mov_b32_e32 v43, v0
	v_mov_b32_e32 v12, v0
	v_mov_b32_e32 v13, v0
	v_mov_b32_e32 v14, v0
	v_mov_b32_e32 v15, v0
	v_mov_b32_e32 v44, v0
	v_mov_b32_e32 v45, v0
	v_mov_b32_e32 v46, v0
	v_mov_b32_e32 v47, v0
	v_mov_b32_e32 v64, v0
	v_mov_b32_e32 v65, v0
	v_mov_b32_e32 v66, v0
	v_mov_b32_e32 v67, v0
	v_mov_b32_e32 v96, v0
	v_mov_b32_e32 v97, v0
	v_mov_b32_e32 v98, v0
	v_mov_b32_e32 v99, v0
	v_mov_b32_e32 v68, v0
	v_mov_b32_e32 v69, v0
	v_mov_b32_e32 v70, v0
	v_mov_b32_e32 v71, v0
	v_mov_b32_e32 v100, v0
	v_mov_b32_e32 v101, v0
	v_mov_b32_e32 v102, v0
	v_mov_b32_e32 v103, v0
	v_mov_b32_e32 v72, v0
	v_mov_b32_e32 v73, v0
	v_mov_b32_e32 v74, v0
	v_mov_b32_e32 v75, v0
	v_mov_b32_e32 v104, v0
	v_mov_b32_e32 v105, v0
	v_mov_b32_e32 v106, v0
	v_mov_b32_e32 v107, v0
	v_mov_b32_e32 v76, v0
	v_mov_b32_e32 v77, v0
	v_mov_b32_e32 v78, v0
	v_mov_b32_e32 v79, v0
	v_mov_b32_e32 v108, v0
	v_mov_b32_e32 v109, v0
	v_mov_b32_e32 v110, v0
	v_mov_b32_e32 v111, v0
	v_mov_b32_e32 v16, v0
	v_mov_b32_e32 v17, v0
	v_mov_b32_e32 v18, v0
	v_mov_b32_e32 v19, v0
	v_mov_b32_e32 v48, v0
	v_mov_b32_e32 v49, v0
	v_mov_b32_e32 v50, v0
	v_mov_b32_e32 v51, v0
	v_mov_b32_e32 v20, v0
	v_mov_b32_e32 v21, v0
	v_mov_b32_e32 v22, v0
	v_mov_b32_e32 v23, v0
	v_mov_b32_e32 v52, v0
	v_mov_b32_e32 v53, v0
	v_mov_b32_e32 v54, v0
	v_mov_b32_e32 v55, v0
	v_mov_b32_e32 v24, v0
	v_mov_b32_e32 v25, v0
	v_mov_b32_e32 v26, v0
	v_mov_b32_e32 v27, v0
	v_mov_b32_e32 v56, v0
	v_mov_b32_e32 v57, v0
	v_mov_b32_e32 v58, v0
	v_mov_b32_e32 v59, v0
	v_mov_b32_e32 v28, v0
	v_mov_b32_e32 v29, v0
	v_mov_b32_e32 v30, v0
	v_mov_b32_e32 v31, v0
	v_mov_b32_e32 v60, v0
	v_mov_b32_e32 v61, v0
	v_mov_b32_e32 v62, v0
	v_mov_b32_e32 v63, v0
	v_mov_b32_e32 v80, v0
	v_mov_b32_e32 v81, v0
	v_mov_b32_e32 v82, v0
	v_mov_b32_e32 v83, v0
	v_mov_b32_e32 v112, v0
	v_mov_b32_e32 v113, v0
	v_mov_b32_e32 v114, v0
	v_mov_b32_e32 v115, v0
	v_mov_b32_e32 v84, v0
	v_mov_b32_e32 v85, v0
	v_mov_b32_e32 v86, v0
	v_mov_b32_e32 v87, v0
	v_mov_b32_e32 v116, v0
	v_mov_b32_e32 v117, v0
	v_mov_b32_e32 v118, v0
	v_mov_b32_e32 v119, v0
	v_mov_b32_e32 v88, v0
	v_mov_b32_e32 v89, v0
	v_mov_b32_e32 v90, v0
	v_mov_b32_e32 v91, v0
	v_mov_b32_e32 v120, v0
	v_mov_b32_e32 v121, v0
	v_mov_b32_e32 v122, v0
	v_mov_b32_e32 v123, v0
	v_mov_b32_e32 v92, v0
	v_mov_b32_e32 v93, v0
	v_mov_b32_e32 v94, v0
	v_mov_b32_e32 v95, v0
	v_mov_b32_e32 v124, v0
	v_mov_b32_e32 v125, v0
	v_mov_b32_e32 v126, v0
	v_mov_b32_e32 v127, v0
	ds_read_b128 v[128:131], v165
	ds_read_b128 v[132:135], v165 offset:1024
	ds_read_b128 v[150:153], v165 offset:2048
	ds_read_b128 v[154:157], v165 offset:3072
.LBB0_1533:
	s_add_u32 s68, s8, 0x100
	s_addc_u32 s69, s9, 0
	s_cmp_eq_u32 s78, 28
	s_cselect_b32 s5, s0, s69
	s_cselect_b32 s4, s1, s68
	s_cselect_b32 s71, s59, s77
	s_cselect_b32 s70, s61, s76
	v_lshl_add_u64 v[136:137], s[8:9], 0, v[142:143]
	s_add_i32 m0, s25, 0xc000
	ds_read_b128 v[158:161], v166
	ds_read_b128 v[168:171], v166 offset:1024
	ds_read_b128 v[172:175], v166 offset:2048
	ds_read_b128 v[176:179], v166 offset:3072
	ds_read_b128 v[180:183], v166 offset:4096
	ds_read_b128 v[184:187], v166 offset:5120
	ds_read_b128 v[188:191], v166 offset:6144
	ds_read_b128 v[192:195], v166 offset:7168
	global_load_lds_dwordx4 v[136:137], off
	v_lshl_add_u64 v[136:137], s[8:9], 0, v[144:145]
	s_add_i32 m0, s25, 0xe000
	s_nop 0
	global_load_lds_dwordx4 v[136:137], off
	s_waitcnt lgkmcnt(8)
	s_barrier
	s_waitcnt lgkmcnt(0)
	s_waitcnt lgkmcnt(0)
	v_mfma_f32_16x16x32_bf16 v[124:127], v[128:131], v[158:161], v[124:127]
	v_mfma_f32_16x16x32_bf16 v[92:95], v[150:153], v[158:161], v[92:95]
	v_mfma_f32_16x16x32_bf16 v[120:123], v[128:131], v[172:175], v[120:123]
	v_mfma_f32_16x16x32_bf16 v[88:91], v[150:153], v[172:175], v[88:91]
	v_mfma_f32_16x16x32_bf16 v[116:119], v[128:131], v[180:183], v[116:119]
	v_mfma_f32_16x16x32_bf16 v[84:87], v[150:153], v[180:183], v[84:87]
	v_mfma_f32_16x16x32_bf16 v[112:115], v[128:131], v[188:191], v[112:115]
	v_mfma_f32_16x16x32_bf16 v[80:83], v[150:153], v[188:191], v[80:83]
	v_mfma_f32_16x16x32_bf16 v[124:127], v[132:135], v[168:171], v[124:127]
	v_mfma_f32_16x16x32_bf16 v[92:95], v[154:157], v[168:171], v[92:95]
	v_mfma_f32_16x16x32_bf16 v[120:123], v[132:135], v[176:179], v[120:123]
	v_mfma_f32_16x16x32_bf16 v[88:91], v[154:157], v[176:179], v[88:91]
	v_mfma_f32_16x16x32_bf16 v[116:119], v[132:135], v[184:187], v[116:119]
	v_mfma_f32_16x16x32_bf16 v[84:87], v[154:157], v[184:187], v[84:87]
	v_mfma_f32_16x16x32_bf16 v[112:115], v[132:135], v[192:195], v[112:115]
	v_mfma_f32_16x16x32_bf16 v[80:83], v[154:157], v[192:195], v[80:83]
	s_barrier
	s_add_i32 s8, s41, s24
	v_lshl_add_u64 v[136:137], s[70:71], 0, v[140:141]
	s_mov_b32 m0, s8
	ds_read_b128 v[196:199], v167
	ds_read_b128 v[200:203], v167 offset:1024
	ds_read_b128 v[204:207], v167 offset:2048
	ds_read_b128 v[208:211], v167 offset:3072
	global_load_lds_dwordx4 v[136:137], off
	v_lshl_add_u64 v[212:213], s[70:71], 0, v[138:139]
	s_add_i32 m0, s8, 0x2000
	s_nop 0
	global_load_lds_dwordx4 v[212:213], off
	s_barrier
	s_waitcnt lgkmcnt(0)
	s_waitcnt lgkmcnt(0)
	v_mfma_f32_16x16x32_bf16 v[60:63], v[196:199], v[158:161], v[60:63]
	v_mfma_f32_16x16x32_bf16 v[28:31], v[204:207], v[158:161], v[28:31]
	v_mfma_f32_16x16x32_bf16 v[56:59], v[196:199], v[172:175], v[56:59]
	v_mfma_f32_16x16x32_bf16 v[24:27], v[204:207], v[172:175], v[24:27]
	v_mfma_f32_16x16x32_bf16 v[52:55], v[196:199], v[180:183], v[52:55]
	v_mfma_f32_16x16x32_bf16 v[20:23], v[204:207], v[180:183], v[20:23]
	v_mfma_f32_16x16x32_bf16 v[48:51], v[196:199], v[188:191], v[48:51]
	v_mfma_f32_16x16x32_bf16 v[16:19], v[204:207], v[188:191], v[16:19]
	v_mfma_f32_16x16x32_bf16 v[60:63], v[200:203], v[168:171], v[60:63]
	v_mfma_f32_16x16x32_bf16 v[28:31], v[208:211], v[168:171], v[28:31]
	v_mfma_f32_16x16x32_bf16 v[56:59], v[200:203], v[176:179], v[56:59]
	v_mfma_f32_16x16x32_bf16 v[24:27], v[208:211], v[176:179], v[24:27]
	v_mfma_f32_16x16x32_bf16 v[52:55], v[200:203], v[184:187], v[52:55]
	v_mfma_f32_16x16x32_bf16 v[20:23], v[208:211], v[184:187], v[20:23]
	v_mfma_f32_16x16x32_bf16 v[48:51], v[200:203], v[192:195], v[48:51]
	v_mfma_f32_16x16x32_bf16 v[16:19], v[208:211], v[192:195], v[16:19]
	s_mov_b32 m0, s25
	v_lshl_add_u64 v[214:215], s[4:5], 0, v[140:141]
	s_barrier
	s_waitcnt vmcnt(8)
	ds_read_b128 v[158:161], v166 offset:16384
	ds_read_b128 v[168:171], v166 offset:17408
	ds_read_b128 v[172:175], v166 offset:18432
	ds_read_b128 v[176:179], v166 offset:19456
	ds_read_b128 v[180:183], v166 offset:20480
	ds_read_b128 v[184:187], v166 offset:21504
	ds_read_b128 v[188:191], v166 offset:22528
	ds_read_b128 v[192:195], v166 offset:23552
	global_load_lds_dwordx4 v[214:215], off
	v_lshl_add_u64 v[216:217], s[4:5], 0, v[138:139]
	s_mov_b32 m0, s28
	s_nop 0
	global_load_lds_dwordx4 v[216:217], off
	s_barrier
	s_waitcnt lgkmcnt(0)
	s_waitcnt lgkmcnt(0)
	v_mfma_f32_16x16x32_bf16 v[108:111], v[128:131], v[158:161], v[108:111]
	v_mfma_f32_16x16x32_bf16 v[76:79], v[150:153], v[158:161], v[76:79]
	v_mfma_f32_16x16x32_bf16 v[104:107], v[128:131], v[172:175], v[104:107]
	v_mfma_f32_16x16x32_bf16 v[72:75], v[150:153], v[172:175], v[72:75]
	v_mfma_f32_16x16x32_bf16 v[100:103], v[128:131], v[180:183], v[100:103]
	v_mfma_f32_16x16x32_bf16 v[68:71], v[150:153], v[180:183], v[68:71]
	v_mfma_f32_16x16x32_bf16 v[96:99], v[128:131], v[188:191], v[96:99]
	v_mfma_f32_16x16x32_bf16 v[64:67], v[150:153], v[188:191], v[64:67]
	v_mfma_f32_16x16x32_bf16 v[108:111], v[132:135], v[168:171], v[108:111]
	v_mfma_f32_16x16x32_bf16 v[76:79], v[154:157], v[168:171], v[76:79]
	v_mfma_f32_16x16x32_bf16 v[104:107], v[132:135], v[176:179], v[104:107]
	v_mfma_f32_16x16x32_bf16 v[72:75], v[154:157], v[176:179], v[72:75]
	v_mfma_f32_16x16x32_bf16 v[100:103], v[132:135], v[184:187], v[100:103]
	v_mfma_f32_16x16x32_bf16 v[68:71], v[154:157], v[184:187], v[68:71]
	v_mfma_f32_16x16x32_bf16 v[96:99], v[132:135], v[192:195], v[96:99]
	v_mfma_f32_16x16x32_bf16 v[64:67], v[154:157], v[192:195], v[64:67]
	s_barrier
	s_add_u32 s8, s70, 0x80000
	s_addc_u32 s9, s71, 0
	s_add_i32 s42, s53, s24
	v_lshl_add_u64 v[128:129], s[8:9], 0, v[140:141]
	s_mov_b32 m0, s42
	s_nop 0
	global_load_lds_dwordx4 v[128:129], off
	v_lshl_add_u64 v[128:129], s[8:9], 0, v[138:139]
	s_add_i32 m0, s42, 0x2000
	s_nop 0
	global_load_lds_dwordx4 v[128:129], off
	v_add_u32_e32 v154, 0x18000, v163
	ds_read_b128 v[128:131], v154
	ds_read_b128 v[132:135], v154 offset:1024
	ds_read_b128 v[150:153], v154 offset:2048
	ds_read_b128 v[154:157], v154 offset:3072
	s_waitcnt vmcnt(6)
	s_barrier
	v_mfma_f32_16x16x32_bf16 v[44:47], v[196:199], v[158:161], v[44:47]
	v_mfma_f32_16x16x32_bf16 v[12:15], v[204:207], v[158:161], v[12:15]
	v_mfma_f32_16x16x32_bf16 v[40:43], v[196:199], v[172:175], v[40:43]
	v_mfma_f32_16x16x32_bf16 v[8:11], v[204:207], v[172:175], v[8:11]
	v_mfma_f32_16x16x32_bf16 v[36:39], v[196:199], v[180:183], v[36:39]
	v_mfma_f32_16x16x32_bf16 v[4:7], v[204:207], v[180:183], v[4:7]
	v_mfma_f32_16x16x32_bf16 v[32:35], v[196:199], v[188:191], v[32:35]
	v_mfma_f32_16x16x32_bf16 v[0:3], v[204:207], v[188:191], v[0:3]
	v_mfma_f32_16x16x32_bf16 v[44:47], v[200:203], v[168:171], v[44:47]
	v_mfma_f32_16x16x32_bf16 v[12:15], v[208:211], v[168:171], v[12:15]
	v_mfma_f32_16x16x32_bf16 v[40:43], v[200:203], v[176:179], v[40:43]
	v_mfma_f32_16x16x32_bf16 v[8:11], v[208:211], v[176:179], v[8:11]
	v_mfma_f32_16x16x32_bf16 v[36:39], v[200:203], v[184:187], v[36:39]
	v_mfma_f32_16x16x32_bf16 v[4:7], v[208:211], v[184:187], v[4:7]
	v_mfma_f32_16x16x32_bf16 v[32:35], v[200:203], v[192:195], v[32:35]
	v_mfma_f32_16x16x32_bf16 v[0:3], v[208:211], v[192:195], v[0:3]
	s_add_i32 s8, 0, 0x18000
	s_barrier
	s_add_u32 s4, s4, 0x80000
	s_addc_u32 s5, s5, 0
	s_mov_b32 m0, s29
	v_lshl_add_u64 v[196:197], s[4:5], 0, v[140:141]
	ds_read_b128 v[158:161], v166 offset:32768
	ds_read_b128 v[168:171], v166 offset:33792
	ds_read_b128 v[172:175], v166 offset:34816
	ds_read_b128 v[176:179], v166 offset:35840
	ds_read_b128 v[180:183], v166 offset:36864
	ds_read_b128 v[184:187], v166 offset:37888
	ds_read_b128 v[188:191], v166 offset:38912
	ds_read_b128 v[192:195], v166 offset:39936
	global_load_lds_dwordx4 v[196:197], off
	v_lshl_add_u64 v[196:197], s[4:5], 0, v[138:139]
	s_mov_b32 m0, s33
	s_nop 0
	global_load_lds_dwordx4 v[196:197], off
	s_waitcnt lgkmcnt(8)
	s_barrier
	s_waitcnt lgkmcnt(0)
	s_waitcnt lgkmcnt(0)
	v_mfma_f32_16x16x32_bf16 v[124:127], v[128:131], v[158:161], v[124:127]
	v_mfma_f32_16x16x32_bf16 v[92:95], v[150:153], v[158:161], v[92:95]
	v_mfma_f32_16x16x32_bf16 v[120:123], v[128:131], v[172:175], v[120:123]
	v_mfma_f32_16x16x32_bf16 v[88:91], v[150:153], v[172:175], v[88:91]
	v_mfma_f32_16x16x32_bf16 v[116:119], v[128:131], v[180:183], v[116:119]
	v_mfma_f32_16x16x32_bf16 v[84:87], v[150:153], v[180:183], v[84:87]
	v_mfma_f32_16x16x32_bf16 v[112:115], v[128:131], v[188:191], v[112:115]
	v_mfma_f32_16x16x32_bf16 v[80:83], v[150:153], v[188:191], v[80:83]
	v_mfma_f32_16x16x32_bf16 v[124:127], v[132:135], v[168:171], v[124:127]
	v_mfma_f32_16x16x32_bf16 v[92:95], v[154:157], v[168:171], v[92:95]
	v_mfma_f32_16x16x32_bf16 v[120:123], v[132:135], v[176:179], v[120:123]
	v_mfma_f32_16x16x32_bf16 v[88:91], v[154:157], v[176:179], v[88:91]
	v_mfma_f32_16x16x32_bf16 v[116:119], v[132:135], v[184:187], v[116:119]
	v_mfma_f32_16x16x32_bf16 v[84:87], v[154:157], v[184:187], v[84:87]
	v_mfma_f32_16x16x32_bf16 v[112:115], v[132:135], v[192:195], v[112:115]
	v_mfma_f32_16x16x32_bf16 v[80:83], v[154:157], v[192:195], v[80:83]
	s_barrier
	s_add_i32 s9, 0, 0x1c000
	s_add_i32 s4, s8, s24
	v_add_u32_e32 v208, s9, v163
	v_lshl_add_u64 v[136:137], v[136:137], 0, s[16:17]
	s_mov_b32 m0, s4
	ds_read_b128 v[196:199], v208
	ds_read_b128 v[200:203], v208 offset:1024
	ds_read_b128 v[204:207], v208 offset:2048
	ds_read_b128 v[208:211], v208 offset:3072
	global_load_lds_dwordx4 v[136:137], off
	v_lshl_add_u64 v[136:137], v[212:213], 0, s[16:17]
	s_add_i32 m0, s4, 0x2000
	s_nop 0
	global_load_lds_dwordx4 v[136:137], off
	s_barrier
	s_waitcnt lgkmcnt(0)
	s_waitcnt lgkmcnt(0)
	v_mfma_f32_16x16x32_bf16 v[60:63], v[196:199], v[158:161], v[60:63]
	v_mfma_f32_16x16x32_bf16 v[28:31], v[204:207], v[158:161], v[28:31]
	v_mfma_f32_16x16x32_bf16 v[56:59], v[196:199], v[172:175], v[56:59]
	v_mfma_f32_16x16x32_bf16 v[24:27], v[204:207], v[172:175], v[24:27]
	v_mfma_f32_16x16x32_bf16 v[52:55], v[196:199], v[180:183], v[52:55]
	v_mfma_f32_16x16x32_bf16 v[20:23], v[204:207], v[180:183], v[20:23]
	v_mfma_f32_16x16x32_bf16 v[48:51], v[196:199], v[188:191], v[48:51]
	v_mfma_f32_16x16x32_bf16 v[16:19], v[204:207], v[188:191], v[16:19]
	v_mfma_f32_16x16x32_bf16 v[60:63], v[200:203], v[168:171], v[60:63]
	v_mfma_f32_16x16x32_bf16 v[28:31], v[208:211], v[168:171], v[28:31]
	v_mfma_f32_16x16x32_bf16 v[56:59], v[200:203], v[176:179], v[56:59]
	v_mfma_f32_16x16x32_bf16 v[24:27], v[208:211], v[176:179], v[24:27]
	v_mfma_f32_16x16x32_bf16 v[52:55], v[200:203], v[184:187], v[52:55]
	v_mfma_f32_16x16x32_bf16 v[20:23], v[208:211], v[184:187], v[20:23]
	v_mfma_f32_16x16x32_bf16 v[48:51], v[200:203], v[192:195], v[48:51]
	v_mfma_f32_16x16x32_bf16 v[16:19], v[208:211], v[192:195], v[16:19]
	s_mov_b32 m0, s37
	v_lshl_add_u64 v[136:137], v[214:215], 0, s[16:17]
	s_barrier
	s_waitcnt vmcnt(8)
	ds_read_b128 v[158:161], v166 offset:49152
	ds_read_b128 v[168:171], v166 offset:50176
	ds_read_b128 v[172:175], v166 offset:51200
	ds_read_b128 v[176:179], v166 offset:52224
	ds_read_b128 v[180:183], v166 offset:53248
	ds_read_b128 v[184:187], v166 offset:54272
	ds_read_b128 v[188:191], v166 offset:55296
	ds_read_b128 v[192:195], v166 offset:56320
	global_load_lds_dwordx4 v[136:137], off
	v_lshl_add_u64 v[136:137], v[216:217], 0, s[16:17]
	s_mov_b32 m0, s40
	s_nop 0
	global_load_lds_dwordx4 v[136:137], off
	s_barrier
	s_waitcnt lgkmcnt(0)
	s_waitcnt lgkmcnt(0)
	v_mfma_f32_16x16x32_bf16 v[108:111], v[128:131], v[158:161], v[108:111]
	v_mfma_f32_16x16x32_bf16 v[76:79], v[150:153], v[158:161], v[76:79]
	v_mfma_f32_16x16x32_bf16 v[104:107], v[128:131], v[172:175], v[104:107]
	v_mfma_f32_16x16x32_bf16 v[72:75], v[150:153], v[172:175], v[72:75]
	v_mfma_f32_16x16x32_bf16 v[100:103], v[128:131], v[180:183], v[100:103]
	v_mfma_f32_16x16x32_bf16 v[68:71], v[150:153], v[180:183], v[68:71]
	v_mfma_f32_16x16x32_bf16 v[96:99], v[128:131], v[188:191], v[96:99]
	v_mfma_f32_16x16x32_bf16 v[64:67], v[150:153], v[188:191], v[64:67]
	v_mfma_f32_16x16x32_bf16 v[108:111], v[132:135], v[168:171], v[108:111]
	v_mfma_f32_16x16x32_bf16 v[76:79], v[154:157], v[168:171], v[76:79]
	v_mfma_f32_16x16x32_bf16 v[104:107], v[132:135], v[176:179], v[104:107]
	v_mfma_f32_16x16x32_bf16 v[72:75], v[154:157], v[176:179], v[72:75]
	v_mfma_f32_16x16x32_bf16 v[100:103], v[132:135], v[184:187], v[100:103]
	v_mfma_f32_16x16x32_bf16 v[68:71], v[154:157], v[184:187], v[68:71]
	v_mfma_f32_16x16x32_bf16 v[96:99], v[132:135], v[192:195], v[96:99]
	v_mfma_f32_16x16x32_bf16 v[64:67], v[154:157], v[192:195], v[64:67]
	s_barrier
	s_add_u32 s4, s70, 0x80080
	s_addc_u32 s5, s71, 0
	s_add_i32 s8, s9, s24
	v_lshl_add_u64 v[128:129], s[4:5], 0, v[140:141]
	s_mov_b32 m0, s8
	s_nop 0
	global_load_lds_dwordx4 v[128:129], off
	v_lshl_add_u64 v[128:129], s[4:5], 0, v[138:139]
	s_add_i32 m0, s8, 0x2000
	s_nop 0
	global_load_lds_dwordx4 v[128:129], off
	ds_read_b128 v[128:131], v165
	ds_read_b128 v[132:135], v165 offset:1024
	ds_read_b128 v[150:153], v165 offset:2048
	ds_read_b128 v[154:157], v165 offset:3072
	s_waitcnt vmcnt(6)
	s_barrier
	v_mfma_f32_16x16x32_bf16 v[44:47], v[196:199], v[158:161], v[44:47]
	v_mfma_f32_16x16x32_bf16 v[12:15], v[204:207], v[158:161], v[12:15]
	v_mfma_f32_16x16x32_bf16 v[40:43], v[196:199], v[172:175], v[40:43]
	v_mfma_f32_16x16x32_bf16 v[8:11], v[204:207], v[172:175], v[8:11]
	v_mfma_f32_16x16x32_bf16 v[36:39], v[196:199], v[180:183], v[36:39]
	v_mfma_f32_16x16x32_bf16 v[4:7], v[204:207], v[180:183], v[4:7]
	v_mfma_f32_16x16x32_bf16 v[32:35], v[196:199], v[188:191], v[32:35]
	v_mfma_f32_16x16x32_bf16 v[0:3], v[204:207], v[188:191], v[0:3]
	v_mfma_f32_16x16x32_bf16 v[44:47], v[200:203], v[168:171], v[44:47]
	v_mfma_f32_16x16x32_bf16 v[12:15], v[208:211], v[168:171], v[12:15]
	v_mfma_f32_16x16x32_bf16 v[40:43], v[200:203], v[176:179], v[40:43]
	v_mfma_f32_16x16x32_bf16 v[8:11], v[208:211], v[176:179], v[8:11]
	v_mfma_f32_16x16x32_bf16 v[36:39], v[200:203], v[184:187], v[36:39]
	v_mfma_f32_16x16x32_bf16 v[4:7], v[208:211], v[184:187], v[4:7]
	v_mfma_f32_16x16x32_bf16 v[32:35], v[200:203], v[192:195], v[32:35]
	v_mfma_f32_16x16x32_bf16 v[0:3], v[208:211], v[192:195], v[0:3]
	s_add_i32 s78, s78, 2
	s_add_u32 s76, s76, 0x100
	s_addc_u32 s77, s77, 0
	s_cmp_gt_u32 s78, 29
	s_mov_b64 s[8:9], s[68:69]
	s_barrier
	s_cbranch_scc0 .LBB0_1533
	v_lshl_or_b32 v160, s75, 8, v164
	v_ashrrev_i32_e32 v161, 31, v160
	v_lshl_add_u64 v[128:129], v[160:161], 2, s[14:15]
	global_load_dwordx4 v[130:133], v[128:129], off
	v_cndmask_b32_e64 v129, 0, 1, s[18:19]
	v_mov_b32_e32 v128, 0
	v_cmp_ne_u32_e64 s[8:9], 1, v129
	s_andn2_b64 vcc, exec, s[18:19]
	v_lshl_add_u64 v[158:159], v[160:161], 2, s[10:11]
	v_mov_b32_e32 v134, 0
	v_mov_b32_e32 v135, 0
	v_mov_b32_e32 v136, 0
	v_mov_b32_e32 v137, 0
	s_cbranch_vccnz .LBB0_1536
	flat_load_dwordx4 v[134:137], v[158:159]

.LBB0_1675:
	s_ashr_i32 s13, s12, 31
	v_cmp_lt_i64_e32 vcc, s[0:1], v[140:141]
	s_lshl_b64 s[0:1], s[12:13], 20
	s_add_u32 s14, s38, s0
	s_addc_u32 s15, s39, s1
	s_and_b64 s[0:1], vcc, exec
	s_cselect_b32 s0, s15, s21
	s_cselect_b32 s1, s14, s20
	s_ashr_i32 s11, s10, 31
	s_lshl_b64 s[4:5], s[10:11], 20
	s_add_u32 s16, s56, s4
	s_addc_u32 s17, s57, s5
	s_and_b64 s[4:5], vcc, exec
	s_cselect_b32 s11, s17, s45
	s_cselect_b32 s13, s16, s44
	s_add_u32 s20, s20, 0x80080
	s_addc_u32 s21, s21, 0
	s_add_u32 s51, s44, 0x100
	v_mov_b32_e32 v0, 0
	s_addc_u32 s52, s45, 0
	s_mov_b32 s53, -2
	v_mov_b32_e32 v1, v0
	v_mov_b32_e32 v2, v0
	v_mov_b32_e32 v3, v0
	v_mov_b32_e32 v4, v0
	v_mov_b32_e32 v5, v0
	v_mov_b32_e32 v6, v0
	v_mov_b32_e32 v7, v0
	v_mov_b32_e32 v16, v0
	v_mov_b32_e32 v17, v0
	v_mov_b32_e32 v18, v0
	v_mov_b32_e32 v19, v0
	v_mov_b32_e32 v20, v0
	v_mov_b32_e32 v21, v0
	v_mov_b32_e32 v22, v0
	v_mov_b32_e32 v23, v0
	v_mov_b32_e32 v32, v0
	v_mov_b32_e32 v33, v0
	v_mov_b32_e32 v34, v0
	v_mov_b32_e32 v35, v0
	v_mov_b32_e32 v36, v0
	v_mov_b32_e32 v37, v0
	v_mov_b32_e32 v38, v0
	v_mov_b32_e32 v39, v0
	v_mov_b32_e32 v48, v0
	v_mov_b32_e32 v49, v0
	v_mov_b32_e32 v50, v0
	v_mov_b32_e32 v51, v0
	v_mov_b32_e32 v52, v0
	v_mov_b32_e32 v53, v0
	v_mov_b32_e32 v54, v0
	v_mov_b32_e32 v55, v0
	v_mov_b32_e32 v8, v0
	v_mov_b32_e32 v9, v0
	v_mov_b32_e32 v10, v0
	v_mov_b32_e32 v11, v0
	v_mov_b32_e32 v12, v0
	v_mov_b32_e32 v13, v0
	v_mov_b32_e32 v14, v0
	v_mov_b32_e32 v15, v0
	v_mov_b32_e32 v24, v0
	v_mov_b32_e32 v25, v0
	v_mov_b32_e32 v26, v0
	v_mov_b32_e32 v27, v0
	v_mov_b32_e32 v28, v0
	v_mov_b32_e32 v29, v0
	v_mov_b32_e32 v30, v0
	v_mov_b32_e32 v31, v0
	v_mov_b32_e32 v40, v0
	v_mov_b32_e32 v41, v0
	v_mov_b32_e32 v42, v0
	v_mov_b32_e32 v43, v0
	v_mov_b32_e32 v44, v0
	v_mov_b32_e32 v45, v0
	v_mov_b32_e32 v46, v0
	v_mov_b32_e32 v47, v0
	v_mov_b32_e32 v56, v0
	v_mov_b32_e32 v57, v0
	v_mov_b32_e32 v58, v0
	v_mov_b32_e32 v59, v0
	v_mov_b32_e32 v60, v0
	v_mov_b32_e32 v61, v0
	v_mov_b32_e32 v62, v0
	v_mov_b32_e32 v63, v0
	v_mov_b32_e32 v64, v0
	v_mov_b32_e32 v65, v0
	v_mov_b32_e32 v66, v0
	v_mov_b32_e32 v67, v0
	v_mov_b32_e32 v68, v0
	v_mov_b32_e32 v69, v0
	v_mov_b32_e32 v70, v0
	v_mov_b32_e32 v71, v0
	v_mov_b32_e32 v80, v0
	v_mov_b32_e32 v81, v0
	v_mov_b32_e32 v82, v0
	v_mov_b32_e32 v83, v0
	v_mov_b32_e32 v84, v0
	v_mov_b32_e32 v85, v0
	v_mov_b32_e32 v86, v0
	v_mov_b32_e32 v87, v0
	v_mov_b32_e32 v96, v0
	v_mov_b32_e32 v97, v0
	v_mov_b32_e32 v98, v0
	v_mov_b32_e32 v99, v0
	v_mov_b32_e32 v100, v0
	v_mov_b32_e32 v101, v0
	v_mov_b32_e32 v102, v0
	v_mov_b32_e32 v103, v0
	v_mov_b32_e32 v112, v0
	v_mov_b32_e32 v113, v0
	v_mov_b32_e32 v114, v0
	v_mov_b32_e32 v115, v0
	v_mov_b32_e32 v116, v0
	v_mov_b32_e32 v117, v0
	v_mov_b32_e32 v118, v0
	v_mov_b32_e32 v119, v0
	v_mov_b32_e32 v72, v0
	v_mov_b32_e32 v73, v0
	v_mov_b32_e32 v74, v0
	v_mov_b32_e32 v75, v0
	v_mov_b32_e32 v76, v0
	v_mov_b32_e32 v77, v0
	v_mov_b32_e32 v78, v0
	v_mov_b32_e32 v79, v0
	v_mov_b32_e32 v88, v0
	v_mov_b32_e32 v89, v0
	v_mov_b32_e32 v90, v0
	v_mov_b32_e32 v91, v0
	v_mov_b32_e32 v92, v0
	v_mov_b32_e32 v93, v0
	v_mov_b32_e32 v94, v0
	v_mov_b32_e32 v95, v0
	v_mov_b32_e32 v104, v0
	v_mov_b32_e32 v105, v0
	v_mov_b32_e32 v106, v0
	v_mov_b32_e32 v107, v0
	v_mov_b32_e32 v108, v0
	v_mov_b32_e32 v109, v0
	v_mov_b32_e32 v110, v0
	v_mov_b32_e32 v111, v0
	v_mov_b32_e32 v120, v0
	v_mov_b32_e32 v121, v0
	v_mov_b32_e32 v122, v0
	v_mov_b32_e32 v123, v0
	v_mov_b32_e32 v124, v0
	v_mov_b32_e32 v125, v0
	v_mov_b32_e32 v126, v0
	v_mov_b32_e32 v127, v0
	ds_read_b128 v[150:153], v147
	ds_read_b128 v[154:157], v147 offset:1024
	ds_read_b128 v[158:161], v147 offset:2048
	ds_read_b128 v[162:165], v147 offset:3072
.LBB0_1676:
	s_add_u32 s4, s20, 0xfff80080
	s_addc_u32 s5, s21, -1
	s_cmp_eq_u32 s53, 28
	s_cselect_b32 s5, s0, s5
	s_cselect_b32 s4, s1, s4
	s_cselect_b32 s45, s11, s52
	s_cselect_b32 s44, s13, s51
	v_lshl_add_u64 v[198:199], s[20:21], 0, v[136:137]
	s_add_i32 m0, s19, 0xc000
	ds_read_b128 v[166:169], v148
	ds_read_b128 v[170:173], v148 offset:1024
	ds_read_b128 v[174:177], v148 offset:2048
	ds_read_b128 v[178:181], v148 offset:3072
	ds_read_b128 v[182:185], v148 offset:4096
	ds_read_b128 v[186:189], v148 offset:5120
	ds_read_b128 v[190:193], v148 offset:6144
	ds_read_b128 v[194:197], v148 offset:7168
	global_load_lds_dwordx4 v[198:199], off
	v_lshl_add_u64 v[198:199], s[20:21], 0, v[138:139]
	s_add_i32 m0, s19, 0xe000
	s_nop 0
	global_load_lds_dwordx4 v[198:199], off
	s_waitcnt lgkmcnt(8)
	s_barrier
	s_waitcnt lgkmcnt(0)
	s_waitcnt lgkmcnt(0)
	v_mfma_f32_16x16x32_bf16 v[124:127], v[150:153], v[166:169], v[124:127]
	v_mfma_f32_16x16x32_bf16 v[120:123], v[158:161], v[166:169], v[120:123]
	v_mfma_f32_16x16x32_bf16 v[108:111], v[150:153], v[174:177], v[108:111]
	v_mfma_f32_16x16x32_bf16 v[104:107], v[158:161], v[174:177], v[104:107]
	v_mfma_f32_16x16x32_bf16 v[92:95], v[150:153], v[182:185], v[92:95]
	v_mfma_f32_16x16x32_bf16 v[88:91], v[158:161], v[182:185], v[88:91]
	v_mfma_f32_16x16x32_bf16 v[76:79], v[150:153], v[190:193], v[76:79]
	v_mfma_f32_16x16x32_bf16 v[72:75], v[158:161], v[190:193], v[72:75]
	v_mfma_f32_16x16x32_bf16 v[124:127], v[154:157], v[170:173], v[124:127]
	v_mfma_f32_16x16x32_bf16 v[120:123], v[162:165], v[170:173], v[120:123]
	v_mfma_f32_16x16x32_bf16 v[108:111], v[154:157], v[178:181], v[108:111]
	v_mfma_f32_16x16x32_bf16 v[104:107], v[162:165], v[178:181], v[104:107]
	v_mfma_f32_16x16x32_bf16 v[92:95], v[154:157], v[186:189], v[92:95]
	v_mfma_f32_16x16x32_bf16 v[88:91], v[162:165], v[186:189], v[88:91]
	v_mfma_f32_16x16x32_bf16 v[76:79], v[154:157], v[194:197], v[76:79]
	v_mfma_f32_16x16x32_bf16 v[72:75], v[162:165], v[194:197], v[72:75]
	s_barrier
	s_add_i32 s42, s41, s24
	v_lshl_add_u64 v[214:215], s[44:45], 0, v[132:133]
	s_mov_b32 m0, s42
	ds_read_b128 v[198:201], v149
	ds_read_b128 v[202:205], v149 offset:1024
	ds_read_b128 v[206:209], v149 offset:2048
	ds_read_b128 v[210:213], v149 offset:3072
	global_load_lds_dwordx4 v[214:215], off
	v_lshl_add_u64 v[216:217], s[44:45], 0, v[128:129]
	s_add_i32 m0, s42, 0x2000
	s_nop 0
	global_load_lds_dwordx4 v[216:217], off
	s_barrier
	s_waitcnt lgkmcnt(0)
	s_waitcnt lgkmcnt(0)
	v_mfma_f32_16x16x32_bf16 v[116:119], v[198:201], v[166:169], v[116:119]
	v_mfma_f32_16x16x32_bf16 v[112:115], v[206:209], v[166:169], v[112:115]
	v_mfma_f32_16x16x32_bf16 v[100:103], v[198:201], v[174:177], v[100:103]
	v_mfma_f32_16x16x32_bf16 v[96:99], v[206:209], v[174:177], v[96:99]
	v_mfma_f32_16x16x32_bf16 v[84:87], v[198:201], v[182:185], v[84:87]
	v_mfma_f32_16x16x32_bf16 v[80:83], v[206:209], v[182:185], v[80:83]
	v_mfma_f32_16x16x32_bf16 v[68:71], v[198:201], v[190:193], v[68:71]
	v_mfma_f32_16x16x32_bf16 v[64:67], v[206:209], v[190:193], v[64:67]
	v_mfma_f32_16x16x32_bf16 v[116:119], v[202:205], v[170:173], v[116:119]
	v_mfma_f32_16x16x32_bf16 v[112:115], v[210:213], v[170:173], v[112:115]
	v_mfma_f32_16x16x32_bf16 v[100:103], v[202:205], v[178:181], v[100:103]
	v_mfma_f32_16x16x32_bf16 v[96:99], v[210:213], v[178:181], v[96:99]
	v_mfma_f32_16x16x32_bf16 v[84:87], v[202:205], v[186:189], v[84:87]
	v_mfma_f32_16x16x32_bf16 v[80:83], v[210:213], v[186:189], v[80:83]
	v_mfma_f32_16x16x32_bf16 v[68:71], v[202:205], v[194:197], v[68:71]
	v_mfma_f32_16x16x32_bf16 v[64:67], v[210:213], v[194:197], v[64:67]
	s_mov_b32 m0, s19
	v_lshl_add_u64 v[218:219], s[4:5], 0, v[134:135]
	s_barrier
	s_waitcnt vmcnt(8)
	ds_read_b128 v[166:169], v148 offset:16384
	ds_read_b128 v[170:173], v148 offset:17408
	ds_read_b128 v[174:177], v148 offset:18432
	ds_read_b128 v[178:181], v148 offset:19456
	ds_read_b128 v[182:185], v148 offset:20480
	ds_read_b128 v[186:189], v148 offset:21504
	ds_read_b128 v[190:193], v148 offset:22528
	ds_read_b128 v[194:197], v148 offset:23552
	global_load_lds_dwordx4 v[218:219], off
	v_lshl_add_u64 v[220:221], s[4:5], 0, v[130:131]
	s_mov_b32 m0, s28
	s_nop 0
	global_load_lds_dwordx4 v[220:221], off
	s_barrier
	s_waitcnt lgkmcnt(0)
	s_waitcnt lgkmcnt(0)
	v_mfma_f32_16x16x32_bf16 v[60:63], v[150:153], v[166:169], v[60:63]
	v_mfma_f32_16x16x32_bf16 v[56:59], v[158:161], v[166:169], v[56:59]
	v_mfma_f32_16x16x32_bf16 v[44:47], v[150:153], v[174:177], v[44:47]
	v_mfma_f32_16x16x32_bf16 v[40:43], v[158:161], v[174:177], v[40:43]
	v_mfma_f32_16x16x32_bf16 v[28:31], v[150:153], v[182:185], v[28:31]
	v_mfma_f32_16x16x32_bf16 v[24:27], v[158:161], v[182:185], v[24:27]
	v_mfma_f32_16x16x32_bf16 v[12:15], v[150:153], v[190:193], v[12:15]
	v_mfma_f32_16x16x32_bf16 v[8:11], v[158:161], v[190:193], v[8:11]
	v_mfma_f32_16x16x32_bf16 v[60:63], v[154:157], v[170:173], v[60:63]
	v_mfma_f32_16x16x32_bf16 v[56:59], v[162:165], v[170:173], v[56:59]
	v_mfma_f32_16x16x32_bf16 v[44:47], v[154:157], v[178:181], v[44:47]
	v_mfma_f32_16x16x32_bf16 v[40:43], v[162:165], v[178:181], v[40:43]
	v_mfma_f32_16x16x32_bf16 v[28:31], v[154:157], v[186:189], v[28:31]
	v_mfma_f32_16x16x32_bf16 v[24:27], v[162:165], v[186:189], v[24:27]
	v_mfma_f32_16x16x32_bf16 v[12:15], v[154:157], v[194:197], v[12:15]
	v_mfma_f32_16x16x32_bf16 v[8:11], v[162:165], v[194:197], v[8:11]
	s_barrier
	s_add_u32 s42, s44, 0x80000
	s_addc_u32 s43, s45, 0
	s_add_i32 s54, s46, s24
	v_lshl_add_u64 v[150:151], s[42:43], 0, v[132:133]
	s_mov_b32 m0, s54
	s_nop 0
	global_load_lds_dwordx4 v[150:151], off
	v_lshl_add_u64 v[150:151], s[42:43], 0, v[128:129]
	s_add_i32 m0, s54, 0x2000
	s_nop 0
	global_load_lds_dwordx4 v[150:151], off
	v_add_u32_e32 v162, 0x18000, v145
	ds_read_b128 v[150:153], v162
	ds_read_b128 v[154:157], v162 offset:1024
	ds_read_b128 v[158:161], v162 offset:2048
	ds_read_b128 v[162:165], v162 offset:3072
	s_waitcnt vmcnt(6)
	s_barrier
	v_mfma_f32_16x16x32_bf16 v[52:55], v[198:201], v[166:169], v[52:55]
	v_mfma_f32_16x16x32_bf16 v[48:51], v[206:209], v[166:169], v[48:51]
	v_mfma_f32_16x16x32_bf16 v[36:39], v[198:201], v[174:177], v[36:39]
	v_mfma_f32_16x16x32_bf16 v[32:35], v[206:209], v[174:177], v[32:35]
	v_mfma_f32_16x16x32_bf16 v[20:23], v[198:201], v[182:185], v[20:23]
	v_mfma_f32_16x16x32_bf16 v[16:19], v[206:209], v[182:185], v[16:19]
	v_mfma_f32_16x16x32_bf16 v[4:7], v[198:201], v[190:193], v[4:7]
	v_mfma_f32_16x16x32_bf16 v[0:3], v[206:209], v[190:193], v[0:3]
	v_mfma_f32_16x16x32_bf16 v[52:55], v[202:205], v[170:173], v[52:55]
	v_mfma_f32_16x16x32_bf16 v[48:51], v[210:213], v[170:173], v[48:51]
	v_mfma_f32_16x16x32_bf16 v[36:39], v[202:205], v[178:181], v[36:39]
	v_mfma_f32_16x16x32_bf16 v[32:35], v[210:213], v[178:181], v[32:35]
	v_mfma_f32_16x16x32_bf16 v[20:23], v[202:205], v[186:189], v[20:23]
	v_mfma_f32_16x16x32_bf16 v[16:19], v[210:213], v[186:189], v[16:19]
	v_mfma_f32_16x16x32_bf16 v[4:7], v[202:205], v[194:197], v[4:7]
	v_mfma_f32_16x16x32_bf16 v[0:3], v[210:213], v[194:197], v[0:3]
	s_add_i32 s42, 0, 0x18000
	s_barrier
	s_add_u32 s4, s4, 0x80000
	s_addc_u32 s5, s5, 0
	s_mov_b32 m0, s29
	v_lshl_add_u64 v[198:199], s[4:5], 0, v[134:135]
	ds_read_b128 v[166:169], v148 offset:32768
	ds_read_b128 v[170:173], v148 offset:33792
	ds_read_b128 v[174:177], v148 offset:34816
	ds_read_b128 v[178:181], v148 offset:35840
	ds_read_b128 v[182:185], v148 offset:36864
	ds_read_b128 v[186:189], v148 offset:37888
	ds_read_b128 v[190:193], v148 offset:38912
	ds_read_b128 v[194:197], v148 offset:39936
	global_load_lds_dwordx4 v[198:199], off
	v_lshl_add_u64 v[198:199], s[4:5], 0, v[130:131]
	s_mov_b32 m0, s33
	s_nop 0
	global_load_lds_dwordx4 v[198:199], off
	s_waitcnt lgkmcnt(8)
	s_barrier
	s_waitcnt lgkmcnt(0)
	s_waitcnt lgkmcnt(0)
	v_mfma_f32_16x16x32_bf16 v[124:127], v[150:153], v[166:169], v[124:127]
	v_mfma_f32_16x16x32_bf16 v[120:123], v[158:161], v[166:169], v[120:123]
	v_mfma_f32_16x16x32_bf16 v[108:111], v[150:153], v[174:177], v[108:111]
	v_mfma_f32_16x16x32_bf16 v[104:107], v[158:161], v[174:177], v[104:107]
	v_mfma_f32_16x16x32_bf16 v[92:95], v[150:153], v[182:185], v[92:95]
	v_mfma_f32_16x16x32_bf16 v[88:91], v[158:161], v[182:185], v[88:91]
	v_mfma_f32_16x16x32_bf16 v[76:79], v[150:153], v[190:193], v[76:79]
	v_mfma_f32_16x16x32_bf16 v[72:75], v[158:161], v[190:193], v[72:75]
	v_mfma_f32_16x16x32_bf16 v[124:127], v[154:157], v[170:173], v[124:127]
	v_mfma_f32_16x16x32_bf16 v[120:123], v[162:165], v[170:173], v[120:123]
	v_mfma_f32_16x16x32_bf16 v[108:111], v[154:157], v[178:181], v[108:111]
	v_mfma_f32_16x16x32_bf16 v[104:107], v[162:165], v[178:181], v[104:107]
	v_mfma_f32_16x16x32_bf16 v[92:95], v[154:157], v[186:189], v[92:95]
	v_mfma_f32_16x16x32_bf16 v[88:91], v[162:165], v[186:189], v[88:91]
	v_mfma_f32_16x16x32_bf16 v[76:79], v[154:157], v[194:197], v[76:79]
	v_mfma_f32_16x16x32_bf16 v[72:75], v[162:165], v[194:197], v[72:75]
	s_barrier
	s_add_i32 s43, 0, 0x1c000
	s_add_i32 s4, s42, s24
	v_add_u32_e32 v210, s43, v145
	v_lshl_add_u64 v[214:215], v[214:215], 0, s[8:9]
	s_mov_b32 m0, s4
	ds_read_b128 v[198:201], v210
	ds_read_b128 v[202:205], v210 offset:1024
	ds_read_b128 v[206:209], v210 offset:2048
	ds_read_b128 v[210:213], v210 offset:3072
	global_load_lds_dwordx4 v[214:215], off
	v_lshl_add_u64 v[214:215], v[216:217], 0, s[8:9]
	s_add_i32 m0, s4, 0x2000
	s_nop 0
	global_load_lds_dwordx4 v[214:215], off
	s_barrier
	s_waitcnt lgkmcnt(0)
	s_waitcnt lgkmcnt(0)
	v_mfma_f32_16x16x32_bf16 v[116:119], v[198:201], v[166:169], v[116:119]
	v_mfma_f32_16x16x32_bf16 v[112:115], v[206:209], v[166:169], v[112:115]
	v_mfma_f32_16x16x32_bf16 v[100:103], v[198:201], v[174:177], v[100:103]
	v_mfma_f32_16x16x32_bf16 v[96:99], v[206:209], v[174:177], v[96:99]
	v_mfma_f32_16x16x32_bf16 v[84:87], v[198:201], v[182:185], v[84:87]
	v_mfma_f32_16x16x32_bf16 v[80:83], v[206:209], v[182:185], v[80:83]
	v_mfma_f32_16x16x32_bf16 v[68:71], v[198:201], v[190:193], v[68:71]
	v_mfma_f32_16x16x32_bf16 v[64:67], v[206:209], v[190:193], v[64:67]
	v_mfma_f32_16x16x32_bf16 v[116:119], v[202:205], v[170:173], v[116:119]
	v_mfma_f32_16x16x32_bf16 v[112:115], v[210:213], v[170:173], v[112:115]
	v_mfma_f32_16x16x32_bf16 v[100:103], v[202:205], v[178:181], v[100:103]
	v_mfma_f32_16x16x32_bf16 v[96:99], v[210:213], v[178:181], v[96:99]
	v_mfma_f32_16x16x32_bf16 v[84:87], v[202:205], v[186:189], v[84:87]
	v_mfma_f32_16x16x32_bf16 v[80:83], v[210:213], v[186:189], v[80:83]
	v_mfma_f32_16x16x32_bf16 v[68:71], v[202:205], v[194:197], v[68:71]
	v_mfma_f32_16x16x32_bf16 v[64:67], v[210:213], v[194:197], v[64:67]
	s_mov_b32 m0, s37
	v_lshl_add_u64 v[214:215], v[218:219], 0, s[8:9]
	s_barrier
	s_waitcnt vmcnt(8)
	ds_read_b128 v[166:169], v148 offset:49152
	ds_read_b128 v[170:173], v148 offset:50176
	ds_read_b128 v[174:177], v148 offset:51200
	ds_read_b128 v[178:181], v148 offset:52224
	ds_read_b128 v[182:185], v148 offset:53248
	ds_read_b128 v[186:189], v148 offset:54272
	ds_read_b128 v[190:193], v148 offset:55296
	ds_read_b128 v[194:197], v148 offset:56320
	global_load_lds_dwordx4 v[214:215], off
	v_lshl_add_u64 v[214:215], v[220:221], 0, s[8:9]
	s_mov_b32 m0, s40
	s_nop 0
	global_load_lds_dwordx4 v[214:215], off
	s_barrier
	s_waitcnt lgkmcnt(0)
	s_waitcnt lgkmcnt(0)
	v_mfma_f32_16x16x32_bf16 v[60:63], v[150:153], v[166:169], v[60:63]
	v_mfma_f32_16x16x32_bf16 v[56:59], v[158:161], v[166:169], v[56:59]
	v_mfma_f32_16x16x32_bf16 v[44:47], v[150:153], v[174:177], v[44:47]
	v_mfma_f32_16x16x32_bf16 v[40:43], v[158:161], v[174:177], v[40:43]
	v_mfma_f32_16x16x32_bf16 v[28:31], v[150:153], v[182:185], v[28:31]
	v_mfma_f32_16x16x32_bf16 v[24:27], v[158:161], v[182:185], v[24:27]
	v_mfma_f32_16x16x32_bf16 v[12:15], v[150:153], v[190:193], v[12:15]
	v_mfma_f32_16x16x32_bf16 v[8:11], v[158:161], v[190:193], v[8:11]
	v_mfma_f32_16x16x32_bf16 v[60:63], v[154:157], v[170:173], v[60:63]
	v_mfma_f32_16x16x32_bf16 v[56:59], v[162:165], v[170:173], v[56:59]
	v_mfma_f32_16x16x32_bf16 v[44:47], v[154:157], v[178:181], v[44:47]
	v_mfma_f32_16x16x32_bf16 v[40:43], v[162:165], v[178:181], v[40:43]
	v_mfma_f32_16x16x32_bf16 v[28:31], v[154:157], v[186:189], v[28:31]
	v_mfma_f32_16x16x32_bf16 v[24:27], v[162:165], v[186:189], v[24:27]
	v_mfma_f32_16x16x32_bf16 v[12:15], v[154:157], v[194:197], v[12:15]
	v_mfma_f32_16x16x32_bf16 v[8:11], v[162:165], v[194:197], v[8:11]
	s_barrier
	s_add_u32 s4, s44, 0x80080
	s_addc_u32 s5, s45, 0
	s_add_i32 s42, s43, s24
	v_lshl_add_u64 v[150:151], s[4:5], 0, v[132:133]
	s_mov_b32 m0, s42
	s_nop 0
	global_load_lds_dwordx4 v[150:151], off
	v_lshl_add_u64 v[150:151], s[4:5], 0, v[128:129]
	s_add_i32 m0, s42, 0x2000
	s_nop 0
	global_load_lds_dwordx4 v[150:151], off
	ds_read_b128 v[150:153], v147
	ds_read_b128 v[154:157], v147 offset:1024
	ds_read_b128 v[158:161], v147 offset:2048
	ds_read_b128 v[162:165], v147 offset:3072
	s_waitcnt vmcnt(6)
	s_barrier
	v_mfma_f32_16x16x32_bf16 v[52:55], v[198:201], v[166:169], v[52:55]
	v_mfma_f32_16x16x32_bf16 v[48:51], v[206:209], v[166:169], v[48:51]
	v_mfma_f32_16x16x32_bf16 v[36:39], v[198:201], v[174:177], v[36:39]
	v_mfma_f32_16x16x32_bf16 v[32:35], v[206:209], v[174:177], v[32:35]
	v_mfma_f32_16x16x32_bf16 v[20:23], v[198:201], v[182:185], v[20:23]
	v_mfma_f32_16x16x32_bf16 v[16:19], v[206:209], v[182:185], v[16:19]
	v_mfma_f32_16x16x32_bf16 v[4:7], v[198:201], v[190:193], v[4:7]
	v_mfma_f32_16x16x32_bf16 v[0:3], v[206:209], v[190:193], v[0:3]
	v_mfma_f32_16x16x32_bf16 v[52:55], v[202:205], v[170:173], v[52:55]
	v_mfma_f32_16x16x32_bf16 v[48:51], v[210:213], v[170:173], v[48:51]
	v_mfma_f32_16x16x32_bf16 v[36:39], v[202:205], v[178:181], v[36:39]
	v_mfma_f32_16x16x32_bf16 v[32:35], v[210:213], v[178:181], v[32:35]
	v_mfma_f32_16x16x32_bf16 v[20:23], v[202:205], v[186:189], v[20:23]
	v_mfma_f32_16x16x32_bf16 v[16:19], v[210:213], v[186:189], v[16:19]
	v_mfma_f32_16x16x32_bf16 v[4:7], v[202:205], v[194:197], v[4:7]
	v_mfma_f32_16x16x32_bf16 v[0:3], v[210:213], v[194:197], v[0:3]
	s_add_i32 s53, s53, 2
	s_add_u32 s20, s20, 0x100
	s_addc_u32 s21, s21, 0
	s_add_u32 s51, s51, 0x100
	s_addc_u32 s52, s52, 0
	s_cmp_gt_u32 s53, 29
	s_barrier
	s_cbranch_scc0 .LBB0_1676
	v_mul_f32_e32 v151, 0xbfb8aa3b, v124
	v_exp_f32_e32 v151, v151
	v_mul_f32_e32 v152, 0xbfb8aa3b, v120
	v_exp_f32_e32 v153, v152
	v_lshl_or_b32 v152, s50, 7, v146
	v_add_f32_e32 v151, 1.0, v151
	v_rcp_f32_e32 v151, v151
	v_add_f32_e32 v153, 1.0, v153
	v_rcp_f32_e32 v154, v153
	v_lshl_add_u32 v150, s18, 8, v144
	v_mul_f32_e32 v124, v124, v151
	v_mul_f32_e32 v116, v124, v116
	v_mul_f32_e32 v124, 0xbfb8aa3b, v125
	v_exp_f32_e32 v124, v124
	v_mul_f32_e32 v151, 0xbfb8aa3b, v121
	v_exp_f32_e32 v151, v151
	v_mul_f32_e32 v120, v120, v154
	v_mul_f32_e32 v112, v120, v112
	v_add_f32_e32 v120, 1.0, v124
	v_rcp_f32_e32 v120, v120
	v_add_f32_e32 v124, 1.0, v151
	v_mul_f32_e32 v151, 0xbfb8aa3b, v126
	v_rcp_f32_e32 v124, v124
	v_exp_f32_e32 v151, v151
	v_mul_f32_e32 v120, v125, v120
	v_mul_f32_e32 v117, v120, v117
	v_mul_f32_e32 v120, v121, v124
	v_add_f32_e32 v121, 1.0, v151
	v_rcp_f32_e32 v121, v121
	v_mul_f32_e32 v124, 0xbfb8aa3b, v122
	v_exp_f32_e32 v124, v124
	v_mul_f32_e32 v113, v120, v113
	v_mul_f32_e32 v120, v126, v121
	v_mul_f32_e32 v121, 0xbfb8aa3b, v127
	v_mul_f32_e32 v118, v120, v118
	v_add_f32_e32 v120, 1.0, v124
	v_exp_f32_e32 v121, v121
	v_mul_f32_e32 v124, 0xbfb8aa3b, v123
	v_rcp_f32_e32 v120, v120
	v_exp_f32_e32 v124, v124
	v_add_f32_e32 v121, 1.0, v121
	v_rcp_f32_e32 v121, v121
	v_mul_f32_e32 v120, v122, v120
	v_add_f32_e32 v122, 1.0, v124
	v_rcp_f32_e32 v122, v122
	v_mul_f32_e32 v114, v120, v114
	v_mul_f32_e32 v120, v127, v121
	v_mul_f32_e32 v119, v120, v119
	v_mul_f32_e32 v120, v123, v122
	v_mul_f32_e32 v122, 0xbfb8aa3b, v108
	v_exp_f32_e32 v122, v122
	v_mul_f32_e32 v123, 0xbfb8aa3b, v104
	v_exp_f32_e32 v123, v123
	v_ashrrev_i32_e32 v153, 31, v152
	v_add_f32_e32 v122, 1.0, v122
	v_rcp_f32_e32 v122, v122
	v_mul_f32_e32 v115, v120, v115
	s_nop 1
	v_cvt_pk_bf16_f32 v116, v116, v117
	s_nop 1
	v_cvt_pk_bf16_f32 v117, v118, v119
	s_nop 1
	v_cvt_pk_bf16_f32 v118, v112, v113
	v_mov_b64_e32 v[112:113], s[48:49]
	s_nop 1
	v_cvt_pk_bf16_f32 v119, v114, v115
	v_mad_i64_i32 v[120:121], s[0:1], v150, s47, v[112:113]
	v_lshlrev_b64 v[114:115], 1, v[152:153]
	v_add_f32_e32 v123, 1.0, v123
	v_mul_f32_e32 v108, v108, v122
	v_lshl_add_u64 v[120:121], v[120:121], 0, v[114:115]
	v_rcp_f32_e32 v123, v123
	v_mul_f32_e32 v100, v108, v100
	v_mul_f32_e32 v108, 0xbfb8aa3b, v109
	global_store_dwordx4 v[120:121], v[116:119], off
	v_exp_f32_e32 v108, v108
	v_mul_f32_e32 v104, v104, v123
	v_mul_f32_e32 v116, 0xbfb8aa3b, v105
	v_exp_f32_e32 v116, v116
	v_mul_f32_e32 v104, v104, v96
	v_add_f32_e32 v96, 1.0, v108
	v_rcp_f32_e32 v96, v96
	v_add_f32_e32 v108, 1.0, v116
	v_mul_f32_e32 v116, 0xbfb8aa3b, v110
	v_rcp_f32_e32 v108, v108
	v_exp_f32_e32 v116, v116
	v_mul_f32_e32 v96, v109, v96
	v_mul_f32_e32 v96, v96, v101
	v_mul_f32_e32 v101, v105, v108
	v_add_f32_e32 v105, 1.0, v116
	v_rcp_f32_e32 v105, v105
	v_mul_f32_e32 v108, 0xbfb8aa3b, v106
	v_exp_f32_e32 v108, v108
	v_mul_f32_e32 v101, v101, v97
	v_mul_f32_e32 v97, v110, v105
	v_mul_f32_e32 v105, 0xbfb8aa3b, v111
	v_mul_f32_e32 v97, v97, v102
	v_add_f32_e32 v102, 1.0, v108
	v_exp_f32_e32 v105, v105
	v_mul_f32_e32 v108, 0xbfb8aa3b, v107
	v_rcp_f32_e32 v102, v102
	v_exp_f32_e32 v108, v108
	v_add_f32_e32 v105, 1.0, v105
	v_rcp_f32_e32 v105, v105
	v_mul_f32_e32 v102, v106, v102
	v_add_f32_e32 v106, 1.0, v108
	v_rcp_f32_e32 v106, v106
	v_mul_f32_e32 v102, v102, v98
	v_mul_f32_e32 v98, v111, v105
	v_mul_f32_e32 v98, v98, v103
	v_mul_f32_e32 v103, v107, v106
	v_mul_f32_e32 v99, v103, v99
	s_nop 1
	v_cvt_pk_bf16_f32 v96, v100, v96
	s_nop 1
	v_cvt_pk_bf16_f32 v97, v97, v98
	s_nop 1
	v_cvt_pk_bf16_f32 v98, v104, v101
	s_nop 1
	v_cvt_pk_bf16_f32 v99, v102, v99
	v_mul_f32_e32 v102, 0xbfb8aa3b, v92
	v_exp_f32_e32 v102, v102
	v_mul_f32_e32 v103, 0xbfb8aa3b, v88
	v_exp_f32_e32 v103, v103
	v_or_b32_e32 v100, 16, v150
	v_add_f32_e32 v102, 1.0, v102
	v_rcp_f32_e32 v102, v102
	v_mad_i64_i32 v[100:101], s[0:1], v100, s47, v[112:113]
	v_add_f32_e32 v103, 1.0, v103
	v_mul_f32_e32 v92, v92, v102
	v_lshl_add_u64 v[100:101], v[100:101], 0, v[114:115]
	v_rcp_f32_e32 v103, v103
	v_mul_f32_e32 v84, v92, v84
	v_mul_f32_e32 v92, 0xbfb8aa3b, v93
	global_store_dwordx4 v[100:101], v[96:99], off
	v_exp_f32_e32 v92, v92
	v_mul_f32_e32 v88, v88, v103
	v_mul_f32_e32 v96, 0xbfb8aa3b, v89
	v_exp_f32_e32 v96, v96
	v_mul_f32_e32 v88, v88, v80
	v_add_f32_e32 v80, 1.0, v92
	v_rcp_f32_e32 v80, v80
	v_add_f32_e32 v92, 1.0, v96
	v_mul_f32_e32 v96, 0xbfb8aa3b, v94
	v_rcp_f32_e32 v92, v92
	v_exp_f32_e32 v96, v96
	v_mul_f32_e32 v80, v93, v80
	v_mul_f32_e32 v80, v80, v85
	v_mul_f32_e32 v85, v89, v92
	v_add_f32_e32 v89, 1.0, v96
	v_rcp_f32_e32 v89, v89
	v_mul_f32_e32 v92, 0xbfb8aa3b, v90
	v_exp_f32_e32 v92, v92
	v_mul_f32_e32 v85, v85, v81
	v_mul_f32_e32 v81, v94, v89
	v_mul_f32_e32 v89, 0xbfb8aa3b, v95
	v_mul_f32_e32 v81, v81, v86
	v_add_f32_e32 v86, 1.0, v92
	v_exp_f32_e32 v89, v89
	v_mul_f32_e32 v92, 0xbfb8aa3b, v91
	v_rcp_f32_e32 v86, v86
	v_exp_f32_e32 v92, v92
	v_add_f32_e32 v89, 1.0, v89
	v_rcp_f32_e32 v89, v89
	v_mul_f32_e32 v86, v90, v86
	v_add_f32_e32 v90, 1.0, v92
	v_rcp_f32_e32 v90, v90
	v_mul_f32_e32 v86, v86, v82
	v_mul_f32_e32 v82, v95, v89
	v_mul_f32_e32 v82, v82, v87
	v_mul_f32_e32 v87, v91, v90
	v_mul_f32_e32 v83, v87, v83
	s_nop 1
	v_cvt_pk_bf16_f32 v80, v84, v80
	s_nop 1
	v_cvt_pk_bf16_f32 v81, v81, v82
	s_nop 1
	v_cvt_pk_bf16_f32 v82, v88, v85
	s_nop 1
	v_cvt_pk_bf16_f32 v83, v86, v83
	v_mul_f32_e32 v86, 0xbfb8aa3b, v76
	v_exp_f32_e32 v86, v86
	v_mul_f32_e32 v87, 0xbfb8aa3b, v72
	v_exp_f32_e32 v87, v87
	v_or_b32_e32 v84, 32, v150
	v_add_f32_e32 v86, 1.0, v86
	v_rcp_f32_e32 v86, v86
	v_mad_i64_i32 v[84:85], s[0:1], v84, s47, v[112:113]
	v_add_f32_e32 v87, 1.0, v87
	v_mul_f32_e32 v76, v76, v86
	v_lshl_add_u64 v[84:85], v[84:85], 0, v[114:115]
	v_rcp_f32_e32 v87, v87
	v_mul_f32_e32 v68, v76, v68
	v_mul_f32_e32 v76, 0xbfb8aa3b, v77
	global_store_dwordx4 v[84:85], v[80:83], off
	v_exp_f32_e32 v76, v76
	v_mul_f32_e32 v72, v72, v87
	v_mul_f32_e32 v80, 0xbfb8aa3b, v73
	v_exp_f32_e32 v80, v80
	v_mul_f32_e32 v72, v72, v64
	v_add_f32_e32 v64, 1.0, v76
	v_rcp_f32_e32 v64, v64
	v_add_f32_e32 v76, 1.0, v80
	v_mul_f32_e32 v80, 0xbfb8aa3b, v78
	v_rcp_f32_e32 v76, v76
	v_exp_f32_e32 v80, v80
	v_mul_f32_e32 v64, v77, v64
	v_mul_f32_e32 v64, v64, v69
	v_mul_f32_e32 v69, v73, v76
	v_add_f32_e32 v73, 1.0, v80
	v_rcp_f32_e32 v73, v73
	v_mul_f32_e32 v76, 0xbfb8aa3b, v74
	v_exp_f32_e32 v76, v76
	v_mul_f32_e32 v69, v69, v65
	v_mul_f32_e32 v65, v78, v73
	v_mul_f32_e32 v73, 0xbfb8aa3b, v79
	v_mul_f32_e32 v65, v65, v70
	v_add_f32_e32 v70, 1.0, v76
	v_exp_f32_e32 v73, v73
	v_mul_f32_e32 v76, 0xbfb8aa3b, v75
	v_rcp_f32_e32 v70, v70
	v_exp_f32_e32 v76, v76
	v_add_f32_e32 v73, 1.0, v73
	v_rcp_f32_e32 v73, v73
	v_mul_f32_e32 v70, v74, v70
	v_add_f32_e32 v74, 1.0, v76
	v_rcp_f32_e32 v74, v74
	v_mul_f32_e32 v70, v70, v66
	v_mul_f32_e32 v66, v79, v73
	v_mul_f32_e32 v66, v66, v71
	v_mul_f32_e32 v71, v75, v74
	v_mul_f32_e32 v67, v71, v67
	s_nop 1
	v_cvt_pk_bf16_f32 v64, v68, v64
	s_nop 1
	v_cvt_pk_bf16_f32 v65, v65, v66
	s_nop 1
	v_cvt_pk_bf16_f32 v66, v72, v69
	s_nop 1
	v_cvt_pk_bf16_f32 v67, v70, v67
	v_mul_f32_e32 v70, 0xbfb8aa3b, v60
	v_exp_f32_e32 v70, v70
	v_or_b32_e32 v68, 48, v150
	v_mad_i64_i32 v[68:69], s[0:1], v68, s47, v[112:113]
	v_lshl_add_u64 v[68:69], v[68:69], 0, v[114:115]
	v_mul_f32_e32 v71, 0xbfb8aa3b, v56
	global_store_dwordx4 v[68:69], v[64:67], off
	v_exp_f32_e32 v71, v71
	s_and_b64 vcc, exec, s[6:7]
	v_add_f32_e32 v64, 1.0, v70
	v_rcp_f32_e32 v64, v64
	v_add_f32_e32 v65, 1.0, v71
	v_rcp_f32_e32 v65, v65
	v_add_u32_e32 v66, 0x80, v150
	v_mul_f32_e32 v60, v60, v64
	v_mul_f32_e32 v52, v60, v52
	v_mul_f32_e32 v60, 0xbfb8aa3b, v61
	v_exp_f32_e32 v60, v60
	v_mul_f32_e32 v64, 0xbfb8aa3b, v57
	v_exp_f32_e32 v64, v64
	v_mul_f32_e32 v56, v56, v65
	v_mul_f32_e32 v56, v56, v48
	v_add_f32_e32 v48, 1.0, v60
	v_rcp_f32_e32 v48, v48
	v_add_f32_e32 v60, 1.0, v64
	v_mul_f32_e32 v64, 0xbfb8aa3b, v62
	v_rcp_f32_e32 v60, v60
	v_exp_f32_e32 v64, v64
	v_mul_f32_e32 v48, v61, v48
	v_mul_f32_e32 v48, v48, v53
	v_mul_f32_e32 v53, v57, v60
	v_add_f32_e32 v57, 1.0, v64
	v_rcp_f32_e32 v57, v57
	v_mul_f32_e32 v60, 0xbfb8aa3b, v58
	v_exp_f32_e32 v60, v60
	v_mul_f32_e32 v53, v53, v49
	v_mul_f32_e32 v49, v62, v57
	v_mul_f32_e32 v57, 0xbfb8aa3b, v63
	v_mul_f32_e32 v49, v49, v54
	v_add_f32_e32 v54, 1.0, v60
	v_exp_f32_e32 v57, v57
	v_mul_f32_e32 v60, 0xbfb8aa3b, v59
	v_rcp_f32_e32 v54, v54
	v_exp_f32_e32 v60, v60
	v_add_f32_e32 v57, 1.0, v57
	v_rcp_f32_e32 v57, v57
	v_mul_f32_e32 v54, v58, v54
	v_add_f32_e32 v58, 1.0, v60
	v_rcp_f32_e32 v58, v58
	v_mul_f32_e32 v54, v54, v50
	v_mul_f32_e32 v50, v63, v57
	v_mul_f32_e32 v50, v50, v55
	v_mul_f32_e32 v55, v59, v58
	v_mul_f32_e32 v51, v55, v51
	s_nop 1
	v_cvt_pk_bf16_f32 v48, v52, v48
	s_nop 1
	v_cvt_pk_bf16_f32 v49, v49, v50
	s_nop 1
	v_cvt_pk_bf16_f32 v50, v56, v53
	s_nop 1
	v_cvt_pk_bf16_f32 v51, v54, v51
	v_mul_f32_e32 v54, 0xbfb8aa3b, v44
	v_exp_f32_e32 v54, v54
	v_mul_f32_e32 v55, 0xbfb8aa3b, v40
	v_exp_f32_e32 v55, v55
	v_mad_i64_i32 v[52:53], s[0:1], v66, s47, v[112:113]
	v_add_f32_e32 v54, 1.0, v54
	v_rcp_f32_e32 v54, v54
	v_add_f32_e32 v55, 1.0, v55
	v_lshl_add_u64 v[52:53], v[52:53], 0, v[114:115]
	v_rcp_f32_e32 v55, v55
	v_mul_f32_e32 v44, v44, v54
	v_mul_f32_e32 v36, v44, v36
	v_mul_f32_e32 v44, 0xbfb8aa3b, v45
	global_store_dwordx4 v[52:53], v[48:51], off
	v_exp_f32_e32 v44, v44
	v_mul_f32_e32 v40, v40, v55
	v_mul_f32_e32 v48, 0xbfb8aa3b, v41
	v_exp_f32_e32 v48, v48
	v_mul_f32_e32 v40, v40, v32
	v_add_f32_e32 v32, 1.0, v44
	v_rcp_f32_e32 v32, v32
	v_add_f32_e32 v44, 1.0, v48
	v_mul_f32_e32 v48, 0xbfb8aa3b, v46
	v_rcp_f32_e32 v44, v44
	v_exp_f32_e32 v48, v48
	v_mul_f32_e32 v32, v45, v32
	v_mul_f32_e32 v32, v32, v37
	v_mul_f32_e32 v37, v41, v44
	v_add_f32_e32 v41, 1.0, v48
	v_rcp_f32_e32 v41, v41
	v_mul_f32_e32 v44, 0xbfb8aa3b, v42
	v_exp_f32_e32 v44, v44
	v_mul_f32_e32 v37, v37, v33
	v_mul_f32_e32 v33, v46, v41
	v_mul_f32_e32 v41, 0xbfb8aa3b, v47
	v_mul_f32_e32 v33, v33, v38
	v_add_f32_e32 v38, 1.0, v44
	v_exp_f32_e32 v41, v41
	v_mul_f32_e32 v44, 0xbfb8aa3b, v43
	v_rcp_f32_e32 v38, v38
	v_exp_f32_e32 v44, v44
	v_add_f32_e32 v41, 1.0, v41
	v_rcp_f32_e32 v41, v41
	v_mul_f32_e32 v38, v42, v38
	v_add_f32_e32 v42, 1.0, v44
	v_rcp_f32_e32 v42, v42
	v_mul_f32_e32 v38, v38, v34
	v_mul_f32_e32 v34, v47, v41
	v_mul_f32_e32 v34, v34, v39
	v_mul_f32_e32 v39, v43, v42
	v_mul_f32_e32 v35, v39, v35
	s_nop 1
	v_cvt_pk_bf16_f32 v32, v36, v32
	s_nop 1
	v_cvt_pk_bf16_f32 v33, v33, v34
	s_nop 1
	v_cvt_pk_bf16_f32 v34, v40, v37
	s_nop 1
	v_cvt_pk_bf16_f32 v35, v38, v35
	v_mul_f32_e32 v38, 0xbfb8aa3b, v28
	v_exp_f32_e32 v38, v38
	v_mul_f32_e32 v39, 0xbfb8aa3b, v24
	v_exp_f32_e32 v39, v39
	v_add_u32_e32 v36, 0x90, v150
	v_add_f32_e32 v38, 1.0, v38
	v_rcp_f32_e32 v38, v38
	v_mad_i64_i32 v[36:37], s[0:1], v36, s47, v[112:113]
	v_add_f32_e32 v39, 1.0, v39
	v_mul_f32_e32 v28, v28, v38
	v_lshl_add_u64 v[36:37], v[36:37], 0, v[114:115]
	v_rcp_f32_e32 v39, v39
	v_mul_f32_e32 v20, v28, v20
	v_mul_f32_e32 v28, 0xbfb8aa3b, v29
	global_store_dwordx4 v[36:37], v[32:35], off
	v_exp_f32_e32 v28, v28
	v_mul_f32_e32 v24, v24, v39
	v_mul_f32_e32 v32, 0xbfb8aa3b, v25
	v_exp_f32_e32 v32, v32
	v_mul_f32_e32 v24, v24, v16
	v_add_f32_e32 v16, 1.0, v28
	v_rcp_f32_e32 v16, v16
	v_add_f32_e32 v28, 1.0, v32
	v_mul_f32_e32 v32, 0xbfb8aa3b, v30
	v_rcp_f32_e32 v28, v28
	v_exp_f32_e32 v32, v32
	v_mul_f32_e32 v16, v29, v16
	v_mul_f32_e32 v16, v16, v21
	v_mul_f32_e32 v21, v25, v28
	v_add_f32_e32 v25, 1.0, v32
	v_rcp_f32_e32 v25, v25
	v_mul_f32_e32 v28, 0xbfb8aa3b, v26
	v_exp_f32_e32 v28, v28
	v_mul_f32_e32 v21, v21, v17
	v_mul_f32_e32 v17, v30, v25
	v_mul_f32_e32 v25, 0xbfb8aa3b, v31
	v_mul_f32_e32 v17, v17, v22
	v_add_f32_e32 v22, 1.0, v28
	v_exp_f32_e32 v25, v25
	v_mul_f32_e32 v28, 0xbfb8aa3b, v27
	v_rcp_f32_e32 v22, v22
	v_exp_f32_e32 v28, v28
	v_add_f32_e32 v25, 1.0, v25
	v_rcp_f32_e32 v25, v25
	v_mul_f32_e32 v22, v26, v22
	v_add_f32_e32 v26, 1.0, v28
	v_rcp_f32_e32 v26, v26
	v_mul_f32_e32 v22, v22, v18
	v_mul_f32_e32 v18, v31, v25
	v_mul_f32_e32 v18, v18, v23
	v_mul_f32_e32 v23, v27, v26
	v_mul_f32_e32 v19, v23, v19
	s_nop 1
	v_cvt_pk_bf16_f32 v16, v20, v16
	s_nop 1
	v_cvt_pk_bf16_f32 v17, v17, v18
	s_nop 1
	v_cvt_pk_bf16_f32 v18, v24, v21
	s_nop 1
	v_cvt_pk_bf16_f32 v19, v22, v19
	v_mul_f32_e32 v22, 0xbfb8aa3b, v12
	v_exp_f32_e32 v22, v22
	v_mul_f32_e32 v23, 0xbfb8aa3b, v8
	v_exp_f32_e32 v23, v23
	v_add_u32_e32 v20, 0xa0, v150
	v_add_f32_e32 v22, 1.0, v22
	v_rcp_f32_e32 v22, v22
	v_mad_i64_i32 v[20:21], s[0:1], v20, s47, v[112:113]
	v_add_f32_e32 v23, 1.0, v23
	v_mul_f32_e32 v12, v12, v22
	v_lshl_add_u64 v[20:21], v[20:21], 0, v[114:115]
	v_rcp_f32_e32 v23, v23
	v_mul_f32_e32 v4, v12, v4
	v_mul_f32_e32 v12, 0xbfb8aa3b, v13
	global_store_dwordx4 v[20:21], v[16:19], off
	v_exp_f32_e32 v12, v12
	v_mul_f32_e32 v8, v8, v23
	v_mul_f32_e32 v16, 0xbfb8aa3b, v9
	v_exp_f32_e32 v16, v16
	v_mul_f32_e32 v8, v8, v0
	v_add_f32_e32 v0, 1.0, v12
	v_rcp_f32_e32 v0, v0
	v_add_f32_e32 v12, 1.0, v16
	v_mul_f32_e32 v16, 0xbfb8aa3b, v14
	v_rcp_f32_e32 v12, v12
	v_exp_f32_e32 v16, v16
	v_mul_f32_e32 v0, v13, v0
	v_mul_f32_e32 v0, v0, v5
	v_mul_f32_e32 v5, v9, v12
	v_add_f32_e32 v9, 1.0, v16
	v_rcp_f32_e32 v9, v9
	v_mul_f32_e32 v12, 0xbfb8aa3b, v10
	v_exp_f32_e32 v12, v12
	v_mul_f32_e32 v5, v5, v1
	v_mul_f32_e32 v1, v14, v9
	v_mul_f32_e32 v9, 0xbfb8aa3b, v15
	v_exp_f32_e32 v9, v9
	v_mul_f32_e32 v1, v1, v6
	v_add_f32_e32 v6, 1.0, v12
	v_mul_f32_e32 v12, 0xbfb8aa3b, v11
	v_rcp_f32_e32 v6, v6
	v_exp_f32_e32 v12, v12
	v_add_f32_e32 v9, 1.0, v9
	v_rcp_f32_e32 v9, v9
	v_mul_f32_e32 v6, v10, v6
	v_add_f32_e32 v10, 1.0, v12
	v_rcp_f32_e32 v10, v10
	v_mul_f32_e32 v6, v6, v2
	v_mul_f32_e32 v2, v15, v9
	v_mul_f32_e32 v2, v2, v7
	s_nop 1
	v_cvt_pk_bf16_f32 v0, v4, v0
	v_add_u32_e32 v4, 0xb0, v150
	v_mul_f32_e32 v7, v11, v10
	s_nop 1
	v_cvt_pk_bf16_f32 v1, v1, v2
	s_nop 1
	v_cvt_pk_bf16_f32 v2, v8, v5
	v_mad_i64_i32 v[4:5], s[0:1], v4, s47, v[112:113]
	v_mul_f32_e32 v3, v7, v3
	v_lshl_add_u64 v[4:5], v[4:5], 0, v[114:115]
	s_mov_b32 s50, s10
	s_mov_b32 s18, s12
	s_mov_b64 s[44:45], s[16:17]
	s_mov_b64 s[20:21], s[14:15]
	s_nop 1
	v_cvt_pk_bf16_f32 v3, v6, v3
	global_store_dwordx4 v[4:5], v[0:3], off
	s_cbranch_vccz .LBB0_1673
	s_waitcnt vmcnt(0)
	s_cmpk_gt_u32 s23, 0xff
	s_cbranch_scc1 .LBB0_1680
	s_barrier

.LBB0_1748:
	s_add_u32 s0, s44, 0x100
	v_mov_b32_e32 v0, 0
	s_addc_u32 s1, s45, 0
	s_mov_b32 s61, -2
	v_mov_b32_e32 v1, v0
	v_mov_b32_e32 v2, v0
	v_mov_b32_e32 v3, v0
	v_mov_b32_e32 v16, v0
	v_mov_b32_e32 v17, v0
	v_mov_b32_e32 v18, v0
	v_mov_b32_e32 v19, v0
	v_mov_b32_e32 v4, v0
	v_mov_b32_e32 v5, v0
	v_mov_b32_e32 v6, v0
	v_mov_b32_e32 v7, v0
	v_mov_b32_e32 v20, v0
	v_mov_b32_e32 v21, v0
	v_mov_b32_e32 v22, v0
	v_mov_b32_e32 v23, v0
	v_mov_b32_e32 v8, v0
	v_mov_b32_e32 v9, v0
	v_mov_b32_e32 v10, v0
	v_mov_b32_e32 v11, v0
	v_mov_b32_e32 v24, v0
	v_mov_b32_e32 v25, v0
	v_mov_b32_e32 v26, v0
	v_mov_b32_e32 v27, v0
	v_mov_b32_e32 v12, v0
	v_mov_b32_e32 v13, v0
	v_mov_b32_e32 v14, v0
	v_mov_b32_e32 v15, v0
	v_mov_b32_e32 v32, v0
	v_mov_b32_e32 v33, v0
	v_mov_b32_e32 v34, v0
	v_mov_b32_e32 v35, v0
	v_mov_b32_e32 v52, v0
	v_mov_b32_e32 v53, v0
	v_mov_b32_e32 v54, v0
	v_mov_b32_e32 v55, v0
	v_mov_b32_e32 v80, v0
	v_mov_b32_e32 v81, v0
	v_mov_b32_e32 v82, v0
	v_mov_b32_e32 v83, v0
	v_mov_b32_e32 v60, v0
	v_mov_b32_e32 v61, v0
	v_mov_b32_e32 v62, v0
	v_mov_b32_e32 v63, v0
	v_mov_b32_e32 v88, v0
	v_mov_b32_e32 v89, v0
	v_mov_b32_e32 v90, v0
	v_mov_b32_e32 v91, v0
	v_mov_b32_e32 v68, v0
	v_mov_b32_e32 v69, v0
	v_mov_b32_e32 v70, v0
	v_mov_b32_e32 v71, v0
	v_mov_b32_e32 v104, v0
	v_mov_b32_e32 v105, v0
	v_mov_b32_e32 v106, v0
	v_mov_b32_e32 v107, v0
	v_mov_b32_e32 v76, v0
	v_mov_b32_e32 v77, v0
	v_mov_b32_e32 v78, v0
	v_mov_b32_e32 v79, v0
	v_mov_b32_e32 v108, v0
	v_mov_b32_e32 v109, v0
	v_mov_b32_e32 v110, v0
	v_mov_b32_e32 v111, v0
	v_mov_b32_e32 v28, v0
	v_mov_b32_e32 v29, v0
	v_mov_b32_e32 v30, v0
	v_mov_b32_e32 v31, v0
	v_mov_b32_e32 v48, v0
	v_mov_b32_e32 v49, v0
	v_mov_b32_e32 v50, v0
	v_mov_b32_e32 v51, v0
	v_mov_b32_e32 v36, v0
	v_mov_b32_e32 v37, v0
	v_mov_b32_e32 v38, v0
	v_mov_b32_e32 v39, v0
	v_mov_b32_e32 v56, v0
	v_mov_b32_e32 v57, v0
	v_mov_b32_e32 v58, v0
	v_mov_b32_e32 v59, v0
	v_mov_b32_e32 v40, v0
	v_mov_b32_e32 v41, v0
	v_mov_b32_e32 v42, v0
	v_mov_b32_e32 v43, v0
	v_mov_b32_e32 v64, v0
	v_mov_b32_e32 v65, v0
	v_mov_b32_e32 v66, v0
	v_mov_b32_e32 v67, v0
	v_mov_b32_e32 v44, v0
	v_mov_b32_e32 v45, v0
	v_mov_b32_e32 v46, v0
	v_mov_b32_e32 v47, v0
	v_mov_b32_e32 v72, v0
	v_mov_b32_e32 v73, v0
	v_mov_b32_e32 v74, v0
	v_mov_b32_e32 v75, v0
	v_mov_b32_e32 v84, v0
	v_mov_b32_e32 v85, v0
	v_mov_b32_e32 v86, v0
	v_mov_b32_e32 v87, v0
	v_mov_b32_e32 v112, v0
	v_mov_b32_e32 v113, v0
	v_mov_b32_e32 v114, v0
	v_mov_b32_e32 v115, v0
	v_mov_b32_e32 v92, v0
	v_mov_b32_e32 v93, v0
	v_mov_b32_e32 v94, v0
	v_mov_b32_e32 v95, v0
	v_mov_b32_e32 v116, v0
	v_mov_b32_e32 v117, v0
	v_mov_b32_e32 v118, v0
	v_mov_b32_e32 v119, v0
	v_mov_b32_e32 v96, v0
	v_mov_b32_e32 v97, v0
	v_mov_b32_e32 v98, v0
	v_mov_b32_e32 v99, v0
	v_mov_b32_e32 v120, v0
	v_mov_b32_e32 v121, v0
	v_mov_b32_e32 v122, v0
	v_mov_b32_e32 v123, v0
	v_mov_b32_e32 v100, v0
	v_mov_b32_e32 v101, v0
	v_mov_b32_e32 v102, v0
	v_mov_b32_e32 v103, v0
	v_mov_b32_e32 v124, v0
	v_mov_b32_e32 v125, v0
	v_mov_b32_e32 v126, v0
	v_mov_b32_e32 v127, v0
	ds_read_b128 v[128:131], v221
	ds_read_b128 v[132:135], v221 offset:1024
	ds_read_b128 v[136:139], v221 offset:2048
	ds_read_b128 v[140:143], v221 offset:3072
.LBB0_1749:
	s_add_u32 s44, s42, 0x100
	s_addc_u32 s45, s43, 0
	s_cmpk_eq_i32 s61, 0x54
	s_cselect_b32 s5, s9, s45
	s_cselect_b32 s4, s8, s44
	s_cselect_b32 s47, s11, s1
	s_cselect_b32 s46, s10, s0
	v_lshl_add_u64 v[188:189], s[42:43], 0, v[168:169]
	s_add_i32 m0, s25, 0xc000
	ds_read_b128 v[144:147], v222
	ds_read_b128 v[148:151], v222 offset:1024
	ds_read_b128 v[152:155], v222 offset:2048
	ds_read_b128 v[156:159], v222 offset:3072
	ds_read_b128 v[160:163], v222 offset:4096
	ds_read_b128 v[176:179], v222 offset:5120
	ds_read_b128 v[180:183], v222 offset:6144
	ds_read_b128 v[184:187], v222 offset:7168
	global_load_lds_dwordx4 v[188:189], off
	v_lshl_add_u64 v[188:189], s[42:43], 0, v[170:171]
	s_add_i32 m0, s25, 0xe000
	s_nop 0
	global_load_lds_dwordx4 v[188:189], off
	s_waitcnt lgkmcnt(8)
	s_barrier
	s_waitcnt lgkmcnt(0)
	s_waitcnt lgkmcnt(0)
	v_mfma_f32_16x16x32_bf16 v[124:127], v[128:131], v[144:147], v[124:127]
	v_mfma_f32_16x16x32_bf16 v[100:103], v[136:139], v[144:147], v[100:103]
	v_mfma_f32_16x16x32_bf16 v[120:123], v[128:131], v[152:155], v[120:123]
	v_mfma_f32_16x16x32_bf16 v[96:99], v[136:139], v[152:155], v[96:99]
	v_mfma_f32_16x16x32_bf16 v[116:119], v[128:131], v[160:163], v[116:119]
	v_mfma_f32_16x16x32_bf16 v[92:95], v[136:139], v[160:163], v[92:95]
	v_mfma_f32_16x16x32_bf16 v[112:115], v[128:131], v[180:183], v[112:115]
	v_mfma_f32_16x16x32_bf16 v[84:87], v[136:139], v[180:183], v[84:87]
	v_mfma_f32_16x16x32_bf16 v[124:127], v[132:135], v[148:151], v[124:127]
	v_mfma_f32_16x16x32_bf16 v[100:103], v[140:143], v[148:151], v[100:103]
	v_mfma_f32_16x16x32_bf16 v[120:123], v[132:135], v[156:159], v[120:123]
	v_mfma_f32_16x16x32_bf16 v[96:99], v[140:143], v[156:159], v[96:99]
	v_mfma_f32_16x16x32_bf16 v[116:119], v[132:135], v[176:179], v[116:119]
	v_mfma_f32_16x16x32_bf16 v[92:95], v[140:143], v[176:179], v[92:95]
	v_mfma_f32_16x16x32_bf16 v[112:115], v[132:135], v[184:187], v[112:115]
	v_mfma_f32_16x16x32_bf16 v[84:87], v[140:143], v[184:187], v[84:87]
	s_barrier
	s_add_i32 s42, s51, s24
	v_lshl_add_u64 v[204:205], s[46:47], 0, v[166:167]
	s_mov_b32 m0, s42
	ds_read_b128 v[188:191], v223
	ds_read_b128 v[192:195], v223 offset:1024
	ds_read_b128 v[196:199], v223 offset:2048
	ds_read_b128 v[200:203], v223 offset:3072
	global_load_lds_dwordx4 v[204:205], off
	v_lshl_add_u64 v[206:207], s[46:47], 0, v[164:165]
	s_add_i32 m0, s42, 0x2000
	s_nop 0
	global_load_lds_dwordx4 v[206:207], off
	s_barrier
	s_waitcnt lgkmcnt(0)
	s_waitcnt lgkmcnt(0)
	v_mfma_f32_16x16x32_bf16 v[72:75], v[188:191], v[144:147], v[72:75]
	v_mfma_f32_16x16x32_bf16 v[44:47], v[196:199], v[144:147], v[44:47]
	v_mfma_f32_16x16x32_bf16 v[64:67], v[188:191], v[152:155], v[64:67]
	v_mfma_f32_16x16x32_bf16 v[40:43], v[196:199], v[152:155], v[40:43]
	v_mfma_f32_16x16x32_bf16 v[56:59], v[188:191], v[160:163], v[56:59]
	v_mfma_f32_16x16x32_bf16 v[36:39], v[196:199], v[160:163], v[36:39]
	v_mfma_f32_16x16x32_bf16 v[48:51], v[188:191], v[180:183], v[48:51]
	v_mfma_f32_16x16x32_bf16 v[28:31], v[196:199], v[180:183], v[28:31]
	v_mfma_f32_16x16x32_bf16 v[72:75], v[192:195], v[148:151], v[72:75]
	v_mfma_f32_16x16x32_bf16 v[44:47], v[200:203], v[148:151], v[44:47]
	v_mfma_f32_16x16x32_bf16 v[64:67], v[192:195], v[156:159], v[64:67]
	v_mfma_f32_16x16x32_bf16 v[40:43], v[200:203], v[156:159], v[40:43]
	v_mfma_f32_16x16x32_bf16 v[56:59], v[192:195], v[176:179], v[56:59]
	v_mfma_f32_16x16x32_bf16 v[36:39], v[200:203], v[176:179], v[36:39]
	v_mfma_f32_16x16x32_bf16 v[48:51], v[192:195], v[184:187], v[48:51]
	v_mfma_f32_16x16x32_bf16 v[28:31], v[200:203], v[184:187], v[28:31]
	s_mov_b32 m0, s25
	v_lshl_add_u64 v[208:209], s[4:5], 0, v[166:167]
	s_barrier
	s_waitcnt vmcnt(8)
	ds_read_b128 v[144:147], v222 offset:16384
	ds_read_b128 v[148:151], v222 offset:17408
	ds_read_b128 v[152:155], v222 offset:18432
	ds_read_b128 v[156:159], v222 offset:19456
	ds_read_b128 v[160:163], v222 offset:20480
	ds_read_b128 v[176:179], v222 offset:21504
	ds_read_b128 v[180:183], v222 offset:22528
	ds_read_b128 v[184:187], v222 offset:23552
	global_load_lds_dwordx4 v[208:209], off
	v_lshl_add_u64 v[210:211], s[4:5], 0, v[164:165]
	s_mov_b32 m0, s28
	s_nop 0
	global_load_lds_dwordx4 v[210:211], off
	s_barrier
	s_waitcnt lgkmcnt(0)
	s_waitcnt lgkmcnt(0)
	v_mfma_f32_16x16x32_bf16 v[108:111], v[128:131], v[144:147], v[108:111]
	v_mfma_f32_16x16x32_bf16 v[76:79], v[136:139], v[144:147], v[76:79]
	v_mfma_f32_16x16x32_bf16 v[104:107], v[128:131], v[152:155], v[104:107]
	v_mfma_f32_16x16x32_bf16 v[68:71], v[136:139], v[152:155], v[68:71]
	v_mfma_f32_16x16x32_bf16 v[88:91], v[128:131], v[160:163], v[88:91]
	v_mfma_f32_16x16x32_bf16 v[60:63], v[136:139], v[160:163], v[60:63]
	v_mfma_f32_16x16x32_bf16 v[80:83], v[128:131], v[180:183], v[80:83]
	v_mfma_f32_16x16x32_bf16 v[52:55], v[136:139], v[180:183], v[52:55]
	v_mfma_f32_16x16x32_bf16 v[108:111], v[132:135], v[148:151], v[108:111]
	v_mfma_f32_16x16x32_bf16 v[76:79], v[140:143], v[148:151], v[76:79]
	v_mfma_f32_16x16x32_bf16 v[104:107], v[132:135], v[156:159], v[104:107]
	v_mfma_f32_16x16x32_bf16 v[68:71], v[140:143], v[156:159], v[68:71]
	v_mfma_f32_16x16x32_bf16 v[88:91], v[132:135], v[176:179], v[88:91]
	v_mfma_f32_16x16x32_bf16 v[60:63], v[140:143], v[176:179], v[60:63]
	v_mfma_f32_16x16x32_bf16 v[80:83], v[132:135], v[184:187], v[80:83]
	v_mfma_f32_16x16x32_bf16 v[52:55], v[140:143], v[184:187], v[52:55]
	s_barrier
	s_add_u32 s42, s46, 0x160000
	s_addc_u32 s43, s47, 0
	s_add_i32 s62, s52, s24
	v_lshl_add_u64 v[128:129], s[42:43], 0, v[166:167]
	s_mov_b32 m0, s62
	s_nop 0
	global_load_lds_dwordx4 v[128:129], off
	v_lshl_add_u64 v[128:129], s[42:43], 0, v[164:165]
	s_add_i32 m0, s62, 0x2000
	s_nop 0
	global_load_lds_dwordx4 v[128:129], off
	v_add_u32_e32 v140, 0x18000, v219
	ds_read_b128 v[128:131], v140
	ds_read_b128 v[132:135], v140 offset:1024
	ds_read_b128 v[136:139], v140 offset:2048
	ds_read_b128 v[140:143], v140 offset:3072
	s_waitcnt vmcnt(6)
	s_barrier
	v_mfma_f32_16x16x32_bf16 v[32:35], v[188:191], v[144:147], v[32:35]
	v_mfma_f32_16x16x32_bf16 v[12:15], v[196:199], v[144:147], v[12:15]
	v_mfma_f32_16x16x32_bf16 v[24:27], v[188:191], v[152:155], v[24:27]
	v_mfma_f32_16x16x32_bf16 v[8:11], v[196:199], v[152:155], v[8:11]
	v_mfma_f32_16x16x32_bf16 v[20:23], v[188:191], v[160:163], v[20:23]
	v_mfma_f32_16x16x32_bf16 v[4:7], v[196:199], v[160:163], v[4:7]
	v_mfma_f32_16x16x32_bf16 v[16:19], v[188:191], v[180:183], v[16:19]
	v_mfma_f32_16x16x32_bf16 v[0:3], v[196:199], v[180:183], v[0:3]
	v_mfma_f32_16x16x32_bf16 v[32:35], v[192:195], v[148:151], v[32:35]
	v_mfma_f32_16x16x32_bf16 v[12:15], v[200:203], v[148:151], v[12:15]
	v_mfma_f32_16x16x32_bf16 v[24:27], v[192:195], v[156:159], v[24:27]
	v_mfma_f32_16x16x32_bf16 v[8:11], v[200:203], v[156:159], v[8:11]
	v_mfma_f32_16x16x32_bf16 v[20:23], v[192:195], v[176:179], v[20:23]
	v_mfma_f32_16x16x32_bf16 v[4:7], v[200:203], v[176:179], v[4:7]
	v_mfma_f32_16x16x32_bf16 v[16:19], v[192:195], v[184:187], v[16:19]
	v_mfma_f32_16x16x32_bf16 v[0:3], v[200:203], v[184:187], v[0:3]
	s_add_i32 s42, 0, 0x18000
	s_barrier
	s_add_u32 s4, s4, 0x160000
	s_addc_u32 s5, s5, 0
	s_mov_b32 m0, s29
	v_lshl_add_u64 v[188:189], s[4:5], 0, v[166:167]
	ds_read_b128 v[144:147], v222 offset:32768
	ds_read_b128 v[148:151], v222 offset:33792
	ds_read_b128 v[152:155], v222 offset:34816
	ds_read_b128 v[156:159], v222 offset:35840
	ds_read_b128 v[160:163], v222 offset:36864
	ds_read_b128 v[176:179], v222 offset:37888
	ds_read_b128 v[180:183], v222 offset:38912
	ds_read_b128 v[184:187], v222 offset:39936
	global_load_lds_dwordx4 v[188:189], off
	v_lshl_add_u64 v[188:189], s[4:5], 0, v[164:165]
	s_mov_b32 m0, s33
	s_nop 0
	global_load_lds_dwordx4 v[188:189], off
	s_waitcnt lgkmcnt(8)
	s_barrier
	s_waitcnt lgkmcnt(0)
	s_waitcnt lgkmcnt(0)
	v_mfma_f32_16x16x32_bf16 v[124:127], v[128:131], v[144:147], v[124:127]
	v_mfma_f32_16x16x32_bf16 v[100:103], v[136:139], v[144:147], v[100:103]
	v_mfma_f32_16x16x32_bf16 v[120:123], v[128:131], v[152:155], v[120:123]
	v_mfma_f32_16x16x32_bf16 v[96:99], v[136:139], v[152:155], v[96:99]
	v_mfma_f32_16x16x32_bf16 v[116:119], v[128:131], v[160:163], v[116:119]
	v_mfma_f32_16x16x32_bf16 v[92:95], v[136:139], v[160:163], v[92:95]
	v_mfma_f32_16x16x32_bf16 v[112:115], v[128:131], v[180:183], v[112:115]
	v_mfma_f32_16x16x32_bf16 v[84:87], v[136:139], v[180:183], v[84:87]
	v_mfma_f32_16x16x32_bf16 v[124:127], v[132:135], v[148:151], v[124:127]
	v_mfma_f32_16x16x32_bf16 v[100:103], v[140:143], v[148:151], v[100:103]
	v_mfma_f32_16x16x32_bf16 v[120:123], v[132:135], v[156:159], v[120:123]
	v_mfma_f32_16x16x32_bf16 v[96:99], v[140:143], v[156:159], v[96:99]
	v_mfma_f32_16x16x32_bf16 v[116:119], v[132:135], v[176:179], v[116:119]
	v_mfma_f32_16x16x32_bf16 v[92:95], v[140:143], v[176:179], v[92:95]
	v_mfma_f32_16x16x32_bf16 v[112:115], v[132:135], v[184:187], v[112:115]
	v_mfma_f32_16x16x32_bf16 v[84:87], v[140:143], v[184:187], v[84:87]
	s_barrier
	s_add_i32 s43, 0, 0x1c000
	s_add_i32 s4, s42, s24
	v_add_u32_e32 v200, s43, v219
	v_lshl_add_u64 v[204:205], v[204:205], 0, s[18:19]
	s_mov_b32 m0, s4
	ds_read_b128 v[188:191], v200
	ds_read_b128 v[192:195], v200 offset:1024
	ds_read_b128 v[196:199], v200 offset:2048
	ds_read_b128 v[200:203], v200 offset:3072
	global_load_lds_dwordx4 v[204:205], off
	v_lshl_add_u64 v[204:205], v[206:207], 0, s[18:19]
	s_add_i32 m0, s4, 0x2000
	s_nop 0
	global_load_lds_dwordx4 v[204:205], off
	s_barrier
	s_waitcnt lgkmcnt(0)
	s_waitcnt lgkmcnt(0)
	v_mfma_f32_16x16x32_bf16 v[72:75], v[188:191], v[144:147], v[72:75]
	v_mfma_f32_16x16x32_bf16 v[44:47], v[196:199], v[144:147], v[44:47]
	v_mfma_f32_16x16x32_bf16 v[64:67], v[188:191], v[152:155], v[64:67]
	v_mfma_f32_16x16x32_bf16 v[40:43], v[196:199], v[152:155], v[40:43]
	v_mfma_f32_16x16x32_bf16 v[56:59], v[188:191], v[160:163], v[56:59]
	v_mfma_f32_16x16x32_bf16 v[36:39], v[196:199], v[160:163], v[36:39]
	v_mfma_f32_16x16x32_bf16 v[48:51], v[188:191], v[180:183], v[48:51]
	v_mfma_f32_16x16x32_bf16 v[28:31], v[196:199], v[180:183], v[28:31]
	v_mfma_f32_16x16x32_bf16 v[72:75], v[192:195], v[148:151], v[72:75]
	v_mfma_f32_16x16x32_bf16 v[44:47], v[200:203], v[148:151], v[44:47]
	v_mfma_f32_16x16x32_bf16 v[64:67], v[192:195], v[156:159], v[64:67]
	v_mfma_f32_16x16x32_bf16 v[40:43], v[200:203], v[156:159], v[40:43]
	v_mfma_f32_16x16x32_bf16 v[56:59], v[192:195], v[176:179], v[56:59]
	v_mfma_f32_16x16x32_bf16 v[36:39], v[200:203], v[176:179], v[36:39]
	v_mfma_f32_16x16x32_bf16 v[48:51], v[192:195], v[184:187], v[48:51]
	v_mfma_f32_16x16x32_bf16 v[28:31], v[200:203], v[184:187], v[28:31]
	s_mov_b32 m0, s41
	v_lshl_add_u64 v[204:205], v[208:209], 0, s[18:19]
	s_barrier
	s_waitcnt vmcnt(8)
	ds_read_b128 v[144:147], v222 offset:49152
	ds_read_b128 v[148:151], v222 offset:50176
	ds_read_b128 v[152:155], v222 offset:51200
	ds_read_b128 v[156:159], v222 offset:52224
	ds_read_b128 v[160:163], v222 offset:53248
	ds_read_b128 v[176:179], v222 offset:54272
	ds_read_b128 v[180:183], v222 offset:55296
	ds_read_b128 v[184:187], v222 offset:56320
	global_load_lds_dwordx4 v[204:205], off
	v_lshl_add_u64 v[204:205], v[210:211], 0, s[18:19]
	s_mov_b32 m0, s50
	s_nop 0
	global_load_lds_dwordx4 v[204:205], off
	s_barrier
	s_waitcnt lgkmcnt(0)
	s_waitcnt lgkmcnt(0)
	v_mfma_f32_16x16x32_bf16 v[108:111], v[128:131], v[144:147], v[108:111]
	v_mfma_f32_16x16x32_bf16 v[76:79], v[136:139], v[144:147], v[76:79]
	v_mfma_f32_16x16x32_bf16 v[104:107], v[128:131], v[152:155], v[104:107]
	v_mfma_f32_16x16x32_bf16 v[68:71], v[136:139], v[152:155], v[68:71]
	v_mfma_f32_16x16x32_bf16 v[88:91], v[128:131], v[160:163], v[88:91]
	v_mfma_f32_16x16x32_bf16 v[60:63], v[136:139], v[160:163], v[60:63]
	v_mfma_f32_16x16x32_bf16 v[80:83], v[128:131], v[180:183], v[80:83]
	v_mfma_f32_16x16x32_bf16 v[52:55], v[136:139], v[180:183], v[52:55]
	v_mfma_f32_16x16x32_bf16 v[108:111], v[132:135], v[148:151], v[108:111]
	v_mfma_f32_16x16x32_bf16 v[76:79], v[140:143], v[148:151], v[76:79]
	v_mfma_f32_16x16x32_bf16 v[104:107], v[132:135], v[156:159], v[104:107]
	v_mfma_f32_16x16x32_bf16 v[68:71], v[140:143], v[156:159], v[68:71]
	v_mfma_f32_16x16x32_bf16 v[88:91], v[132:135], v[176:179], v[88:91]
	v_mfma_f32_16x16x32_bf16 v[60:63], v[140:143], v[176:179], v[60:63]
	v_mfma_f32_16x16x32_bf16 v[80:83], v[132:135], v[184:187], v[80:83]
	v_mfma_f32_16x16x32_bf16 v[52:55], v[140:143], v[184:187], v[52:55]
	s_barrier
	s_add_u32 s4, s46, 0x160080
	s_addc_u32 s5, s47, 0
	s_add_i32 s42, s43, s24
	v_lshl_add_u64 v[128:129], s[4:5], 0, v[166:167]
	s_mov_b32 m0, s42
	s_nop 0
	global_load_lds_dwordx4 v[128:129], off
	v_lshl_add_u64 v[128:129], s[4:5], 0, v[164:165]
	s_add_i32 m0, s42, 0x2000
	s_nop 0
	global_load_lds_dwordx4 v[128:129], off
	ds_read_b128 v[128:131], v221
	ds_read_b128 v[132:135], v221 offset:1024
	ds_read_b128 v[136:139], v221 offset:2048
	ds_read_b128 v[140:143], v221 offset:3072
	s_waitcnt vmcnt(6)
	s_barrier
	v_mfma_f32_16x16x32_bf16 v[32:35], v[188:191], v[144:147], v[32:35]
	v_mfma_f32_16x16x32_bf16 v[12:15], v[196:199], v[144:147], v[12:15]
	v_mfma_f32_16x16x32_bf16 v[24:27], v[188:191], v[152:155], v[24:27]
	v_mfma_f32_16x16x32_bf16 v[8:11], v[196:199], v[152:155], v[8:11]
	v_mfma_f32_16x16x32_bf16 v[20:23], v[188:191], v[160:163], v[20:23]
	v_mfma_f32_16x16x32_bf16 v[4:7], v[196:199], v[160:163], v[4:7]
	v_mfma_f32_16x16x32_bf16 v[16:19], v[188:191], v[180:183], v[16:19]
	v_mfma_f32_16x16x32_bf16 v[0:3], v[196:199], v[180:183], v[0:3]
	v_mfma_f32_16x16x32_bf16 v[32:35], v[192:195], v[148:151], v[32:35]
	v_mfma_f32_16x16x32_bf16 v[12:15], v[200:203], v[148:151], v[12:15]
	v_mfma_f32_16x16x32_bf16 v[24:27], v[192:195], v[156:159], v[24:27]
	v_mfma_f32_16x16x32_bf16 v[8:11], v[200:203], v[156:159], v[8:11]
	v_mfma_f32_16x16x32_bf16 v[20:23], v[192:195], v[176:179], v[20:23]
	v_mfma_f32_16x16x32_bf16 v[4:7], v[200:203], v[176:179], v[4:7]
	v_mfma_f32_16x16x32_bf16 v[16:19], v[192:195], v[184:187], v[16:19]
	v_mfma_f32_16x16x32_bf16 v[0:3], v[200:203], v[184:187], v[0:3]
	s_add_i32 s61, s61, 2
	s_add_u32 s0, s0, 0x100
	s_addc_u32 s1, s1, 0
	s_cmpk_gt_u32 s61, 0x55
	s_mov_b64 s[42:43], s[44:45]
	s_barrier
	s_cbranch_scc0 .LBB0_1749
	v_lshl_add_u32 v144, s59, 8, v218
	v_lshl_or_b32 v184, s60, 8, v220
	v_ashrrev_i32_e32 v145, 31, v144
	v_ashrrev_i32_e32 v185, 31, v184
	v_lshlrev_b64 v[132:133], 13, v[144:145]
	v_lshlrev_b64 v[146:147], 2, v[184:185]
	v_lshl_add_u64 v[132:133], s[12:13], 0, v[132:133]
	v_lshl_add_u64 v[176:177], v[132:133], 0, v[146:147]
	v_or_b32_e32 v136, 16, v144
	v_add_co_u32_e32 v186, vcc, s53, v176
	v_ashrrev_i32_e32 v137, 31, v136
	v_or_b32_e32 v140, 32, v144
	v_or_b32_e32 v144, 48, v144
	v_addc_co_u32_e32 v187, vcc, 0, v177, vcc
	v_lshlrev_b64 v[136:137], 13, v[136:137]
	v_ashrrev_i32_e32 v141, 31, v140
	v_ashrrev_i32_e32 v145, 31, v144
	v_add_co_u32_e32 v190, vcc, s54, v176
	v_lshl_add_u64 v[128:129], s[16:17], 0, v[146:147]
	v_lshl_add_u64 v[136:137], s[12:13], 0, v[136:137]
	v_lshlrev_b64 v[140:141], 13, v[140:141]
	v_lshlrev_b64 v[144:145], 13, v[144:145]
	v_addc_co_u32_e32 v191, vcc, 0, v177, vcc
	global_load_dwordx4 v[128:131], v[128:129], off
	v_lshl_add_u64 v[178:179], v[136:137], 0, v[146:147]
	global_load_dwordx4 v[132:135], v[176:177], off
	global_load_dwordx4 v[136:139], v[178:179], off
	v_lshl_add_u64 v[140:141], s[12:13], 0, v[140:141]
	v_lshl_add_u64 v[144:145], s[12:13], 0, v[144:145]
	v_add_co_u32_e32 v192, vcc, s55, v176
	v_lshl_add_u64 v[180:181], v[140:141], 0, v[146:147]
	v_lshl_add_u64 v[182:183], v[144:145], 0, v[146:147]
	v_addc_co_u32_e32 v193, vcc, 0, v177, vcc
	global_load_dwordx4 v[140:143], v[180:181], off
	global_load_dwordx4 v[144:147], v[182:183], off
	global_load_dwordx4 v[148:151], v[186:187], off
	global_load_dwordx4 v[160:163], v[190:191], off
	global_load_dwordx4 v[156:159], v[192:193], off
	v_add_co_u32_e32 v188, vcc, s56, v176
	v_pk_add_f32 v[212:213], v[126:127], 0 op_sel_hi:[1,0]
	s_nop 0
	v_addc_co_u32_e32 v189, vcc, 0, v177, vcc
	global_load_dwordx4 v[152:155], v[188:189], off
	v_pk_add_f32 v[214:215], v[124:125], 0 op_sel_hi:[1,0]
	v_pk_add_f32 v[126:127], v[122:123], 0 op_sel_hi:[1,0]
	v_pk_add_f32 v[194:195], v[120:121], 0 op_sel_hi:[1,0]
	v_pk_add_f32 v[196:197], v[118:119], 0 op_sel_hi:[1,0]
	v_pk_add_f32 v[198:199], v[116:117], 0 op_sel_hi:[1,0]
	v_pk_add_f32 v[200:201], v[114:115], 0 op_sel_hi:[1,0]
	v_pk_add_f32 v[202:203], v[112:113], 0 op_sel_hi:[1,0]
	v_pk_add_f32 v[204:205], v[110:111], 0 op_sel_hi:[1,0]
	v_pk_add_f32 v[206:207], v[108:109], 0 op_sel_hi:[1,0]
	v_pk_add_f32 v[208:209], v[106:107], 0 op_sel_hi:[1,0]
	v_pk_add_f32 v[210:211], v[104:105], 0 op_sel_hi:[1,0]
	v_lshl_add_u64 v[120:121], v[176:177], 0, s[20:21]
	v_lshl_add_u64 v[122:123], v[176:177], 0, s[36:37]
	global_load_dwordx4 v[104:107], v[176:177], off offset:64
	global_load_dwordx4 v[108:111], v[178:179], off offset:64
	global_load_dwordx4 v[112:115], v[180:181], off offset:64
	global_load_dwordx4 v[116:119], v[182:183], off offset:64
	global_load_dwordx4 v[224:227], v[120:121], off offset:576
	global_load_dwordx4 v[228:231], v[122:123], off offset:576
	v_lshl_add_u64 v[124:125], v[176:177], 0, s[38:39]
	v_pk_add_f32 v[102:103], v[102:103], 0 op_sel_hi:[1,0]
	v_pk_add_f32 v[100:101], v[100:101], 0 op_sel_hi:[1,0]
	v_pk_add_f32 v[98:99], v[98:99], 0 op_sel_hi:[1,0]
	v_pk_add_f32 v[96:97], v[96:97], 0 op_sel_hi:[1,0]
	v_pk_add_f32 v[74:75], v[74:75], 0 op_sel_hi:[1,0]
	v_pk_add_f32 v[72:73], v[72:73], 0 op_sel_hi:[1,0]
	v_pk_add_f32 v[66:67], v[66:67], 0 op_sel_hi:[1,0]
	v_pk_add_f32 v[64:65], v[64:65], 0 op_sel_hi:[1,0]
	v_pk_add_f32 v[58:59], v[58:59], 0 op_sel_hi:[1,0]
	v_pk_add_f32 v[56:57], v[56:57], 0 op_sel_hi:[1,0]
	v_pk_add_f32 v[46:47], v[46:47], 0 op_sel_hi:[1,0]
	v_pk_add_f32 v[44:45], v[44:45], 0 op_sel_hi:[1,0]
	v_pk_add_f32 v[42:43], v[42:43], 0 op_sel_hi:[1,0]
	v_pk_add_f32 v[40:41], v[40:41], 0 op_sel_hi:[1,0]
	v_pk_add_f32 v[38:39], v[38:39], 0 op_sel_hi:[1,0]
	v_pk_add_f32 v[36:37], v[36:37], 0 op_sel_hi:[1,0]
	v_pk_add_f32 v[30:31], v[30:31], 0 op_sel_hi:[1,0]
	v_pk_add_f32 v[28:29], v[28:29], 0 op_sel_hi:[1,0]
	s_and_b64 vcc, exec, s[6:7]
	s_mov_b32 s60, s57
	s_mov_b32 s59, s58
	s_mov_b64 s[44:45], s[10:11]
	s_mov_b64 s[42:43], s[8:9]
	s_waitcnt vmcnt(0)
	v_pk_fma_f32 v[134:135], v[212:213], v[130:131], v[134:135]
	v_pk_fma_f32 v[132:133], v[214:215], v[128:129], v[132:133]
	global_store_dwordx4 v[176:177], v[132:135], off
	s_nop 1
	v_pk_fma_f32 v[134:135], v[126:127], v[130:131], v[138:139]
	v_pk_fma_f32 v[132:133], v[194:195], v[128:129], v[136:137]
	v_pk_add_f32 v[126:127], v[90:91], 0 op_sel_hi:[1,0]
	v_pk_fma_f32 v[138:139], v[196:197], v[130:131], v[142:143]
	v_pk_fma_f32 v[136:137], v[198:199], v[128:129], v[140:141]
	v_pk_fma_f32 v[142:143], v[200:201], v[130:131], v[146:147]
	v_pk_fma_f32 v[140:141], v[202:203], v[128:129], v[144:145]
	v_pk_fma_f32 v[146:147], v[204:205], v[130:131], v[150:151]
	v_pk_fma_f32 v[144:145], v[206:207], v[128:129], v[148:149]
	v_pk_fma_f32 v[150:151], v[208:209], v[130:131], v[162:163]
	v_pk_fma_f32 v[148:149], v[210:211], v[128:129], v[160:161]
	global_store_dwordx4 v[178:179], v[132:135], off
	global_store_dwordx4 v[180:181], v[136:139], off
	global_store_dwordx4 v[182:183], v[140:143], off
	global_store_dwordx4 v[186:187], v[144:147], off
	global_store_dwordx4 v[190:191], v[148:151], off
	v_pk_add_f32 v[132:133], v[88:89], 0 op_sel_hi:[1,0]
	v_pk_fma_f32 v[134:135], v[126:127], v[130:131], v[158:159]
	v_pk_fma_f32 v[132:133], v[132:133], v[128:129], v[156:157]
	v_pk_add_f32 v[126:127], v[82:83], 0 op_sel_hi:[1,0]
	global_store_dwordx4 v[192:193], v[132:135], off
	v_pk_fma_f32 v[130:131], v[126:127], v[130:131], v[154:155]
	v_or_b32_e32 v126, 16, v184
	v_pk_add_f32 v[132:133], v[80:81], 0 op_sel_hi:[1,0]
	v_ashrrev_i32_e32 v127, 31, v126
	v_pk_fma_f32 v[128:129], v[132:133], v[128:129], v[152:153]
	v_lshl_add_u64 v[146:147], v[176:177], 0, s[14:15]
	global_store_dwordx4 v[188:189], v[128:131], off
	v_lshl_add_u64 v[126:127], v[126:127], 2, s[16:17]
	global_load_dwordx4 v[88:91], v[124:125], off offset:576
	global_load_dwordx4 v[80:83], v[146:147], off offset:576
	s_nop 0
	global_load_dwordx4 v[126:129], v[126:127], off
	s_nop 0
	global_load_dwordx4 v[130:133], v[120:121], off offset:64
	global_load_dwordx4 v[134:137], v[122:123], off offset:64
	global_load_dwordx4 v[138:141], v[124:125], off offset:64
	global_load_dwordx4 v[142:145], v[146:147], off offset:64
	v_pk_add_f32 v[192:193], v[52:53], 0 op_sel_hi:[1,0]
	v_or_b32_e32 v52, 0x80, v184
	v_pk_add_f32 v[148:149], v[94:95], 0 op_sel_hi:[1,0]
	v_pk_add_f32 v[150:151], v[92:93], 0 op_sel_hi:[1,0]
	v_pk_add_f32 v[152:153], v[86:87], 0 op_sel_hi:[1,0]
	v_pk_add_f32 v[154:155], v[84:85], 0 op_sel_hi:[1,0]
	v_pk_add_f32 v[156:157], v[78:79], 0 op_sel_hi:[1,0]
	v_pk_add_f32 v[158:159], v[76:77], 0 op_sel_hi:[1,0]
	v_pk_add_f32 v[160:161], v[70:71], 0 op_sel_hi:[1,0]
	v_pk_add_f32 v[162:163], v[68:69], 0 op_sel_hi:[1,0]
	v_pk_add_f32 v[186:187], v[62:63], 0 op_sel_hi:[1,0]
	v_pk_add_f32 v[188:189], v[60:61], 0 op_sel_hi:[1,0]
	v_pk_add_f32 v[190:191], v[54:55], 0 op_sel_hi:[1,0]
	v_ashrrev_i32_e32 v53, 31, v52
	v_lshl_add_u64 v[194:195], v[52:53], 2, s[16:17]
	global_load_dwordx4 v[52:55], v[176:177], off offset:512
	global_load_dwordx4 v[60:63], v[120:121], off offset:512
	global_load_dwordx4 v[68:71], v[122:123], off offset:512
	global_load_dwordx4 v[76:79], v[124:125], off offset:512
	global_load_dwordx4 v[84:87], v[146:147], off offset:512
	s_waitcnt vmcnt(0)
	v_pk_fma_f32 v[94:95], v[102:103], v[128:129], v[106:107]
	v_pk_fma_f32 v[92:93], v[100:101], v[126:127], v[104:105]
	v_pk_fma_f32 v[98:99], v[98:99], v[128:129], v[110:111]
	v_pk_fma_f32 v[96:97], v[96:97], v[126:127], v[108:109]
	v_pk_fma_f32 v[102:103], v[148:149], v[128:129], v[114:115]
	v_pk_fma_f32 v[100:101], v[150:151], v[126:127], v[112:113]
	v_pk_fma_f32 v[106:107], v[152:153], v[128:129], v[118:119]
	v_pk_fma_f32 v[104:105], v[154:155], v[126:127], v[116:117]
	v_pk_fma_f32 v[110:111], v[156:157], v[128:129], v[132:133]
	v_pk_fma_f32 v[108:109], v[158:159], v[126:127], v[130:131]
	v_pk_fma_f32 v[114:115], v[160:161], v[128:129], v[136:137]
	v_pk_fma_f32 v[112:113], v[162:163], v[126:127], v[134:135]
	v_pk_fma_f32 v[118:119], v[186:187], v[128:129], v[140:141]
	v_pk_fma_f32 v[116:117], v[188:189], v[126:127], v[138:139]
	v_pk_fma_f32 v[128:129], v[190:191], v[128:129], v[144:145]
	v_pk_fma_f32 v[126:127], v[192:193], v[126:127], v[142:143]
	global_store_dwordx4 v[176:177], v[92:95], off offset:64
	global_store_dwordx4 v[178:179], v[96:99], off offset:64
	global_store_dwordx4 v[180:181], v[100:103], off offset:64
	global_store_dwordx4 v[182:183], v[104:107], off offset:64
	global_store_dwordx4 v[120:121], v[108:111], off offset:64
	global_store_dwordx4 v[122:123], v[112:115], off offset:64
	global_store_dwordx4 v[124:125], v[116:119], off offset:64
	global_store_dwordx4 v[146:147], v[126:129], off offset:64
	global_load_dwordx4 v[92:95], v[194:195], off
	global_load_dwordx4 v[96:99], v[178:179], off offset:512
	global_load_dwordx4 v[100:103], v[180:181], off offset:512
	global_load_dwordx4 v[104:107], v[182:183], off offset:512
	v_pk_add_f32 v[132:133], v[16:17], 0 op_sel_hi:[1,0]
	v_or_b32_e32 v16, 0x90, v184
	v_pk_add_f32 v[108:109], v[50:51], 0 op_sel_hi:[1,0]
	v_pk_add_f32 v[110:111], v[48:49], 0 op_sel_hi:[1,0]
	v_pk_add_f32 v[112:113], v[34:35], 0 op_sel_hi:[1,0]
	v_pk_add_f32 v[114:115], v[32:33], 0 op_sel_hi:[1,0]
	v_pk_add_f32 v[116:117], v[26:27], 0 op_sel_hi:[1,0]
	v_pk_add_f32 v[118:119], v[24:25], 0 op_sel_hi:[1,0]
	v_pk_add_f32 v[126:127], v[22:23], 0 op_sel_hi:[1,0]
	v_pk_add_f32 v[128:129], v[20:21], 0 op_sel_hi:[1,0]
	v_pk_add_f32 v[130:131], v[18:19], 0 op_sel_hi:[1,0]
	v_ashrrev_i32_e32 v17, 31, v16
	v_lshl_add_u64 v[134:135], v[16:17], 2, s[16:17]
	global_load_dwordx4 v[16:19], v[176:177], off offset:576
	global_load_dwordx4 v[20:23], v[178:179], off offset:576
	global_load_dwordx4 v[24:27], v[180:181], off offset:576
	global_load_dwordx4 v[32:35], v[182:183], off offset:576
	s_waitcnt vmcnt(0)
	v_pk_fma_f32 v[50:51], v[74:75], v[94:95], v[54:55]
	v_pk_fma_f32 v[48:49], v[72:73], v[92:93], v[52:53]
	v_pk_fma_f32 v[54:55], v[66:67], v[94:95], v[98:99]
	v_pk_fma_f32 v[52:53], v[64:65], v[92:93], v[96:97]
	v_pk_fma_f32 v[58:59], v[58:59], v[94:95], v[102:103]
	v_pk_fma_f32 v[56:57], v[56:57], v[92:93], v[100:101]
	v_pk_fma_f32 v[66:67], v[108:109], v[94:95], v[106:107]
	v_pk_fma_f32 v[64:65], v[110:111], v[92:93], v[104:105]
	v_pk_fma_f32 v[62:63], v[112:113], v[94:95], v[62:63]
	v_pk_fma_f32 v[60:61], v[114:115], v[92:93], v[60:61]
	v_pk_fma_f32 v[70:71], v[116:117], v[94:95], v[70:71]
	v_pk_fma_f32 v[68:69], v[118:119], v[92:93], v[68:69]
	v_pk_fma_f32 v[74:75], v[126:127], v[94:95], v[78:79]
	v_pk_fma_f32 v[72:73], v[128:129], v[92:93], v[76:77]
	v_pk_fma_f32 v[78:79], v[130:131], v[94:95], v[86:87]
	v_pk_fma_f32 v[76:77], v[132:133], v[92:93], v[84:85]
	global_store_dwordx4 v[176:177], v[48:51], off offset:512
	global_store_dwordx4 v[178:179], v[52:55], off offset:512
	global_store_dwordx4 v[180:181], v[56:59], off offset:512
	global_store_dwordx4 v[182:183], v[64:67], off offset:512
	global_store_dwordx4 v[120:121], v[60:63], off offset:512
	global_store_dwordx4 v[122:123], v[68:71], off offset:512
	global_store_dwordx4 v[124:125], v[72:75], off offset:512
	global_store_dwordx4 v[146:147], v[76:79], off offset:512
	global_load_dwordx4 v[48:51], v[134:135], off
	v_pk_add_f32 v[52:53], v[14:15], 0 op_sel_hi:[1,0]
	v_pk_add_f32 v[54:55], v[12:13], 0 op_sel_hi:[1,0]
	v_pk_add_f32 v[56:57], v[10:11], 0 op_sel_hi:[1,0]
	v_pk_add_f32 v[58:59], v[8:9], 0 op_sel_hi:[1,0]
	v_pk_add_f32 v[60:61], v[6:7], 0 op_sel_hi:[1,0]
	v_pk_add_f32 v[62:63], v[4:5], 0 op_sel_hi:[1,0]
	v_pk_add_f32 v[64:65], v[2:3], 0 op_sel_hi:[1,0]
	v_pk_add_f32 v[66:67], v[0:1], 0 op_sel_hi:[1,0]
	s_waitcnt vmcnt(0)
	v_pk_fma_f32 v[2:3], v[46:47], v[50:51], v[18:19]
	v_pk_fma_f32 v[0:1], v[44:45], v[48:49], v[16:17]
	v_pk_fma_f32 v[6:7], v[42:43], v[50:51], v[22:23]
	v_pk_fma_f32 v[4:5], v[40:41], v[48:49], v[20:21]
	v_pk_fma_f32 v[10:11], v[38:39], v[50:51], v[26:27]
	v_pk_fma_f32 v[8:9], v[36:37], v[48:49], v[24:25]
	v_pk_fma_f32 v[14:15], v[30:31], v[50:51], v[34:35]
	v_pk_fma_f32 v[12:13], v[28:29], v[48:49], v[32:33]
	v_pk_fma_f32 v[18:19], v[52:53], v[50:51], v[226:227]
	v_pk_fma_f32 v[16:17], v[54:55], v[48:49], v[224:225]
	v_pk_fma_f32 v[22:23], v[56:57], v[50:51], v[230:231]
	v_pk_fma_f32 v[20:21], v[58:59], v[48:49], v[228:229]
	v_pk_fma_f32 v[26:27], v[60:61], v[50:51], v[90:91]
	v_pk_fma_f32 v[24:25], v[62:63], v[48:49], v[88:89]
	v_pk_fma_f32 v[30:31], v[64:65], v[50:51], v[82:83]
	v_pk_fma_f32 v[28:29], v[66:67], v[48:49], v[80:81]
	global_store_dwordx4 v[176:177], v[0:3], off offset:576
	global_store_dwordx4 v[178:179], v[4:7], off offset:576
	global_store_dwordx4 v[180:181], v[8:11], off offset:576
	global_store_dwordx4 v[182:183], v[12:15], off offset:576
	global_store_dwordx4 v[120:121], v[16:19], off offset:576
	global_store_dwordx4 v[122:123], v[20:23], off offset:576
	global_store_dwordx4 v[124:125], v[24:27], off offset:576
	global_store_dwordx4 v[146:147], v[28:31], off offset:576
	s_cbranch_vccz .LBB0_1738
	s_waitcnt vmcnt(0)
	s_cmpk_gt_u32 s23, 0xff
	s_cbranch_scc1 .LBB0_1753
	s_barrier
